# GEMM K-loops: dropped the compiler's redundant s_waitcnt lgkmcnt(0) at the head of each MFMA segment (the asm wait before the barrier already covers it)
# speedup vs baseline: 1.0086x; 1.0086x over previous
; #define PG8_STAGE(bufoff, gbase, voff) do { _Pragma("unroll") for (int _i = 0; _i < 2; ++_i) \
;         __builtin_amdgcn_global_load_lds((const unsigned*)((const char*)(gbase) + (voff)[_i]), (PG8_LAS unsigned*)(lds + (bufoff) + ldsw + _i * 8192), 16, 0, 0); } while (0)
; #define PG8_LDA(dst, b, h) do { _Pragma("unroll") for (int m = 0; m < 4; ++m) _Pragma("unroll") for (int k = 0; k < 2; ++k) dst[m][k] = *(const PG8_LAS bf16x8*)(lds + PG8_SA(b, h) + aoff + m * 2048 + k * 1024); } while (0)
; #define PG8_LDB(dst, b, h) do { _Pragma("unroll") for (int n = 0; n < 2; ++n) _Pragma("unroll") for (int k = 0; k < 2; ++k) dst[n][k] = *(const PG8_LAS bf16x8*)(lds + PG8_SB(b, h) + boff + n * 2048 + k * 1024); } while (0)
; #define PG8_MMA(ai, bj, At, Bt) do { __builtin_amdgcn_s_setprio(1); _Pragma("unroll") for (int m = 0; m < 4; ++m) _Pragma("unroll") for (int n = 0; n < 2; ++n) _Pragma("unroll") for (int k = 0; k < 2; ++k) \
;         acc[ai][bj][m][n] = __builtin_amdgcn_mfma_f32_16x16x32_bf16(Bt[n][k], At[m][k], acc[ai][bj][m][n], 0, 0, 0); __builtin_amdgcn_s_setprio(0); } while (0)
; #define PG8_WAIT_V(n) asm volatile("s_waitcnt vmcnt(" #n ")" ::: "memory")
; #define PG8_WAIT_L(n) asm volatile("s_waitcnt lgkmcnt(" #n ")" ::: "memory")
; template <class Epi, class Sched, bool ALIGN_EPI = false, bool SP2 = false>
; __device__ __forceinline__ void gemm_phase(PG8_LAS unsigned char* lds, const Gemm g, const Sched& S, const Epi& E, int tid_in) {
;     ...
;             const bool last = (t == nt - 2);
;             const char* a1 = cA + (size_t)(t + 1) * kstep;
;             const char* a2 = last ? nA : cA + (size_t)(t + 2) * kstep; const char* b2 = last ? nB : cB + (size_t)(t + 2) * kstep;
;             const char* a3 = a2 + kstep; const char* b3 = b2 + kstep;
;             if (last && has_next) S.a_ready(nxt);
;             if constexpr (SP2) {
;             PG8_LDB(B0, 0, 0); PG8_LDB(B1, 0, 1); PG8_SCHED; PG8_LDA(At, 0, 0); PG8_STAGE(PG8_SA(1, 1), a1 + hstep, voffA);
;             PG8_WAIT_V(8); PG8_WAIT_L(0); PG8_BAR; PG8_MMA(0, 0, At, B0); PG8_MMA(0, 1, At, B1); PG8_BAR; PG8_SCHED;
;             PG8_LDA(At, 0, 1); PG8_STAGE(PG8_SB(0, 0), b2, voffB); PG8_STAGE(PG8_SB(0, 1), b2 + hstep, voffB); PG8_STAGE(PG8_SA(0, 0), a2, voffA);
;             PG8_WAIT_V(8); PG8_WAIT_L(0); PG8_BAR; PG8_MMA(1, 0, At, B0); PG8_MMA(1, 1, At, B1); PG8_BAR; PG8_SCHED;
.LBB0_135:
	s_add_u32 s62, s64, 0xfff80080
	s_addc_u32 s63, s65, -1
	s_add_i32 s76, 0, 0x10000
	s_cmp_eq_u32 s75, 28
	s_cselect_b32 s95, s17, s63
	s_cselect_b32 s94, s43, s62
	v_add_u32_e32 v96, s76, v205
	s_cselect_b32 s93, s41, s74
	s_cselect_b32 s92, s72, s73
	s_add_i32 s77, 0, 0x14000
	ds_read_b128 v[130:133], v96
	ds_read_b128 v[134:137], v96 offset:1024
	ds_read_b128 v[138:141], v96 offset:2048
	ds_read_b128 v[142:145], v96 offset:3072
	v_add_u32_e32 v96, s77, v205
	ds_read_b128 v[146:149], v96
	ds_read_b128 v[150:153], v96 offset:1024
	ds_read_b128 v[154:157], v96 offset:2048
	ds_read_b128 v[158:161], v96 offset:3072
	v_lshl_add_u64 v[196:197], s[64:65], 0, v[180:181]
	s_add_i32 m0, s37, 0xc000
	ds_read_b128 v[162:165], v216
	ds_read_b128 v[184:187], v216 offset:1024
	ds_read_b128 v[188:191], v216 offset:2048
	ds_read_b128 v[192:195], v216 offset:3072
	ds_read_b128 v[218:221], v216 offset:4096
	ds_read_b128 v[222:225], v216 offset:5120
	ds_read_b128 v[226:229], v216 offset:6144
	ds_read_b128 v[230:233], v216 offset:7168
	global_load_lds_dwordx4 v[196:197], off
	v_lshl_add_u64 v[196:197], s[64:65], 0, v[182:183]
	s_add_i32 m0, s37, 0xe000
	s_nop 0
	global_load_lds_dwordx4 v[196:197], off
	s_waitcnt vmcnt(8)
	s_waitcnt lgkmcnt(0)
	s_barrier
	s_setprio 1
	v_mfma_f32_16x16x32_bf16 v[126:129], v[130:133], v[162:165], v[126:129]
	v_mfma_f32_16x16x32_bf16 v[122:125], v[138:141], v[162:165], v[122:125]
	v_mfma_f32_16x16x32_bf16 v[118:121], v[130:133], v[188:191], v[118:121]
	v_mfma_f32_16x16x32_bf16 v[114:117], v[138:141], v[188:191], v[114:117]
	v_mfma_f32_16x16x32_bf16 v[102:105], v[130:133], v[218:221], v[102:105]
	v_mfma_f32_16x16x32_bf16 v[98:101], v[138:141], v[218:221], v[98:101]
	v_mfma_f32_16x16x32_bf16 v[84:87], v[130:133], v[226:229], v[84:87]
	v_mfma_f32_16x16x32_bf16 v[80:83], v[138:141], v[226:229], v[80:83]
	v_mfma_f32_16x16x32_bf16 v[126:129], v[134:137], v[184:187], v[126:129]
	v_mfma_f32_16x16x32_bf16 v[122:125], v[142:145], v[184:187], v[122:125]
	v_mfma_f32_16x16x32_bf16 v[118:121], v[134:137], v[192:195], v[118:121]
	v_mfma_f32_16x16x32_bf16 v[114:117], v[142:145], v[192:195], v[114:117]
	v_mfma_f32_16x16x32_bf16 v[102:105], v[134:137], v[222:225], v[102:105]
	v_mfma_f32_16x16x32_bf16 v[98:101], v[142:145], v[222:225], v[98:101]
	v_mfma_f32_16x16x32_bf16 v[84:87], v[134:137], v[230:233], v[84:87]
	v_mfma_f32_16x16x32_bf16 v[80:83], v[142:145], v[230:233], v[80:83]
	s_setprio 0
	s_setprio 1
	v_mfma_f32_16x16x32_bf16 v[110:113], v[146:149], v[162:165], v[110:113]
	v_mfma_f32_16x16x32_bf16 v[106:109], v[154:157], v[162:165], v[106:109]
	v_mfma_f32_16x16x32_bf16 v[92:95], v[146:149], v[188:191], v[92:95]
	v_mfma_f32_16x16x32_bf16 v[88:91], v[154:157], v[188:191], v[88:91]
	v_mfma_f32_16x16x32_bf16 v[76:79], v[146:149], v[218:221], v[76:79]
	v_mfma_f32_16x16x32_bf16 v[72:75], v[154:157], v[218:221], v[72:75]
	v_mfma_f32_16x16x32_bf16 v[68:71], v[146:149], v[226:229], v[68:71]
	v_mfma_f32_16x16x32_bf16 v[64:67], v[154:157], v[226:229], v[64:67]
	v_mfma_f32_16x16x32_bf16 v[110:113], v[150:153], v[184:187], v[110:113]
	v_mfma_f32_16x16x32_bf16 v[106:109], v[158:161], v[184:187], v[106:109]
	v_mfma_f32_16x16x32_bf16 v[92:95], v[150:153], v[192:195], v[92:95]
	v_mfma_f32_16x16x32_bf16 v[88:91], v[158:161], v[192:195], v[88:91]
	v_mfma_f32_16x16x32_bf16 v[76:79], v[150:153], v[222:225], v[76:79]
	v_mfma_f32_16x16x32_bf16 v[72:75], v[158:161], v[222:225], v[72:75]
	v_mfma_f32_16x16x32_bf16 v[68:71], v[150:153], v[230:233], v[68:71]
	v_mfma_f32_16x16x32_bf16 v[64:67], v[158:161], v[230:233], v[64:67]
	s_setprio 0
	s_barrier
	s_add_i32 s62, s76, s70
	v_lshl_add_u64 v[196:197], s[92:93], 0, v[174:175]
	s_mov_b32 m0, s62
	ds_read_b128 v[162:165], v216 offset:16384
	ds_read_b128 v[184:187], v216 offset:17408
	ds_read_b128 v[188:191], v216 offset:18432
	ds_read_b128 v[192:195], v216 offset:19456
	ds_read_b128 v[218:221], v216 offset:20480
	ds_read_b128 v[222:225], v216 offset:21504
	ds_read_b128 v[226:229], v216 offset:22528
	ds_read_b128 v[230:233], v216 offset:23552
	global_load_lds_dwordx4 v[196:197], off
	s_add_i32 m0, s62, 0x2000
	s_add_u32 s62, s92, 0x80000
	v_lshl_add_u64 v[198:199], s[92:93], 0, v[178:179]
	s_addc_u32 s63, s93, 0
	s_add_i32 s76, s77, s70
	global_load_lds_dwordx4 v[198:199], off
	v_lshl_add_u64 v[200:201], s[62:63], 0, v[174:175]
	s_mov_b32 m0, s76
	v_lshl_add_u64 v[234:235], s[94:95], 0, v[176:177]
	global_load_lds_dwordx4 v[200:201], off
	v_lshl_add_u64 v[200:201], s[62:63], 0, v[178:179]
	s_add_i32 m0, s76, 0x2000
	s_nop 0
	global_load_lds_dwordx4 v[200:201], off
	v_lshl_add_u64 v[200:201], s[94:95], 0, v[172:173]
	s_mov_b32 m0, s37
	s_nop 0
	global_load_lds_dwordx4 v[200:201], off
	s_mov_b32 m0, s71
	s_nop 0
	global_load_lds_dwordx4 v[234:235], off
	s_waitcnt vmcnt(8)
	s_waitcnt lgkmcnt(0)
	s_barrier
; #define PG8_STAGE(bufoff, gbase, voff) do { _Pragma("unroll") for (int _i = 0; _i < 2; ++_i) \
;         __builtin_amdgcn_global_load_lds((const unsigned*)((const char*)(gbase) + (voff)[_i]), (PG8_LAS unsigned*)(lds + (bufoff) + ldsw + _i * 8192), 16, 0, 0); } while (0)
; #define PG8_LDA(dst, b, h) do { _Pragma("unroll") for (int m = 0; m < 4; ++m) _Pragma("unroll") for (int k = 0; k < 2; ++k) dst[m][k] = *(const PG8_LAS bf16x8*)(lds + PG8_SA(b, h) + aoff + m * 2048 + k * 1024); } while (0)
; #define PG8_LDB(dst, b, h) do { _Pragma("unroll") for (int n = 0; n < 2; ++n) _Pragma("unroll") for (int k = 0; k < 2; ++k) dst[n][k] = *(const PG8_LAS bf16x8*)(lds + PG8_SB(b, h) + boff + n * 2048 + k * 1024); } while (0)
; #define PG8_MMA(ai, bj, At, Bt) do { __builtin_amdgcn_s_setprio(1); _Pragma("unroll") for (int m = 0; m < 4; ++m) _Pragma("unroll") for (int n = 0; n < 2; ++n) _Pragma("unroll") for (int k = 0; k < 2; ++k) \
;         acc[ai][bj][m][n] = __builtin_amdgcn_mfma_f32_16x16x32_bf16(Bt[n][k], At[m][k], acc[ai][bj][m][n], 0, 0, 0); __builtin_amdgcn_s_setprio(0); } while (0)
; #define PG8_WAIT_V(n) asm volatile("s_waitcnt vmcnt(" #n ")" ::: "memory")
; #define PG8_WAIT_L(n) asm volatile("s_waitcnt lgkmcnt(" #n ")" ::: "memory")
; #define PG8_BAR __builtin_amdgcn_s_barrier()
; #define PG8_SCHED __builtin_amdgcn_sched_barrier(0)
; template <class Epi, class Sched, bool ALIGN_EPI = false, bool SP2 = false>
; __device__ __forceinline__ void gemm_phase(PG8_LAS unsigned char* lds, const Gemm g, const Sched& S, const Epi& E, int tid_in) {
;     ...
;             PG8_WAIT_V(8); PG8_WAIT_L(0); PG8_BAR; PG8_MMA(1, 0, At, B0); PG8_MMA(1, 1, At, B1); PG8_BAR; PG8_SCHED;
;             PG8_LDB(B0, 1, 0); PG8_LDB(B1, 1, 1); PG8_SCHED; PG8_LDA(At, 1, 0); PG8_STAGE(PG8_SA(0, 1), a2 + hstep, voffA);
;             PG8_WAIT_V(8); PG8_WAIT_L(0); PG8_BAR; PG8_MMA(0, 0, At, B0); PG8_MMA(0, 1, At, B1); PG8_BAR; PG8_SCHED;
	s_setprio 1
	v_mfma_f32_16x16x32_bf16 v[60:63], v[130:133], v[162:165], v[60:63]
	v_mfma_f32_16x16x32_bf16 v[56:59], v[138:141], v[162:165], v[56:59]
	v_mfma_f32_16x16x32_bf16 v[52:55], v[130:133], v[188:191], v[52:55]
	v_mfma_f32_16x16x32_bf16 v[48:51], v[138:141], v[188:191], v[48:51]
	v_mfma_f32_16x16x32_bf16 v[36:39], v[130:133], v[218:221], v[36:39]
	v_mfma_f32_16x16x32_bf16 v[32:35], v[138:141], v[218:221], v[32:35]
	v_mfma_f32_16x16x32_bf16 v[20:23], v[130:133], v[226:229], v[20:23]
	v_mfma_f32_16x16x32_bf16 v[16:19], v[138:141], v[226:229], v[16:19]
	v_mfma_f32_16x16x32_bf16 v[60:63], v[134:137], v[184:187], v[60:63]
	v_mfma_f32_16x16x32_bf16 v[56:59], v[142:145], v[184:187], v[56:59]
	v_mfma_f32_16x16x32_bf16 v[52:55], v[134:137], v[192:195], v[52:55]
	v_mfma_f32_16x16x32_bf16 v[48:51], v[142:145], v[192:195], v[48:51]
	v_mfma_f32_16x16x32_bf16 v[36:39], v[134:137], v[222:225], v[36:39]
	v_mfma_f32_16x16x32_bf16 v[32:35], v[142:145], v[222:225], v[32:35]
	v_mfma_f32_16x16x32_bf16 v[20:23], v[134:137], v[230:233], v[20:23]
	v_mfma_f32_16x16x32_bf16 v[16:19], v[142:145], v[230:233], v[16:19]
	s_setprio 0
	s_setprio 1
	v_mfma_f32_16x16x32_bf16 v[44:47], v[146:149], v[162:165], v[44:47]
	v_mfma_f32_16x16x32_bf16 v[40:43], v[154:157], v[162:165], v[40:43]
	v_mfma_f32_16x16x32_bf16 v[28:31], v[146:149], v[188:191], v[28:31]
	v_mfma_f32_16x16x32_bf16 v[24:27], v[154:157], v[188:191], v[24:27]
	v_mfma_f32_16x16x32_bf16 v[12:15], v[146:149], v[218:221], v[12:15]
	v_mfma_f32_16x16x32_bf16 v[8:11], v[154:157], v[218:221], v[8:11]
	v_mfma_f32_16x16x32_bf16 v[4:7], v[146:149], v[226:229], v[4:7]
	v_mfma_f32_16x16x32_bf16 v[0:3], v[154:157], v[226:229], v[0:3]
	v_mfma_f32_16x16x32_bf16 v[44:47], v[150:153], v[184:187], v[44:47]
	v_mfma_f32_16x16x32_bf16 v[40:43], v[158:161], v[184:187], v[40:43]
	v_mfma_f32_16x16x32_bf16 v[28:31], v[150:153], v[192:195], v[28:31]
	v_mfma_f32_16x16x32_bf16 v[24:27], v[158:161], v[192:195], v[24:27]
	v_mfma_f32_16x16x32_bf16 v[12:15], v[150:153], v[222:225], v[12:15]
	v_mfma_f32_16x16x32_bf16 v[8:11], v[158:161], v[222:225], v[8:11]
	v_mfma_f32_16x16x32_bf16 v[4:7], v[150:153], v[230:233], v[4:7]
	v_mfma_f32_16x16x32_bf16 v[0:3], v[158:161], v[230:233], v[0:3]
	s_setprio 0
	s_barrier
	s_add_i32 s76, 0, 0x18000
	v_add_u32_e32 v96, s76, v205
	s_add_i32 s77, 0, 0x1c000
	ds_read_b128 v[130:133], v96
	ds_read_b128 v[134:137], v96 offset:1024
	ds_read_b128 v[138:141], v96 offset:2048
	ds_read_b128 v[142:145], v96 offset:3072
	v_add_u32_e32 v96, s77, v205
	ds_read_b128 v[146:149], v96
	ds_read_b128 v[150:153], v96 offset:1024
	ds_read_b128 v[154:157], v96 offset:2048
	ds_read_b128 v[158:161], v96 offset:3072
	s_add_u32 s62, s94, 0x80000
	s_addc_u32 s63, s95, 0
	s_mov_b32 m0, s91
	v_lshl_add_u64 v[236:237], s[62:63], 0, v[172:173]
	ds_read_b128 v[162:165], v216 offset:32768
	ds_read_b128 v[184:187], v216 offset:33792
	ds_read_b128 v[188:191], v216 offset:34816
	ds_read_b128 v[192:195], v216 offset:35840
	ds_read_b128 v[218:221], v216 offset:36864
	ds_read_b128 v[222:225], v216 offset:37888
	ds_read_b128 v[226:229], v216 offset:38912
	ds_read_b128 v[230:233], v216 offset:39936
	global_load_lds_dwordx4 v[236:237], off
	v_lshl_add_u64 v[236:237], s[62:63], 0, v[176:177]
	s_mov_b32 m0, s96
	s_nop 0
	global_load_lds_dwordx4 v[236:237], off
	s_waitcnt vmcnt(8)
	s_waitcnt lgkmcnt(0)
	s_barrier
	s_setprio 1
	v_mfma_f32_16x16x32_bf16 v[126:129], v[130:133], v[162:165], v[126:129]
	v_mfma_f32_16x16x32_bf16 v[122:125], v[138:141], v[162:165], v[122:125]
	v_mfma_f32_16x16x32_bf16 v[118:121], v[130:133], v[188:191], v[118:121]
	v_mfma_f32_16x16x32_bf16 v[114:117], v[138:141], v[188:191], v[114:117]
	v_mfma_f32_16x16x32_bf16 v[102:105], v[130:133], v[218:221], v[102:105]
	v_mfma_f32_16x16x32_bf16 v[98:101], v[138:141], v[218:221], v[98:101]
	v_mfma_f32_16x16x32_bf16 v[84:87], v[130:133], v[226:229], v[84:87]
	v_mfma_f32_16x16x32_bf16 v[80:83], v[138:141], v[226:229], v[80:83]
	v_mfma_f32_16x16x32_bf16 v[126:129], v[134:137], v[184:187], v[126:129]
	v_mfma_f32_16x16x32_bf16 v[122:125], v[142:145], v[184:187], v[122:125]
	v_mfma_f32_16x16x32_bf16 v[118:121], v[134:137], v[192:195], v[118:121]
	v_mfma_f32_16x16x32_bf16 v[114:117], v[142:145], v[192:195], v[114:117]
	v_mfma_f32_16x16x32_bf16 v[102:105], v[134:137], v[222:225], v[102:105]
	v_mfma_f32_16x16x32_bf16 v[98:101], v[142:145], v[222:225], v[98:101]
	v_mfma_f32_16x16x32_bf16 v[84:87], v[134:137], v[230:233], v[84:87]
	v_mfma_f32_16x16x32_bf16 v[80:83], v[142:145], v[230:233], v[80:83]
	s_setprio 0
	s_setprio 1
	v_mfma_f32_16x16x32_bf16 v[110:113], v[146:149], v[162:165], v[110:113]
	v_mfma_f32_16x16x32_bf16 v[106:109], v[154:157], v[162:165], v[106:109]
	v_mfma_f32_16x16x32_bf16 v[92:95], v[146:149], v[188:191], v[92:95]
	v_mfma_f32_16x16x32_bf16 v[88:91], v[154:157], v[188:191], v[88:91]
	v_mfma_f32_16x16x32_bf16 v[76:79], v[146:149], v[218:221], v[76:79]
	v_mfma_f32_16x16x32_bf16 v[72:75], v[154:157], v[218:221], v[72:75]
	v_mfma_f32_16x16x32_bf16 v[68:71], v[146:149], v[226:229], v[68:71]
	v_mfma_f32_16x16x32_bf16 v[64:67], v[154:157], v[226:229], v[64:67]
	v_mfma_f32_16x16x32_bf16 v[110:113], v[150:153], v[184:187], v[110:113]
	v_mfma_f32_16x16x32_bf16 v[106:109], v[158:161], v[184:187], v[106:109]
	v_mfma_f32_16x16x32_bf16 v[92:95], v[150:153], v[192:195], v[92:95]
	v_mfma_f32_16x16x32_bf16 v[88:91], v[158:161], v[192:195], v[88:91]
	v_mfma_f32_16x16x32_bf16 v[76:79], v[150:153], v[222:225], v[76:79]
	v_mfma_f32_16x16x32_bf16 v[72:75], v[158:161], v[222:225], v[72:75]
	v_mfma_f32_16x16x32_bf16 v[68:71], v[150:153], v[230:233], v[68:71]
	v_mfma_f32_16x16x32_bf16 v[64:67], v[158:161], v[230:233], v[64:67]
	s_setprio 0
	s_barrier
; #define PG8_STAGE(bufoff, gbase, voff) do { _Pragma("unroll") for (int _i = 0; _i < 2; ++_i) \
;         __builtin_amdgcn_global_load_lds((const unsigned*)((const char*)(gbase) + (voff)[_i]), (PG8_LAS unsigned*)(lds + (bufoff) + ldsw + _i * 8192), 16, 0, 0); } while (0)
; #define PG8_LDA(dst, b, h) do { _Pragma("unroll") for (int m = 0; m < 4; ++m) _Pragma("unroll") for (int k = 0; k < 2; ++k) dst[m][k] = *(const PG8_LAS bf16x8*)(lds + PG8_SA(b, h) + aoff + m * 2048 + k * 1024); } while (0)
; #define PG8_MMA(ai, bj, At, Bt) do { __builtin_amdgcn_s_setprio(1); _Pragma("unroll") for (int m = 0; m < 4; ++m) _Pragma("unroll") for (int n = 0; n < 2; ++n) _Pragma("unroll") for (int k = 0; k < 2; ++k) \
;         acc[ai][bj][m][n] = __builtin_amdgcn_mfma_f32_16x16x32_bf16(Bt[n][k], At[m][k], acc[ai][bj][m][n], 0, 0, 0); __builtin_amdgcn_s_setprio(0); } while (0)
; #define PG8_WAIT_V(n) asm volatile("s_waitcnt vmcnt(" #n ")" ::: "memory")
; #define PG8_WAIT_L(n) asm volatile("s_waitcnt lgkmcnt(" #n ")" ::: "memory")
; #define PG8_BAR __builtin_amdgcn_s_barrier()
; #define PG8_SCHED __builtin_amdgcn_sched_barrier(0)
; template <class Epi, class Sched, bool ALIGN_EPI = false, bool SP2 = false>
; __device__ __forceinline__ void gemm_phase(PG8_LAS unsigned char* lds, const Gemm g, const Sched& S, const Epi& E, int tid_in) {
;     ...
;             PG8_LDA(At, 1, 1); PG8_STAGE(PG8_SB(1, 0), b3, voffB); PG8_STAGE(PG8_SB(1, 1), b3 + hstep, voffB); PG8_STAGE(PG8_SA(1, 0), a3, voffA);
;             PG8_WAIT_V(8); PG8_WAIT_L(0); PG8_BAR; PG8_MMA(1, 0, At, B0); PG8_MMA(1, 1, At, B1); PG8_BAR; PG8_SCHED;
;     ...
;         if constexpr (ALIGN_EPI) { if (wr == 0) PG8_BAR; }
	s_add_i32 s62, s76, s70
	v_lshl_add_u64 v[196:197], v[196:197], 0, s[88:89]
	s_mov_b32 m0, s62
	ds_read_b128 v[162:165], v216 offset:49152
	ds_read_b128 v[184:187], v216 offset:50176
	ds_read_b128 v[188:191], v216 offset:51200
	ds_read_b128 v[192:195], v216 offset:52224
	ds_read_b128 v[218:221], v216 offset:53248
	ds_read_b128 v[222:225], v216 offset:54272
	ds_read_b128 v[226:229], v216 offset:55296
	ds_read_b128 v[230:233], v216 offset:56320
	global_load_lds_dwordx4 v[196:197], off
	s_add_i32 m0, s62, 0x2000
	s_add_u32 s62, s92, 0x80080
	v_lshl_add_u64 v[196:197], v[198:199], 0, s[88:89]
	s_addc_u32 s63, s93, 0
	s_add_i32 s76, s77, s70
	global_load_lds_dwordx4 v[196:197], off
	v_lshl_add_u64 v[196:197], s[62:63], 0, v[174:175]
	s_mov_b32 m0, s76
	s_nop 0
	global_load_lds_dwordx4 v[196:197], off
	v_lshl_add_u64 v[196:197], s[62:63], 0, v[178:179]
	s_add_i32 m0, s76, 0x2000
	s_nop 0
	global_load_lds_dwordx4 v[196:197], off
	v_lshl_add_u64 v[196:197], v[200:201], 0, s[88:89]
	s_mov_b32 m0, s97
	s_nop 0
	global_load_lds_dwordx4 v[196:197], off
	v_lshl_add_u64 v[196:197], v[234:235], 0, s[88:89]
	s_mov_b32 m0, s2
	s_nop 0
	global_load_lds_dwordx4 v[196:197], off
	s_waitcnt vmcnt(8)
	s_waitcnt lgkmcnt(0)
	s_barrier
	s_setprio 1
	v_mfma_f32_16x16x32_bf16 v[60:63], v[130:133], v[162:165], v[60:63]
	v_mfma_f32_16x16x32_bf16 v[56:59], v[138:141], v[162:165], v[56:59]
	v_mfma_f32_16x16x32_bf16 v[52:55], v[130:133], v[188:191], v[52:55]
	v_mfma_f32_16x16x32_bf16 v[48:51], v[138:141], v[188:191], v[48:51]
	v_mfma_f32_16x16x32_bf16 v[36:39], v[130:133], v[218:221], v[36:39]
	v_mfma_f32_16x16x32_bf16 v[32:35], v[138:141], v[218:221], v[32:35]
	v_mfma_f32_16x16x32_bf16 v[20:23], v[130:133], v[226:229], v[20:23]
	v_mfma_f32_16x16x32_bf16 v[16:19], v[138:141], v[226:229], v[16:19]
	v_mfma_f32_16x16x32_bf16 v[60:63], v[134:137], v[184:187], v[60:63]
	v_mfma_f32_16x16x32_bf16 v[56:59], v[142:145], v[184:187], v[56:59]
	v_mfma_f32_16x16x32_bf16 v[52:55], v[134:137], v[192:195], v[52:55]
	v_mfma_f32_16x16x32_bf16 v[48:51], v[142:145], v[192:195], v[48:51]
	v_mfma_f32_16x16x32_bf16 v[36:39], v[134:137], v[222:225], v[36:39]
	v_mfma_f32_16x16x32_bf16 v[32:35], v[142:145], v[222:225], v[32:35]
	v_mfma_f32_16x16x32_bf16 v[20:23], v[134:137], v[230:233], v[20:23]
	v_mfma_f32_16x16x32_bf16 v[16:19], v[142:145], v[230:233], v[16:19]
	s_setprio 0
	s_setprio 1
	v_mfma_f32_16x16x32_bf16 v[44:47], v[146:149], v[162:165], v[44:47]
	v_mfma_f32_16x16x32_bf16 v[40:43], v[154:157], v[162:165], v[40:43]
	v_mfma_f32_16x16x32_bf16 v[28:31], v[146:149], v[188:191], v[28:31]
	v_mfma_f32_16x16x32_bf16 v[24:27], v[154:157], v[188:191], v[24:27]
	v_mfma_f32_16x16x32_bf16 v[12:15], v[146:149], v[218:221], v[12:15]
	v_mfma_f32_16x16x32_bf16 v[8:11], v[154:157], v[218:221], v[8:11]
	v_mfma_f32_16x16x32_bf16 v[4:7], v[146:149], v[226:229], v[4:7]
	v_mfma_f32_16x16x32_bf16 v[0:3], v[154:157], v[226:229], v[0:3]
	v_mfma_f32_16x16x32_bf16 v[44:47], v[150:153], v[184:187], v[44:47]
	v_mfma_f32_16x16x32_bf16 v[40:43], v[158:161], v[184:187], v[40:43]
	v_mfma_f32_16x16x32_bf16 v[28:31], v[150:153], v[192:195], v[28:31]
	v_mfma_f32_16x16x32_bf16 v[24:27], v[158:161], v[192:195], v[24:27]
	v_mfma_f32_16x16x32_bf16 v[12:15], v[150:153], v[222:225], v[12:15]
	v_mfma_f32_16x16x32_bf16 v[8:11], v[158:161], v[222:225], v[8:11]
	v_mfma_f32_16x16x32_bf16 v[4:7], v[150:153], v[230:233], v[4:7]
	v_mfma_f32_16x16x32_bf16 v[0:3], v[158:161], v[230:233], v[0:3]
	s_setprio 0
	s_barrier
	s_add_i32 s75, s75, 2
	s_add_u32 s64, s64, 0x100
	s_addc_u32 s65, s65, 0
	s_add_u32 s73, s73, 0x100
	s_addc_u32 s74, s74, 0
	s_cmp_gt_u32 s75, 29
	s_cbranch_scc0 .LBB0_135
	s_and_b64 vcc, exec, s[38:39]
	s_cbranch_vccz .LBB0_138
	s_barrier

; #define PG8_STAGE(bufoff, gbase, voff) do { _Pragma("unroll") for (int _i = 0; _i < 2; ++_i) \
;         __builtin_amdgcn_global_load_lds((const unsigned*)((const char*)(gbase) + (voff)[_i]), (PG8_LAS unsigned*)(lds + (bufoff) + ldsw + _i * 8192), 16, 0, 0); } while (0)
; #define PG8_LDA(dst, b, h) do { _Pragma("unroll") for (int m = 0; m < 4; ++m) _Pragma("unroll") for (int k = 0; k < 2; ++k) dst[m][k] = *(const PG8_LAS bf16x8*)(lds + PG8_SA(b, h) + aoff + m * 2048 + k * 1024); } while (0)
; #define PG8_LDB(dst, b, h) do { _Pragma("unroll") for (int n = 0; n < 2; ++n) _Pragma("unroll") for (int k = 0; k < 2; ++k) dst[n][k] = *(const PG8_LAS bf16x8*)(lds + PG8_SB(b, h) + boff + n * 2048 + k * 1024); } while (0)
; #define PG8_MMA(ai, bj, At, Bt) do { __builtin_amdgcn_s_setprio(1); _Pragma("unroll") for (int m = 0; m < 4; ++m) _Pragma("unroll") for (int n = 0; n < 2; ++n) _Pragma("unroll") for (int k = 0; k < 2; ++k) \
;         acc[ai][bj][m][n] = __builtin_amdgcn_mfma_f32_16x16x32_bf16(Bt[n][k], At[m][k], acc[ai][bj][m][n], 0, 0, 0); __builtin_amdgcn_s_setprio(0); } while (0)
; #define PG8_WAIT_V(n) asm volatile("s_waitcnt vmcnt(" #n ")" ::: "memory")
; #define PG8_WAIT_L(n) asm volatile("s_waitcnt lgkmcnt(" #n ")" ::: "memory")
; template <class Epi, class Sched, bool ALIGN_EPI = false, bool SP2 = false>
; __device__ __forceinline__ void gemm_phase(PG8_LAS unsigned char* lds, const Gemm g, const Sched& S, const Epi& E, int tid_in) {
;     ...
;             const bool last = (t == nt - 2);
;             const char* a1 = cA + (size_t)(t + 1) * kstep;
;             const char* a2 = last ? nA : cA + (size_t)(t + 2) * kstep; const char* b2 = last ? nB : cB + (size_t)(t + 2) * kstep;
;             const char* a3 = a2 + kstep; const char* b3 = b2 + kstep;
;             if (last && has_next) S.a_ready(nxt);
;             if constexpr (SP2) {
;             PG8_LDB(B0, 0, 0); PG8_LDB(B1, 0, 1); PG8_SCHED; PG8_LDA(At, 0, 0); PG8_STAGE(PG8_SA(1, 1), a1 + hstep, voffA);
;             PG8_WAIT_V(8); PG8_WAIT_L(0); PG8_BAR; PG8_MMA(0, 0, At, B0); PG8_MMA(0, 1, At, B1); PG8_BAR; PG8_SCHED;
;             PG8_LDA(At, 0, 1); PG8_STAGE(PG8_SB(0, 0), b2, voffB); PG8_STAGE(PG8_SB(0, 1), b2 + hstep, voffB); PG8_STAGE(PG8_SA(0, 0), a2, voffA);
;             PG8_WAIT_V(8); PG8_WAIT_L(0); PG8_BAR; PG8_MMA(1, 0, At, B0); PG8_MMA(1, 1, At, B1); PG8_BAR; PG8_SCHED;
.LBB0_403:
	s_add_u32 s46, s44, 0xfff80080
	s_addc_u32 s47, s45, -1
	s_add_i32 s62, 0, 0x10000
	s_cmp_eq_u32 s75, 28
	s_cselect_b32 s65, s35, s47
	s_cselect_b32 s64, s43, s46
	v_add_u32_e32 v96, s62, v205
	s_cselect_b32 s47, s37, s74
	s_cselect_b32 s46, s72, s73
	s_add_i32 s76, 0, 0x14000
	ds_read_b128 v[130:133], v96
	ds_read_b128 v[134:137], v96 offset:1024
	ds_read_b128 v[138:141], v96 offset:2048
	ds_read_b128 v[142:145], v96 offset:3072
	v_add_u32_e32 v96, s76, v205
	ds_read_b128 v[146:149], v96
	ds_read_b128 v[150:153], v96 offset:1024
	ds_read_b128 v[154:157], v96 offset:2048
	ds_read_b128 v[158:161], v96 offset:3072
	v_lshl_add_u64 v[200:201], s[44:45], 0, v[180:181]
	s_add_i32 m0, s29, 0xc000
	ds_read_b128 v[162:165], v216
	ds_read_b128 v[184:187], v216 offset:1024
	ds_read_b128 v[188:191], v216 offset:2048
	ds_read_b128 v[192:195], v216 offset:3072
	ds_read_b128 v[196:199], v216 offset:4096
	ds_read_b128 v[218:221], v216 offset:5120
	ds_read_b128 v[222:225], v216 offset:6144
	ds_read_b128 v[226:229], v216 offset:7168
	global_load_lds_dwordx4 v[200:201], off
	v_lshl_add_u64 v[200:201], s[44:45], 0, v[182:183]
	s_add_i32 m0, s29, 0xe000
	s_nop 0
	global_load_lds_dwordx4 v[200:201], off
	s_waitcnt vmcnt(8)
	s_waitcnt lgkmcnt(0)
	s_barrier
	s_setprio 1
	v_mfma_f32_16x16x32_bf16 v[126:129], v[130:133], v[162:165], v[126:129]
	v_mfma_f32_16x16x32_bf16 v[122:125], v[138:141], v[162:165], v[122:125]
	v_mfma_f32_16x16x32_bf16 v[118:121], v[130:133], v[188:191], v[118:121]
	v_mfma_f32_16x16x32_bf16 v[114:117], v[138:141], v[188:191], v[114:117]
	v_mfma_f32_16x16x32_bf16 v[102:105], v[130:133], v[196:199], v[102:105]
	v_mfma_f32_16x16x32_bf16 v[98:101], v[138:141], v[196:199], v[98:101]
	v_mfma_f32_16x16x32_bf16 v[84:87], v[130:133], v[222:225], v[84:87]
	v_mfma_f32_16x16x32_bf16 v[80:83], v[138:141], v[222:225], v[80:83]
	v_mfma_f32_16x16x32_bf16 v[126:129], v[134:137], v[184:187], v[126:129]
	v_mfma_f32_16x16x32_bf16 v[122:125], v[142:145], v[184:187], v[122:125]
	v_mfma_f32_16x16x32_bf16 v[118:121], v[134:137], v[192:195], v[118:121]
	v_mfma_f32_16x16x32_bf16 v[114:117], v[142:145], v[192:195], v[114:117]
	v_mfma_f32_16x16x32_bf16 v[102:105], v[134:137], v[218:221], v[102:105]
	v_mfma_f32_16x16x32_bf16 v[98:101], v[142:145], v[218:221], v[98:101]
	v_mfma_f32_16x16x32_bf16 v[84:87], v[134:137], v[226:229], v[84:87]
	v_mfma_f32_16x16x32_bf16 v[80:83], v[142:145], v[226:229], v[80:83]
	s_setprio 0
	s_setprio 1
	v_mfma_f32_16x16x32_bf16 v[110:113], v[146:149], v[162:165], v[110:113]
	v_mfma_f32_16x16x32_bf16 v[106:109], v[154:157], v[162:165], v[106:109]
	v_mfma_f32_16x16x32_bf16 v[92:95], v[146:149], v[188:191], v[92:95]
	v_mfma_f32_16x16x32_bf16 v[88:91], v[154:157], v[188:191], v[88:91]
	v_mfma_f32_16x16x32_bf16 v[76:79], v[146:149], v[196:199], v[76:79]
	v_mfma_f32_16x16x32_bf16 v[72:75], v[154:157], v[196:199], v[72:75]
	v_mfma_f32_16x16x32_bf16 v[68:71], v[146:149], v[222:225], v[68:71]
	v_mfma_f32_16x16x32_bf16 v[64:67], v[154:157], v[222:225], v[64:67]
	v_mfma_f32_16x16x32_bf16 v[110:113], v[150:153], v[184:187], v[110:113]
	v_mfma_f32_16x16x32_bf16 v[106:109], v[158:161], v[184:187], v[106:109]
	v_mfma_f32_16x16x32_bf16 v[92:95], v[150:153], v[192:195], v[92:95]
	v_mfma_f32_16x16x32_bf16 v[88:91], v[158:161], v[192:195], v[88:91]
	v_mfma_f32_16x16x32_bf16 v[76:79], v[150:153], v[218:221], v[76:79]
	v_mfma_f32_16x16x32_bf16 v[72:75], v[158:161], v[218:221], v[72:75]
	v_mfma_f32_16x16x32_bf16 v[68:71], v[150:153], v[226:229], v[68:71]
	v_mfma_f32_16x16x32_bf16 v[64:67], v[158:161], v[226:229], v[64:67]
	s_setprio 0
	s_barrier
	s_add_i32 s62, s62, s96
	v_lshl_add_u64 v[200:201], s[46:47], 0, v[174:175]
	s_mov_b32 m0, s62
	ds_read_b128 v[162:165], v216 offset:16384
	ds_read_b128 v[184:187], v216 offset:17408
	ds_read_b128 v[188:191], v216 offset:18432
	ds_read_b128 v[192:195], v216 offset:19456
	ds_read_b128 v[196:199], v216 offset:20480
	ds_read_b128 v[218:221], v216 offset:21504
	ds_read_b128 v[222:225], v216 offset:22528
	ds_read_b128 v[226:229], v216 offset:23552
	global_load_lds_dwordx4 v[200:201], off
	s_add_i32 m0, s62, 0x2000
	s_add_u32 s62, s46, 0x80000
	v_lshl_add_u64 v[230:231], s[46:47], 0, v[178:179]
	s_addc_u32 s63, s47, 0
	s_add_i32 s76, s76, s96
	global_load_lds_dwordx4 v[230:231], off
	v_lshl_add_u64 v[232:233], s[62:63], 0, v[174:175]
	s_mov_b32 m0, s76
	v_lshl_add_u64 v[234:235], s[64:65], 0, v[176:177]
	global_load_lds_dwordx4 v[232:233], off
	v_lshl_add_u64 v[232:233], s[62:63], 0, v[178:179]
	s_add_i32 m0, s76, 0x2000
	s_nop 0
	global_load_lds_dwordx4 v[232:233], off
	v_lshl_add_u64 v[232:233], s[64:65], 0, v[172:173]
	s_mov_b32 m0, s29
	s_nop 0
	global_load_lds_dwordx4 v[232:233], off
	s_mov_b32 m0, s97
	s_nop 0
	global_load_lds_dwordx4 v[234:235], off
	s_waitcnt vmcnt(8)
	s_waitcnt lgkmcnt(0)
	s_barrier
; #define PG8_STAGE(bufoff, gbase, voff) do { _Pragma("unroll") for (int _i = 0; _i < 2; ++_i) \
;         __builtin_amdgcn_global_load_lds((const unsigned*)((const char*)(gbase) + (voff)[_i]), (PG8_LAS unsigned*)(lds + (bufoff) + ldsw + _i * 8192), 16, 0, 0); } while (0)
; #define PG8_LDA(dst, b, h) do { _Pragma("unroll") for (int m = 0; m < 4; ++m) _Pragma("unroll") for (int k = 0; k < 2; ++k) dst[m][k] = *(const PG8_LAS bf16x8*)(lds + PG8_SA(b, h) + aoff + m * 2048 + k * 1024); } while (0)
; #define PG8_LDB(dst, b, h) do { _Pragma("unroll") for (int n = 0; n < 2; ++n) _Pragma("unroll") for (int k = 0; k < 2; ++k) dst[n][k] = *(const PG8_LAS bf16x8*)(lds + PG8_SB(b, h) + boff + n * 2048 + k * 1024); } while (0)
; #define PG8_MMA(ai, bj, At, Bt) do { __builtin_amdgcn_s_setprio(1); _Pragma("unroll") for (int m = 0; m < 4; ++m) _Pragma("unroll") for (int n = 0; n < 2; ++n) _Pragma("unroll") for (int k = 0; k < 2; ++k) \
;         acc[ai][bj][m][n] = __builtin_amdgcn_mfma_f32_16x16x32_bf16(Bt[n][k], At[m][k], acc[ai][bj][m][n], 0, 0, 0); __builtin_amdgcn_s_setprio(0); } while (0)
; #define PG8_WAIT_V(n) asm volatile("s_waitcnt vmcnt(" #n ")" ::: "memory")
; #define PG8_WAIT_L(n) asm volatile("s_waitcnt lgkmcnt(" #n ")" ::: "memory")
; #define PG8_BAR __builtin_amdgcn_s_barrier()
; #define PG8_SCHED __builtin_amdgcn_sched_barrier(0)
; template <class Epi, class Sched, bool ALIGN_EPI = false, bool SP2 = false>
; __device__ __forceinline__ void gemm_phase(PG8_LAS unsigned char* lds, const Gemm g, const Sched& S, const Epi& E, int tid_in) {
;     ...
;             PG8_WAIT_V(8); PG8_WAIT_L(0); PG8_BAR; PG8_MMA(1, 0, At, B0); PG8_MMA(1, 1, At, B1); PG8_BAR; PG8_SCHED;
;             PG8_LDB(B0, 1, 0); PG8_LDB(B1, 1, 1); PG8_SCHED; PG8_LDA(At, 1, 0); PG8_STAGE(PG8_SA(0, 1), a2 + hstep, voffA);
;             PG8_WAIT_V(8); PG8_WAIT_L(0); PG8_BAR; PG8_MMA(0, 0, At, B0); PG8_MMA(0, 1, At, B1); PG8_BAR; PG8_SCHED;
	s_setprio 1
	v_mfma_f32_16x16x32_bf16 v[60:63], v[130:133], v[162:165], v[60:63]
	v_mfma_f32_16x16x32_bf16 v[56:59], v[138:141], v[162:165], v[56:59]
	v_mfma_f32_16x16x32_bf16 v[52:55], v[130:133], v[188:191], v[52:55]
	v_mfma_f32_16x16x32_bf16 v[48:51], v[138:141], v[188:191], v[48:51]
	v_mfma_f32_16x16x32_bf16 v[36:39], v[130:133], v[196:199], v[36:39]
	v_mfma_f32_16x16x32_bf16 v[32:35], v[138:141], v[196:199], v[32:35]
	v_mfma_f32_16x16x32_bf16 v[20:23], v[130:133], v[222:225], v[20:23]
	v_mfma_f32_16x16x32_bf16 v[16:19], v[138:141], v[222:225], v[16:19]
	v_mfma_f32_16x16x32_bf16 v[60:63], v[134:137], v[184:187], v[60:63]
	v_mfma_f32_16x16x32_bf16 v[56:59], v[142:145], v[184:187], v[56:59]
	v_mfma_f32_16x16x32_bf16 v[52:55], v[134:137], v[192:195], v[52:55]
	v_mfma_f32_16x16x32_bf16 v[48:51], v[142:145], v[192:195], v[48:51]
	v_mfma_f32_16x16x32_bf16 v[36:39], v[134:137], v[218:221], v[36:39]
	v_mfma_f32_16x16x32_bf16 v[32:35], v[142:145], v[218:221], v[32:35]
	v_mfma_f32_16x16x32_bf16 v[20:23], v[134:137], v[226:229], v[20:23]
	v_mfma_f32_16x16x32_bf16 v[16:19], v[142:145], v[226:229], v[16:19]
	s_setprio 0
	s_setprio 1
	v_mfma_f32_16x16x32_bf16 v[44:47], v[146:149], v[162:165], v[44:47]
	v_mfma_f32_16x16x32_bf16 v[40:43], v[154:157], v[162:165], v[40:43]
	v_mfma_f32_16x16x32_bf16 v[28:31], v[146:149], v[188:191], v[28:31]
	v_mfma_f32_16x16x32_bf16 v[24:27], v[154:157], v[188:191], v[24:27]
	v_mfma_f32_16x16x32_bf16 v[12:15], v[146:149], v[196:199], v[12:15]
	v_mfma_f32_16x16x32_bf16 v[8:11], v[154:157], v[196:199], v[8:11]
	v_mfma_f32_16x16x32_bf16 v[4:7], v[146:149], v[222:225], v[4:7]
	v_mfma_f32_16x16x32_bf16 v[0:3], v[154:157], v[222:225], v[0:3]
	v_mfma_f32_16x16x32_bf16 v[44:47], v[150:153], v[184:187], v[44:47]
	v_mfma_f32_16x16x32_bf16 v[40:43], v[158:161], v[184:187], v[40:43]
	v_mfma_f32_16x16x32_bf16 v[28:31], v[150:153], v[192:195], v[28:31]
	v_mfma_f32_16x16x32_bf16 v[24:27], v[158:161], v[192:195], v[24:27]
	v_mfma_f32_16x16x32_bf16 v[12:15], v[150:153], v[218:221], v[12:15]
	v_mfma_f32_16x16x32_bf16 v[8:11], v[158:161], v[218:221], v[8:11]
	v_mfma_f32_16x16x32_bf16 v[4:7], v[150:153], v[226:229], v[4:7]
	v_mfma_f32_16x16x32_bf16 v[0:3], v[158:161], v[226:229], v[0:3]
	s_setprio 0
	s_barrier
	s_add_i32 s76, 0, 0x18000
	v_add_u32_e32 v96, s76, v205
	s_add_i32 s77, 0, 0x1c000
	ds_read_b128 v[130:133], v96
	ds_read_b128 v[134:137], v96 offset:1024
	ds_read_b128 v[138:141], v96 offset:2048
	ds_read_b128 v[142:145], v96 offset:3072
	v_add_u32_e32 v96, s77, v205
	ds_read_b128 v[146:149], v96
	ds_read_b128 v[150:153], v96 offset:1024
	ds_read_b128 v[154:157], v96 offset:2048
	ds_read_b128 v[158:161], v96 offset:3072
	s_add_u32 s62, s64, 0x80000
	s_addc_u32 s63, s65, 0
	s_mov_b32 m0, s20
	v_lshl_add_u64 v[236:237], s[62:63], 0, v[172:173]
	ds_read_b128 v[162:165], v216 offset:32768
	ds_read_b128 v[184:187], v216 offset:33792
	ds_read_b128 v[188:191], v216 offset:34816
	ds_read_b128 v[192:195], v216 offset:35840
	ds_read_b128 v[196:199], v216 offset:36864
	ds_read_b128 v[218:221], v216 offset:37888
	ds_read_b128 v[222:225], v216 offset:38912
	ds_read_b128 v[226:229], v216 offset:39936
	global_load_lds_dwordx4 v[236:237], off
	v_lshl_add_u64 v[236:237], s[62:63], 0, v[176:177]
	s_mov_b32 m0, s21
	s_nop 0
	global_load_lds_dwordx4 v[236:237], off
	s_waitcnt vmcnt(8)
	s_waitcnt lgkmcnt(0)
	s_barrier
	s_setprio 1
	v_mfma_f32_16x16x32_bf16 v[126:129], v[130:133], v[162:165], v[126:129]
	v_mfma_f32_16x16x32_bf16 v[122:125], v[138:141], v[162:165], v[122:125]
	v_mfma_f32_16x16x32_bf16 v[118:121], v[130:133], v[188:191], v[118:121]
	v_mfma_f32_16x16x32_bf16 v[114:117], v[138:141], v[188:191], v[114:117]
	v_mfma_f32_16x16x32_bf16 v[102:105], v[130:133], v[196:199], v[102:105]
	v_mfma_f32_16x16x32_bf16 v[98:101], v[138:141], v[196:199], v[98:101]
	v_mfma_f32_16x16x32_bf16 v[84:87], v[130:133], v[222:225], v[84:87]
	v_mfma_f32_16x16x32_bf16 v[80:83], v[138:141], v[222:225], v[80:83]
	v_mfma_f32_16x16x32_bf16 v[126:129], v[134:137], v[184:187], v[126:129]
	v_mfma_f32_16x16x32_bf16 v[122:125], v[142:145], v[184:187], v[122:125]
	v_mfma_f32_16x16x32_bf16 v[118:121], v[134:137], v[192:195], v[118:121]
	v_mfma_f32_16x16x32_bf16 v[114:117], v[142:145], v[192:195], v[114:117]
	v_mfma_f32_16x16x32_bf16 v[102:105], v[134:137], v[218:221], v[102:105]
	v_mfma_f32_16x16x32_bf16 v[98:101], v[142:145], v[218:221], v[98:101]
	v_mfma_f32_16x16x32_bf16 v[84:87], v[134:137], v[226:229], v[84:87]
	v_mfma_f32_16x16x32_bf16 v[80:83], v[142:145], v[226:229], v[80:83]
	s_setprio 0
	s_setprio 1
	v_mfma_f32_16x16x32_bf16 v[110:113], v[146:149], v[162:165], v[110:113]
	v_mfma_f32_16x16x32_bf16 v[106:109], v[154:157], v[162:165], v[106:109]
	v_mfma_f32_16x16x32_bf16 v[92:95], v[146:149], v[188:191], v[92:95]
	v_mfma_f32_16x16x32_bf16 v[88:91], v[154:157], v[188:191], v[88:91]
	v_mfma_f32_16x16x32_bf16 v[76:79], v[146:149], v[196:199], v[76:79]
	v_mfma_f32_16x16x32_bf16 v[72:75], v[154:157], v[196:199], v[72:75]
	v_mfma_f32_16x16x32_bf16 v[68:71], v[146:149], v[222:225], v[68:71]
	v_mfma_f32_16x16x32_bf16 v[64:67], v[154:157], v[222:225], v[64:67]
	v_mfma_f32_16x16x32_bf16 v[110:113], v[150:153], v[184:187], v[110:113]
	v_mfma_f32_16x16x32_bf16 v[106:109], v[158:161], v[184:187], v[106:109]
	v_mfma_f32_16x16x32_bf16 v[92:95], v[150:153], v[192:195], v[92:95]
	v_mfma_f32_16x16x32_bf16 v[88:91], v[158:161], v[192:195], v[88:91]
	v_mfma_f32_16x16x32_bf16 v[76:79], v[150:153], v[218:221], v[76:79]
	v_mfma_f32_16x16x32_bf16 v[72:75], v[158:161], v[218:221], v[72:75]
	v_mfma_f32_16x16x32_bf16 v[68:71], v[150:153], v[226:229], v[68:71]
	v_mfma_f32_16x16x32_bf16 v[64:67], v[158:161], v[226:229], v[64:67]
	s_setprio 0
	s_barrier
; #define PG8_STAGE(bufoff, gbase, voff) do { _Pragma("unroll") for (int _i = 0; _i < 2; ++_i) \
;         __builtin_amdgcn_global_load_lds((const unsigned*)((const char*)(gbase) + (voff)[_i]), (PG8_LAS unsigned*)(lds + (bufoff) + ldsw + _i * 8192), 16, 0, 0); } while (0)
; #define PG8_LDA(dst, b, h) do { _Pragma("unroll") for (int m = 0; m < 4; ++m) _Pragma("unroll") for (int k = 0; k < 2; ++k) dst[m][k] = *(const PG8_LAS bf16x8*)(lds + PG8_SA(b, h) + aoff + m * 2048 + k * 1024); } while (0)
; #define PG8_MMA(ai, bj, At, Bt) do { __builtin_amdgcn_s_setprio(1); _Pragma("unroll") for (int m = 0; m < 4; ++m) _Pragma("unroll") for (int n = 0; n < 2; ++n) _Pragma("unroll") for (int k = 0; k < 2; ++k) \
;         acc[ai][bj][m][n] = __builtin_amdgcn_mfma_f32_16x16x32_bf16(Bt[n][k], At[m][k], acc[ai][bj][m][n], 0, 0, 0); __builtin_amdgcn_s_setprio(0); } while (0)
; #define PG8_WAIT_V(n) asm volatile("s_waitcnt vmcnt(" #n ")" ::: "memory")
; #define PG8_WAIT_L(n) asm volatile("s_waitcnt lgkmcnt(" #n ")" ::: "memory")
; #define PG8_BAR __builtin_amdgcn_s_barrier()
; #define PG8_SCHED __builtin_amdgcn_sched_barrier(0)
; template <class Epi, class Sched, bool ALIGN_EPI = false, bool SP2 = false>
; __device__ __forceinline__ void gemm_phase(PG8_LAS unsigned char* lds, const Gemm g, const Sched& S, const Epi& E, int tid_in) {
;     ...
;             PG8_LDA(At, 1, 1); PG8_STAGE(PG8_SB(1, 0), b3, voffB); PG8_STAGE(PG8_SB(1, 1), b3 + hstep, voffB); PG8_STAGE(PG8_SA(1, 0), a3, voffA);
;             PG8_WAIT_V(8); PG8_WAIT_L(0); PG8_BAR; PG8_MMA(1, 0, At, B0); PG8_MMA(1, 1, At, B1); PG8_BAR; PG8_SCHED;
;     __device__ __forceinline__ void operator()(const acc_t& acc, const pg8::Unit& u, int wr, int wc, int fr, int fq) const {
;         const int pn = u.pn, row0 = u.pm * 256 + wr * 64 + fr, cw = wc * 32 + 8 * fq;
;         if (pn < 4) store_tile_bf16<0>(acc, RQ, 1024, row0, pn * 256 + cw);
	s_add_i32 s62, s76, s96
	v_lshl_add_u64 v[200:201], v[200:201], 0, s[88:89]
	s_mov_b32 m0, s62
	ds_read_b128 v[162:165], v216 offset:49152
	ds_read_b128 v[184:187], v216 offset:50176
	ds_read_b128 v[188:191], v216 offset:51200
	ds_read_b128 v[192:195], v216 offset:52224
	ds_read_b128 v[196:199], v216 offset:53248
	ds_read_b128 v[218:221], v216 offset:54272
	ds_read_b128 v[222:225], v216 offset:55296
	ds_read_b128 v[226:229], v216 offset:56320
	global_load_lds_dwordx4 v[200:201], off
	s_add_i32 m0, s62, 0x2000
	s_add_u32 s46, s46, 0x80080
	v_lshl_add_u64 v[200:201], v[230:231], 0, s[88:89]
	s_addc_u32 s47, s47, 0
	s_add_i32 s62, s77, s96
	global_load_lds_dwordx4 v[200:201], off
	v_lshl_add_u64 v[200:201], s[46:47], 0, v[174:175]
	s_mov_b32 m0, s62
	s_nop 0
	global_load_lds_dwordx4 v[200:201], off
	v_lshl_add_u64 v[200:201], s[46:47], 0, v[178:179]
	s_add_i32 m0, s62, 0x2000
	s_nop 0
	global_load_lds_dwordx4 v[200:201], off
	v_lshl_add_u64 v[200:201], v[232:233], 0, s[88:89]
	s_mov_b32 m0, s22
	s_nop 0
	global_load_lds_dwordx4 v[200:201], off
	v_lshl_add_u64 v[200:201], v[234:235], 0, s[88:89]
	s_mov_b32 m0, s23
	s_nop 0
	global_load_lds_dwordx4 v[200:201], off
	s_waitcnt vmcnt(8)
	s_waitcnt lgkmcnt(0)
	s_barrier
	s_setprio 1
	v_mfma_f32_16x16x32_bf16 v[60:63], v[130:133], v[162:165], v[60:63]
	v_mfma_f32_16x16x32_bf16 v[56:59], v[138:141], v[162:165], v[56:59]
	v_mfma_f32_16x16x32_bf16 v[52:55], v[130:133], v[188:191], v[52:55]
	v_mfma_f32_16x16x32_bf16 v[48:51], v[138:141], v[188:191], v[48:51]
	v_mfma_f32_16x16x32_bf16 v[36:39], v[130:133], v[196:199], v[36:39]
	v_mfma_f32_16x16x32_bf16 v[32:35], v[138:141], v[196:199], v[32:35]
	v_mfma_f32_16x16x32_bf16 v[20:23], v[130:133], v[222:225], v[20:23]
	v_mfma_f32_16x16x32_bf16 v[16:19], v[138:141], v[222:225], v[16:19]
	v_mfma_f32_16x16x32_bf16 v[60:63], v[134:137], v[184:187], v[60:63]
	v_mfma_f32_16x16x32_bf16 v[56:59], v[142:145], v[184:187], v[56:59]
	v_mfma_f32_16x16x32_bf16 v[52:55], v[134:137], v[192:195], v[52:55]
	v_mfma_f32_16x16x32_bf16 v[48:51], v[142:145], v[192:195], v[48:51]
	v_mfma_f32_16x16x32_bf16 v[36:39], v[134:137], v[218:221], v[36:39]
	v_mfma_f32_16x16x32_bf16 v[32:35], v[142:145], v[218:221], v[32:35]
	v_mfma_f32_16x16x32_bf16 v[20:23], v[134:137], v[226:229], v[20:23]
	v_mfma_f32_16x16x32_bf16 v[16:19], v[142:145], v[226:229], v[16:19]
	s_setprio 0
	s_setprio 1
	v_mfma_f32_16x16x32_bf16 v[44:47], v[146:149], v[162:165], v[44:47]
	v_mfma_f32_16x16x32_bf16 v[40:43], v[154:157], v[162:165], v[40:43]
	v_mfma_f32_16x16x32_bf16 v[28:31], v[146:149], v[188:191], v[28:31]
	v_mfma_f32_16x16x32_bf16 v[24:27], v[154:157], v[188:191], v[24:27]
	v_mfma_f32_16x16x32_bf16 v[12:15], v[146:149], v[196:199], v[12:15]
	v_mfma_f32_16x16x32_bf16 v[8:11], v[154:157], v[196:199], v[8:11]
	v_mfma_f32_16x16x32_bf16 v[4:7], v[146:149], v[222:225], v[4:7]
	v_mfma_f32_16x16x32_bf16 v[0:3], v[154:157], v[222:225], v[0:3]
	v_mfma_f32_16x16x32_bf16 v[44:47], v[150:153], v[184:187], v[44:47]
	v_mfma_f32_16x16x32_bf16 v[40:43], v[158:161], v[184:187], v[40:43]
	v_mfma_f32_16x16x32_bf16 v[28:31], v[150:153], v[192:195], v[28:31]
	v_mfma_f32_16x16x32_bf16 v[24:27], v[158:161], v[192:195], v[24:27]
	v_mfma_f32_16x16x32_bf16 v[12:15], v[150:153], v[218:221], v[12:15]
	v_mfma_f32_16x16x32_bf16 v[8:11], v[158:161], v[218:221], v[8:11]
	v_mfma_f32_16x16x32_bf16 v[4:7], v[150:153], v[226:229], v[4:7]
	v_mfma_f32_16x16x32_bf16 v[0:3], v[158:161], v[226:229], v[0:3]
	s_setprio 0
	s_barrier
	s_add_i32 s75, s75, 2
	s_add_u32 s44, s44, 0x100
	s_addc_u32 s45, s45, 0
	s_add_u32 s73, s73, 0x100
	s_addc_u32 s74, s74, 0
	s_cmp_gt_u32 s75, 29
	s_cbranch_scc0 .LBB0_403
	s_and_b64 vcc, exec, s[30:31]
	s_cbranch_vccnz .LBB0_408
	v_lshl_add_u32 v184, s42, 8, v204
	s_cmp_gt_i32 s28, 3
	s_mov_b64 s[42:43], -1
	s_cbranch_scc1 .LBB0_409

; #define PG8_STAGE(bufoff, gbase, voff) do { _Pragma("unroll") for (int _i = 0; _i < 2; ++_i) \
;         __builtin_amdgcn_global_load_lds((const unsigned*)((const char*)(gbase) + (voff)[_i]), (PG8_LAS unsigned*)(lds + (bufoff) + ldsw + _i * 8192), 16, 0, 0); } while (0)
; #define PG8_LDA(dst, b, h) do { _Pragma("unroll") for (int m = 0; m < 4; ++m) _Pragma("unroll") for (int k = 0; k < 2; ++k) dst[m][k] = *(const PG8_LAS bf16x8*)(lds + PG8_SA(b, h) + aoff + m * 2048 + k * 1024); } while (0)
; #define PG8_LDB(dst, b, h) do { _Pragma("unroll") for (int n = 0; n < 2; ++n) _Pragma("unroll") for (int k = 0; k < 2; ++k) dst[n][k] = *(const PG8_LAS bf16x8*)(lds + PG8_SB(b, h) + boff + n * 2048 + k * 1024); } while (0)
; #define PG8_MMA(ai, bj, At, Bt) do { __builtin_amdgcn_s_setprio(1); _Pragma("unroll") for (int m = 0; m < 4; ++m) _Pragma("unroll") for (int n = 0; n < 2; ++n) _Pragma("unroll") for (int k = 0; k < 2; ++k) \
;         acc[ai][bj][m][n] = __builtin_amdgcn_mfma_f32_16x16x32_bf16(Bt[n][k], At[m][k], acc[ai][bj][m][n], 0, 0, 0); __builtin_amdgcn_s_setprio(0); } while (0)
; #define PG8_WAIT_V(n) asm volatile("s_waitcnt vmcnt(" #n ")" ::: "memory")
; #define PG8_WAIT_L(n) asm volatile("s_waitcnt lgkmcnt(" #n ")" ::: "memory")
; template <class Epi, class Sched, bool ALIGN_EPI = false, bool SP2 = false>
; __device__ __forceinline__ void gemm_phase(PG8_LAS unsigned char* lds, const Gemm g, const Sched& S, const Epi& E, int tid_in) {
;     ...
;             const bool last = (t == nt - 2);
;             const char* a1 = cA + (size_t)(t + 1) * kstep;
;             const char* a2 = last ? nA : cA + (size_t)(t + 2) * kstep; const char* b2 = last ? nB : cB + (size_t)(t + 2) * kstep;
;             const char* a3 = a2 + kstep; const char* b3 = b2 + kstep;
;             if (last && has_next) S.a_ready(nxt);
;             if constexpr (SP2) {
;             PG8_LDB(B0, 0, 0); PG8_LDB(B1, 0, 1); PG8_SCHED; PG8_LDA(At, 0, 0); PG8_STAGE(PG8_SA(1, 1), a1 + hstep, voffA);
;             PG8_WAIT_V(8); PG8_WAIT_L(0); PG8_BAR; PG8_MMA(0, 0, At, B0); PG8_MMA(0, 1, At, B1); PG8_BAR; PG8_SCHED;
;             PG8_LDA(At, 0, 1); PG8_STAGE(PG8_SB(0, 0), b2, voffB); PG8_STAGE(PG8_SB(0, 1), b2 + hstep, voffB); PG8_STAGE(PG8_SA(0, 0), a2, voffA);
;             PG8_WAIT_V(8); PG8_WAIT_L(0); PG8_BAR; PG8_MMA(1, 0, At, B0); PG8_MMA(1, 1, At, B1); PG8_BAR; PG8_SCHED;
.LBB0_455:
	s_add_u32 s42, s40, 0xfff80080
	s_addc_u32 s43, s41, -1
	s_add_i32 s62, 0, 0x10000
	s_cmp_eq_u32 s77, 28
	s_cselect_b32 s45, s39, s43
	s_cselect_b32 s44, s73, s42
	v_add_u32_e32 v96, s62, v203
	s_cselect_b32 s43, s37, s76
	s_cselect_b32 s42, s74, s75
	s_add_i32 s78, 0, 0x14000
	ds_read_b128 v[130:133], v96
	ds_read_b128 v[134:137], v96 offset:1024
	ds_read_b128 v[138:141], v96 offset:2048
	ds_read_b128 v[142:145], v96 offset:3072
	v_add_u32_e32 v96, s78, v203
	ds_read_b128 v[146:149], v96
	ds_read_b128 v[150:153], v96 offset:1024
	ds_read_b128 v[154:157], v96 offset:2048
	ds_read_b128 v[158:161], v96 offset:3072
	v_lshl_add_u64 v[196:197], s[40:41], 0, v[180:181]
	s_add_i32 m0, s1, 0xc000
	ds_read_b128 v[162:165], v215
	ds_read_b128 v[184:187], v215 offset:1024
	ds_read_b128 v[188:191], v215 offset:2048
	ds_read_b128 v[192:195], v215 offset:3072
	ds_read_b128 v[216:219], v215 offset:4096
	ds_read_b128 v[220:223], v215 offset:5120
	ds_read_b128 v[224:227], v215 offset:6144
	ds_read_b128 v[228:231], v215 offset:7168
	global_load_lds_dwordx4 v[196:197], off
	v_lshl_add_u64 v[196:197], s[40:41], 0, v[182:183]
	s_add_i32 m0, s1, 0xe000
	s_nop 0
	global_load_lds_dwordx4 v[196:197], off
	s_waitcnt vmcnt(8)
	s_waitcnt lgkmcnt(0)
	s_barrier
	s_setprio 1
	v_mfma_f32_16x16x32_bf16 v[126:129], v[130:133], v[162:165], v[126:129]
	v_mfma_f32_16x16x32_bf16 v[122:125], v[138:141], v[162:165], v[122:125]
	v_mfma_f32_16x16x32_bf16 v[118:121], v[130:133], v[188:191], v[118:121]
	v_mfma_f32_16x16x32_bf16 v[114:117], v[138:141], v[188:191], v[114:117]
	v_mfma_f32_16x16x32_bf16 v[102:105], v[130:133], v[216:219], v[102:105]
	v_mfma_f32_16x16x32_bf16 v[98:101], v[138:141], v[216:219], v[98:101]
	v_mfma_f32_16x16x32_bf16 v[84:87], v[130:133], v[224:227], v[84:87]
	v_mfma_f32_16x16x32_bf16 v[80:83], v[138:141], v[224:227], v[80:83]
	v_mfma_f32_16x16x32_bf16 v[126:129], v[134:137], v[184:187], v[126:129]
	v_mfma_f32_16x16x32_bf16 v[122:125], v[142:145], v[184:187], v[122:125]
	v_mfma_f32_16x16x32_bf16 v[118:121], v[134:137], v[192:195], v[118:121]
	v_mfma_f32_16x16x32_bf16 v[114:117], v[142:145], v[192:195], v[114:117]
	v_mfma_f32_16x16x32_bf16 v[102:105], v[134:137], v[220:223], v[102:105]
	v_mfma_f32_16x16x32_bf16 v[98:101], v[142:145], v[220:223], v[98:101]
	v_mfma_f32_16x16x32_bf16 v[84:87], v[134:137], v[228:231], v[84:87]
	v_mfma_f32_16x16x32_bf16 v[80:83], v[142:145], v[228:231], v[80:83]
	s_setprio 0
	s_setprio 1
	v_mfma_f32_16x16x32_bf16 v[110:113], v[146:149], v[162:165], v[110:113]
	v_mfma_f32_16x16x32_bf16 v[106:109], v[154:157], v[162:165], v[106:109]
	v_mfma_f32_16x16x32_bf16 v[92:95], v[146:149], v[188:191], v[92:95]
	v_mfma_f32_16x16x32_bf16 v[88:91], v[154:157], v[188:191], v[88:91]
	v_mfma_f32_16x16x32_bf16 v[76:79], v[146:149], v[216:219], v[76:79]
	v_mfma_f32_16x16x32_bf16 v[72:75], v[154:157], v[216:219], v[72:75]
	v_mfma_f32_16x16x32_bf16 v[68:71], v[146:149], v[224:227], v[68:71]
	v_mfma_f32_16x16x32_bf16 v[64:67], v[154:157], v[224:227], v[64:67]
	v_mfma_f32_16x16x32_bf16 v[110:113], v[150:153], v[184:187], v[110:113]
	v_mfma_f32_16x16x32_bf16 v[106:109], v[158:161], v[184:187], v[106:109]
	v_mfma_f32_16x16x32_bf16 v[92:95], v[150:153], v[192:195], v[92:95]
	v_mfma_f32_16x16x32_bf16 v[88:91], v[158:161], v[192:195], v[88:91]
	v_mfma_f32_16x16x32_bf16 v[76:79], v[150:153], v[220:223], v[76:79]
	v_mfma_f32_16x16x32_bf16 v[72:75], v[158:161], v[220:223], v[72:75]
	v_mfma_f32_16x16x32_bf16 v[68:71], v[150:153], v[228:231], v[68:71]
	v_mfma_f32_16x16x32_bf16 v[64:67], v[158:161], v[228:231], v[64:67]
	s_setprio 0
	s_barrier
	s_add_i32 s62, s62, s64
	v_lshl_add_u64 v[196:197], s[42:43], 0, v[176:177]
	s_mov_b32 m0, s62
	ds_read_b128 v[162:165], v215 offset:16384
	ds_read_b128 v[184:187], v215 offset:17408
	ds_read_b128 v[188:191], v215 offset:18432
	ds_read_b128 v[192:195], v215 offset:19456
	ds_read_b128 v[216:219], v215 offset:20480
	ds_read_b128 v[220:223], v215 offset:21504
	ds_read_b128 v[224:227], v215 offset:22528
	ds_read_b128 v[228:231], v215 offset:23552
	global_load_lds_dwordx4 v[196:197], off
	s_add_i32 m0, s62, 0x2000
	s_add_u32 s62, s42, 0x80000
	v_lshl_add_u64 v[198:199], s[42:43], 0, v[172:173]
	s_addc_u32 s63, s43, 0
	s_add_i32 s78, s78, s64
	global_load_lds_dwordx4 v[198:199], off
	v_lshl_add_u64 v[200:201], s[62:63], 0, v[176:177]
	s_mov_b32 m0, s78
	v_lshl_add_u64 v[232:233], s[44:45], 0, v[174:175]
	global_load_lds_dwordx4 v[200:201], off
	v_lshl_add_u64 v[200:201], s[62:63], 0, v[172:173]
	s_add_i32 m0, s78, 0x2000
	s_nop 0
	global_load_lds_dwordx4 v[200:201], off
	v_lshl_add_u64 v[200:201], s[44:45], 0, v[178:179]
	s_mov_b32 m0, s1
	s_nop 0
	global_load_lds_dwordx4 v[200:201], off
	s_mov_b32 m0, s3
	s_nop 0
	global_load_lds_dwordx4 v[232:233], off
	s_waitcnt vmcnt(8)
	s_waitcnt lgkmcnt(0)
	s_barrier
; #define PG8_STAGE(bufoff, gbase, voff) do { _Pragma("unroll") for (int _i = 0; _i < 2; ++_i) \
;         __builtin_amdgcn_global_load_lds((const unsigned*)((const char*)(gbase) + (voff)[_i]), (PG8_LAS unsigned*)(lds + (bufoff) + ldsw + _i * 8192), 16, 0, 0); } while (0)
; #define PG8_LDA(dst, b, h) do { _Pragma("unroll") for (int m = 0; m < 4; ++m) _Pragma("unroll") for (int k = 0; k < 2; ++k) dst[m][k] = *(const PG8_LAS bf16x8*)(lds + PG8_SA(b, h) + aoff + m * 2048 + k * 1024); } while (0)
; #define PG8_LDB(dst, b, h) do { _Pragma("unroll") for (int n = 0; n < 2; ++n) _Pragma("unroll") for (int k = 0; k < 2; ++k) dst[n][k] = *(const PG8_LAS bf16x8*)(lds + PG8_SB(b, h) + boff + n * 2048 + k * 1024); } while (0)
; #define PG8_MMA(ai, bj, At, Bt) do { __builtin_amdgcn_s_setprio(1); _Pragma("unroll") for (int m = 0; m < 4; ++m) _Pragma("unroll") for (int n = 0; n < 2; ++n) _Pragma("unroll") for (int k = 0; k < 2; ++k) \
;         acc[ai][bj][m][n] = __builtin_amdgcn_mfma_f32_16x16x32_bf16(Bt[n][k], At[m][k], acc[ai][bj][m][n], 0, 0, 0); __builtin_amdgcn_s_setprio(0); } while (0)
; #define PG8_WAIT_V(n) asm volatile("s_waitcnt vmcnt(" #n ")" ::: "memory")
; #define PG8_WAIT_L(n) asm volatile("s_waitcnt lgkmcnt(" #n ")" ::: "memory")
; #define PG8_BAR __builtin_amdgcn_s_barrier()
; #define PG8_SCHED __builtin_amdgcn_sched_barrier(0)
; template <class Epi, class Sched, bool ALIGN_EPI = false, bool SP2 = false>
; __device__ __forceinline__ void gemm_phase(PG8_LAS unsigned char* lds, const Gemm g, const Sched& S, const Epi& E, int tid_in) {
;     ...
;             PG8_WAIT_V(8); PG8_WAIT_L(0); PG8_BAR; PG8_MMA(0, 0, At, B0); PG8_MMA(0, 1, At, B1); PG8_BAR; PG8_SCHED;
;             PG8_LDA(At, 0, 1); PG8_STAGE(PG8_SB(0, 0), b2, voffB); PG8_STAGE(PG8_SB(0, 1), b2 + hstep, voffB); PG8_STAGE(PG8_SA(0, 0), a2, voffA);
;             PG8_WAIT_V(8); PG8_WAIT_L(0); PG8_BAR; PG8_MMA(1, 0, At, B0); PG8_MMA(1, 1, At, B1); PG8_BAR; PG8_SCHED;
;             PG8_LDB(B0, 1, 0); PG8_LDB(B1, 1, 1); PG8_SCHED; PG8_LDA(At, 1, 0); PG8_STAGE(PG8_SA(0, 1), a2 + hstep, voffA);
;             PG8_WAIT_V(8); PG8_WAIT_L(0); PG8_BAR; PG8_MMA(0, 0, At, B0); PG8_MMA(0, 1, At, B1); PG8_BAR; PG8_SCHED;
	s_setprio 1
	v_mfma_f32_16x16x32_bf16 v[60:63], v[130:133], v[162:165], v[60:63]
	v_mfma_f32_16x16x32_bf16 v[56:59], v[138:141], v[162:165], v[56:59]
	v_mfma_f32_16x16x32_bf16 v[52:55], v[130:133], v[188:191], v[52:55]
	v_mfma_f32_16x16x32_bf16 v[48:51], v[138:141], v[188:191], v[48:51]
	v_mfma_f32_16x16x32_bf16 v[36:39], v[130:133], v[216:219], v[36:39]
	v_mfma_f32_16x16x32_bf16 v[32:35], v[138:141], v[216:219], v[32:35]
	v_mfma_f32_16x16x32_bf16 v[20:23], v[130:133], v[224:227], v[20:23]
	v_mfma_f32_16x16x32_bf16 v[16:19], v[138:141], v[224:227], v[16:19]
	v_mfma_f32_16x16x32_bf16 v[60:63], v[134:137], v[184:187], v[60:63]
	v_mfma_f32_16x16x32_bf16 v[56:59], v[142:145], v[184:187], v[56:59]
	v_mfma_f32_16x16x32_bf16 v[52:55], v[134:137], v[192:195], v[52:55]
	v_mfma_f32_16x16x32_bf16 v[48:51], v[142:145], v[192:195], v[48:51]
	v_mfma_f32_16x16x32_bf16 v[36:39], v[134:137], v[220:223], v[36:39]
	v_mfma_f32_16x16x32_bf16 v[32:35], v[142:145], v[220:223], v[32:35]
	v_mfma_f32_16x16x32_bf16 v[20:23], v[134:137], v[228:231], v[20:23]
	v_mfma_f32_16x16x32_bf16 v[16:19], v[142:145], v[228:231], v[16:19]
	s_setprio 0
	s_setprio 1
	v_mfma_f32_16x16x32_bf16 v[44:47], v[146:149], v[162:165], v[44:47]
	v_mfma_f32_16x16x32_bf16 v[40:43], v[154:157], v[162:165], v[40:43]
	v_mfma_f32_16x16x32_bf16 v[28:31], v[146:149], v[188:191], v[28:31]
	v_mfma_f32_16x16x32_bf16 v[24:27], v[154:157], v[188:191], v[24:27]
	v_mfma_f32_16x16x32_bf16 v[12:15], v[146:149], v[216:219], v[12:15]
	v_mfma_f32_16x16x32_bf16 v[8:11], v[154:157], v[216:219], v[8:11]
	v_mfma_f32_16x16x32_bf16 v[4:7], v[146:149], v[224:227], v[4:7]
	v_mfma_f32_16x16x32_bf16 v[0:3], v[154:157], v[224:227], v[0:3]
	v_mfma_f32_16x16x32_bf16 v[44:47], v[150:153], v[184:187], v[44:47]
	v_mfma_f32_16x16x32_bf16 v[40:43], v[158:161], v[184:187], v[40:43]
	v_mfma_f32_16x16x32_bf16 v[28:31], v[150:153], v[192:195], v[28:31]
	v_mfma_f32_16x16x32_bf16 v[24:27], v[158:161], v[192:195], v[24:27]
	v_mfma_f32_16x16x32_bf16 v[12:15], v[150:153], v[220:223], v[12:15]
	v_mfma_f32_16x16x32_bf16 v[8:11], v[158:161], v[220:223], v[8:11]
	v_mfma_f32_16x16x32_bf16 v[4:7], v[150:153], v[228:231], v[4:7]
	v_mfma_f32_16x16x32_bf16 v[0:3], v[158:161], v[228:231], v[0:3]
	s_setprio 0
	s_barrier
	s_add_i32 s62, 0, 0x18000
	v_add_u32_e32 v96, s62, v203
	s_add_i32 s63, 0, 0x1c000
	ds_read_b128 v[130:133], v96
	ds_read_b128 v[134:137], v96 offset:1024
	ds_read_b128 v[138:141], v96 offset:2048
	ds_read_b128 v[142:145], v96 offset:3072
	v_add_u32_e32 v96, s63, v203
	ds_read_b128 v[146:149], v96
	ds_read_b128 v[150:153], v96 offset:1024
	ds_read_b128 v[154:157], v96 offset:2048
	ds_read_b128 v[158:161], v96 offset:3072
	s_add_u32 s44, s44, 0x80000
	s_addc_u32 s45, s45, 0
	s_mov_b32 m0, s65
	v_lshl_add_u64 v[234:235], s[44:45], 0, v[178:179]
	ds_read_b128 v[162:165], v215 offset:32768
	ds_read_b128 v[184:187], v215 offset:33792
	ds_read_b128 v[188:191], v215 offset:34816
	ds_read_b128 v[192:195], v215 offset:35840
	ds_read_b128 v[216:219], v215 offset:36864
	ds_read_b128 v[220:223], v215 offset:37888
	ds_read_b128 v[224:227], v215 offset:38912
	ds_read_b128 v[228:231], v215 offset:39936
	global_load_lds_dwordx4 v[234:235], off
	v_lshl_add_u64 v[234:235], s[44:45], 0, v[174:175]
	s_mov_b32 m0, s66
	s_nop 0
	global_load_lds_dwordx4 v[234:235], off
	s_waitcnt vmcnt(8)
	s_waitcnt lgkmcnt(0)
	s_barrier
	s_setprio 1
	v_mfma_f32_16x16x32_bf16 v[126:129], v[130:133], v[162:165], v[126:129]
	v_mfma_f32_16x16x32_bf16 v[122:125], v[138:141], v[162:165], v[122:125]
	v_mfma_f32_16x16x32_bf16 v[118:121], v[130:133], v[188:191], v[118:121]
	v_mfma_f32_16x16x32_bf16 v[114:117], v[138:141], v[188:191], v[114:117]
	v_mfma_f32_16x16x32_bf16 v[102:105], v[130:133], v[216:219], v[102:105]
	v_mfma_f32_16x16x32_bf16 v[98:101], v[138:141], v[216:219], v[98:101]
	v_mfma_f32_16x16x32_bf16 v[84:87], v[130:133], v[224:227], v[84:87]
	v_mfma_f32_16x16x32_bf16 v[80:83], v[138:141], v[224:227], v[80:83]
	v_mfma_f32_16x16x32_bf16 v[126:129], v[134:137], v[184:187], v[126:129]
	v_mfma_f32_16x16x32_bf16 v[122:125], v[142:145], v[184:187], v[122:125]
	v_mfma_f32_16x16x32_bf16 v[118:121], v[134:137], v[192:195], v[118:121]
	v_mfma_f32_16x16x32_bf16 v[114:117], v[142:145], v[192:195], v[114:117]
	v_mfma_f32_16x16x32_bf16 v[102:105], v[134:137], v[220:223], v[102:105]
	v_mfma_f32_16x16x32_bf16 v[98:101], v[142:145], v[220:223], v[98:101]
	v_mfma_f32_16x16x32_bf16 v[84:87], v[134:137], v[228:231], v[84:87]
	v_mfma_f32_16x16x32_bf16 v[80:83], v[142:145], v[228:231], v[80:83]
	s_setprio 0
	s_setprio 1
	v_mfma_f32_16x16x32_bf16 v[110:113], v[146:149], v[162:165], v[110:113]
	v_mfma_f32_16x16x32_bf16 v[106:109], v[154:157], v[162:165], v[106:109]
	v_mfma_f32_16x16x32_bf16 v[92:95], v[146:149], v[188:191], v[92:95]
	v_mfma_f32_16x16x32_bf16 v[88:91], v[154:157], v[188:191], v[88:91]
	v_mfma_f32_16x16x32_bf16 v[76:79], v[146:149], v[216:219], v[76:79]
	v_mfma_f32_16x16x32_bf16 v[72:75], v[154:157], v[216:219], v[72:75]
	v_mfma_f32_16x16x32_bf16 v[68:71], v[146:149], v[224:227], v[68:71]
	v_mfma_f32_16x16x32_bf16 v[64:67], v[154:157], v[224:227], v[64:67]
	v_mfma_f32_16x16x32_bf16 v[110:113], v[150:153], v[184:187], v[110:113]
	v_mfma_f32_16x16x32_bf16 v[106:109], v[158:161], v[184:187], v[106:109]
	v_mfma_f32_16x16x32_bf16 v[92:95], v[150:153], v[192:195], v[92:95]
	v_mfma_f32_16x16x32_bf16 v[88:91], v[158:161], v[192:195], v[88:91]
	v_mfma_f32_16x16x32_bf16 v[76:79], v[150:153], v[220:223], v[76:79]
	v_mfma_f32_16x16x32_bf16 v[72:75], v[158:161], v[220:223], v[72:75]
	v_mfma_f32_16x16x32_bf16 v[68:71], v[150:153], v[228:231], v[68:71]
	v_mfma_f32_16x16x32_bf16 v[64:67], v[158:161], v[228:231], v[64:67]
	s_setprio 0
	s_barrier
; #define PG8_STAGE(bufoff, gbase, voff) do { _Pragma("unroll") for (int _i = 0; _i < 2; ++_i) \
;         __builtin_amdgcn_global_load_lds((const unsigned*)((const char*)(gbase) + (voff)[_i]), (PG8_LAS unsigned*)(lds + (bufoff) + ldsw + _i * 8192), 16, 0, 0); } while (0)
; #define PG8_LDA(dst, b, h) do { _Pragma("unroll") for (int m = 0; m < 4; ++m) _Pragma("unroll") for (int k = 0; k < 2; ++k) dst[m][k] = *(const PG8_LAS bf16x8*)(lds + PG8_SA(b, h) + aoff + m * 2048 + k * 1024); } while (0)
; #define PG8_MMA(ai, bj, At, Bt) do { __builtin_amdgcn_s_setprio(1); _Pragma("unroll") for (int m = 0; m < 4; ++m) _Pragma("unroll") for (int n = 0; n < 2; ++n) _Pragma("unroll") for (int k = 0; k < 2; ++k) \
;         acc[ai][bj][m][n] = __builtin_amdgcn_mfma_f32_16x16x32_bf16(Bt[n][k], At[m][k], acc[ai][bj][m][n], 0, 0, 0); __builtin_amdgcn_s_setprio(0); } while (0)
; #define PG8_WAIT_V(n) asm volatile("s_waitcnt vmcnt(" #n ")" ::: "memory")
; #define PG8_WAIT_L(n) asm volatile("s_waitcnt lgkmcnt(" #n ")" ::: "memory")
; #define PG8_BAR __builtin_amdgcn_s_barrier()
; #define PG8_SCHED __builtin_amdgcn_sched_barrier(0)
; template <class Epi, class Sched, bool ALIGN_EPI = false, bool SP2 = false>
; __device__ __forceinline__ void gemm_phase(PG8_LAS unsigned char* lds, const Gemm g, const Sched& S, const Epi& E, int tid_in) {
;     ...
;             PG8_LDA(At, 1, 1); PG8_STAGE(PG8_SB(1, 0), b3, voffB); PG8_STAGE(PG8_SB(1, 1), b3 + hstep, voffB); PG8_STAGE(PG8_SA(1, 0), a3, voffA);
;             PG8_WAIT_V(8); PG8_WAIT_L(0); PG8_BAR; PG8_MMA(1, 0, At, B0); PG8_MMA(1, 1, At, B1); PG8_BAR; PG8_SCHED;
;     ...
;         if constexpr (ALIGN_EPI) { if (wr == 0) PG8_BAR; }
	s_add_i32 s44, s62, s64
	v_lshl_add_u64 v[196:197], v[196:197], 0, s[88:89]
	s_mov_b32 m0, s44
	ds_read_b128 v[162:165], v215 offset:49152
	ds_read_b128 v[184:187], v215 offset:50176
	ds_read_b128 v[188:191], v215 offset:51200
	ds_read_b128 v[192:195], v215 offset:52224
	ds_read_b128 v[216:219], v215 offset:53248
	ds_read_b128 v[220:223], v215 offset:54272
	ds_read_b128 v[224:227], v215 offset:55296
	ds_read_b128 v[228:231], v215 offset:56320
	global_load_lds_dwordx4 v[196:197], off
	s_add_i32 m0, s44, 0x2000
	s_add_u32 s42, s42, 0x80080
	v_lshl_add_u64 v[196:197], v[198:199], 0, s[88:89]
	s_addc_u32 s43, s43, 0
	s_add_i32 s44, s63, s64
	global_load_lds_dwordx4 v[196:197], off
	v_lshl_add_u64 v[196:197], s[42:43], 0, v[176:177]
	s_mov_b32 m0, s44
	s_nop 0
	global_load_lds_dwordx4 v[196:197], off
	v_lshl_add_u64 v[196:197], s[42:43], 0, v[172:173]
	s_add_i32 m0, s44, 0x2000
	s_nop 0
	global_load_lds_dwordx4 v[196:197], off
	v_lshl_add_u64 v[196:197], v[200:201], 0, s[88:89]
	s_mov_b32 m0, s67
	s_nop 0
	global_load_lds_dwordx4 v[196:197], off
	v_lshl_add_u64 v[196:197], v[232:233], 0, s[88:89]
	s_mov_b32 m0, s71
	s_nop 0
	global_load_lds_dwordx4 v[196:197], off
	s_waitcnt vmcnt(8)
	s_waitcnt lgkmcnt(0)
	s_barrier
	s_setprio 1
	v_mfma_f32_16x16x32_bf16 v[60:63], v[130:133], v[162:165], v[60:63]
	v_mfma_f32_16x16x32_bf16 v[56:59], v[138:141], v[162:165], v[56:59]
	v_mfma_f32_16x16x32_bf16 v[52:55], v[130:133], v[188:191], v[52:55]
	v_mfma_f32_16x16x32_bf16 v[48:51], v[138:141], v[188:191], v[48:51]
	v_mfma_f32_16x16x32_bf16 v[36:39], v[130:133], v[216:219], v[36:39]
	v_mfma_f32_16x16x32_bf16 v[32:35], v[138:141], v[216:219], v[32:35]
	v_mfma_f32_16x16x32_bf16 v[20:23], v[130:133], v[224:227], v[20:23]
	v_mfma_f32_16x16x32_bf16 v[16:19], v[138:141], v[224:227], v[16:19]
	v_mfma_f32_16x16x32_bf16 v[60:63], v[134:137], v[184:187], v[60:63]
	v_mfma_f32_16x16x32_bf16 v[56:59], v[142:145], v[184:187], v[56:59]
	v_mfma_f32_16x16x32_bf16 v[52:55], v[134:137], v[192:195], v[52:55]
	v_mfma_f32_16x16x32_bf16 v[48:51], v[142:145], v[192:195], v[48:51]
	v_mfma_f32_16x16x32_bf16 v[36:39], v[134:137], v[220:223], v[36:39]
	v_mfma_f32_16x16x32_bf16 v[32:35], v[142:145], v[220:223], v[32:35]
	v_mfma_f32_16x16x32_bf16 v[20:23], v[134:137], v[228:231], v[20:23]
	v_mfma_f32_16x16x32_bf16 v[16:19], v[142:145], v[228:231], v[16:19]
	s_setprio 0
	s_setprio 1
	v_mfma_f32_16x16x32_bf16 v[44:47], v[146:149], v[162:165], v[44:47]
	v_mfma_f32_16x16x32_bf16 v[40:43], v[154:157], v[162:165], v[40:43]
	v_mfma_f32_16x16x32_bf16 v[28:31], v[146:149], v[188:191], v[28:31]
	v_mfma_f32_16x16x32_bf16 v[24:27], v[154:157], v[188:191], v[24:27]
	v_mfma_f32_16x16x32_bf16 v[12:15], v[146:149], v[216:219], v[12:15]
	v_mfma_f32_16x16x32_bf16 v[8:11], v[154:157], v[216:219], v[8:11]
	v_mfma_f32_16x16x32_bf16 v[4:7], v[146:149], v[224:227], v[4:7]
	v_mfma_f32_16x16x32_bf16 v[0:3], v[154:157], v[224:227], v[0:3]
	v_mfma_f32_16x16x32_bf16 v[44:47], v[150:153], v[184:187], v[44:47]
	v_mfma_f32_16x16x32_bf16 v[40:43], v[158:161], v[184:187], v[40:43]
	v_mfma_f32_16x16x32_bf16 v[28:31], v[150:153], v[192:195], v[28:31]
	v_mfma_f32_16x16x32_bf16 v[24:27], v[158:161], v[192:195], v[24:27]
	v_mfma_f32_16x16x32_bf16 v[12:15], v[150:153], v[220:223], v[12:15]
	v_mfma_f32_16x16x32_bf16 v[8:11], v[158:161], v[220:223], v[8:11]
	v_mfma_f32_16x16x32_bf16 v[4:7], v[150:153], v[228:231], v[4:7]
	v_mfma_f32_16x16x32_bf16 v[0:3], v[158:161], v[228:231], v[0:3]
	s_setprio 0
	s_barrier
	s_add_i32 s77, s77, 2
	s_add_u32 s40, s40, 0x100
	s_addc_u32 s41, s41, 0
	s_add_u32 s75, s75, 0x100
	s_addc_u32 s76, s76, 0
	s_cmp_gt_u32 s77, 29
	s_cbranch_scc0 .LBB0_455
	s_and_b64 vcc, exec, s[34:35]
	s_cbranch_vccz .LBB0_458
	s_barrier

; #define PG8_STAGE(bufoff, gbase, voff) do { _Pragma("unroll") for (int _i = 0; _i < 2; ++_i) \
;         __builtin_amdgcn_global_load_lds((const unsigned*)((const char*)(gbase) + (voff)[_i]), (PG8_LAS unsigned*)(lds + (bufoff) + ldsw + _i * 8192), 16, 0, 0); } while (0)
; #define PG8_LDA(dst, b, h) do { _Pragma("unroll") for (int m = 0; m < 4; ++m) _Pragma("unroll") for (int k = 0; k < 2; ++k) dst[m][k] = *(const PG8_LAS bf16x8*)(lds + PG8_SA(b, h) + aoff + m * 2048 + k * 1024); } while (0)
; #define PG8_LDB(dst, b, h) do { _Pragma("unroll") for (int n = 0; n < 2; ++n) _Pragma("unroll") for (int k = 0; k < 2; ++k) dst[n][k] = *(const PG8_LAS bf16x8*)(lds + PG8_SB(b, h) + boff + n * 2048 + k * 1024); } while (0)
; #define PG8_MMA(ai, bj, At, Bt) do { __builtin_amdgcn_s_setprio(1); _Pragma("unroll") for (int m = 0; m < 4; ++m) _Pragma("unroll") for (int n = 0; n < 2; ++n) _Pragma("unroll") for (int k = 0; k < 2; ++k) \
;         acc[ai][bj][m][n] = __builtin_amdgcn_mfma_f32_16x16x32_bf16(Bt[n][k], At[m][k], acc[ai][bj][m][n], 0, 0, 0); __builtin_amdgcn_s_setprio(0); } while (0)
; #define PG8_WAIT_V(n) asm volatile("s_waitcnt vmcnt(" #n ")" ::: "memory")
; #define PG8_BAR __builtin_amdgcn_s_barrier()
; template <class Epi, class Sched, bool ALIGN_EPI = false, bool SP2 = false>
; __device__ __forceinline__ void gemm_phase(PG8_LAS unsigned char* lds, const Gemm g, const Sched& S, const Epi& E, int tid_in) {
;     ...
;         for (int t = 0; t < nt; t += 2) {
;             const bool last = (t == nt - 2);
;             const char* a1 = cA + (size_t)(t + 1) * kstep;
;             const char* a2 = last ? nA : cA + (size_t)(t + 2) * kstep; const char* b2 = last ? nB : cB + (size_t)(t + 2) * kstep;
;             const char* a3 = a2 + kstep; const char* b3 = b2 + kstep;
;             if (last && has_next) S.a_ready(nxt);
;             if constexpr (SP2) {
;             PG8_LDB(B0, 0, 0); PG8_LDB(B1, 0, 1); PG8_SCHED; PG8_LDA(At, 0, 0); PG8_STAGE(PG8_SA(1, 1), a1 + hstep, voffA);
;             PG8_WAIT_V(8); PG8_WAIT_L(0); PG8_BAR; PG8_MMA(0, 0, At, B0); PG8_MMA(0, 1, At, B1); PG8_BAR; PG8_SCHED;
;             PG8_LDA(At, 0, 1); PG8_STAGE(PG8_SB(0, 0), b2, voffB); PG8_STAGE(PG8_SB(0, 1), b2 + hstep, voffB); PG8_STAGE(PG8_SA(0, 0), a2, voffA);
;             PG8_WAIT_V(8); PG8_WAIT_L(0); PG8_BAR; PG8_MMA(1, 0, At, B0); PG8_MMA(1, 1, At, B1); PG8_BAR; PG8_SCHED;
.LBB0_567:
	s_add_u32 s28, s26, 0xfff80080
	s_addc_u32 s29, s27, -1
	s_add_i32 s62, 0, 0x10000
	s_cmp_eq_u32 s66, 28
	s_cselect_b32 s31, s19, s29
	s_cselect_b32 s30, s47, s28
	v_add_u32_e32 v144, s62, v148
	s_cselect_b32 s29, s17, s65
	s_cselect_b32 s28, s52, s64
	s_add_i32 s67, 0, 0x14000
	ds_read_b128 v[140:143], v144
	ds_read_b128 v[152:155], v144 offset:1024
	ds_read_b128 v[156:159], v144 offset:2048
	ds_read_b128 v[160:163], v144 offset:3072
	v_add_u32_e32 v144, s67, v148
	ds_read_b128 v[172:175], v144
	ds_read_b128 v[176:179], v144 offset:1024
	ds_read_b128 v[180:183], v144 offset:2048
	ds_read_b128 v[184:187], v144 offset:3072
	v_lshl_add_u64 v[144:145], s[26:27], 0, v[136:137]
	s_add_i32 m0, s40, 0xc000
	ds_read_b128 v[188:191], v150
	ds_read_b128 v[192:195], v150 offset:1024
	ds_read_b128 v[196:199], v150 offset:2048
	ds_read_b128 v[204:207], v150 offset:3072
	ds_read_b128 v[208:211], v150 offset:4096
	ds_read_b128 v[212:215], v150 offset:5120
	ds_read_b128 v[216:219], v150 offset:6144
	ds_read_b128 v[220:223], v150 offset:7168
	global_load_lds_dwordx4 v[144:145], off
	v_lshl_add_u64 v[144:145], s[26:27], 0, v[138:139]
	s_add_i32 m0, s40, 0xe000
	s_nop 0
	global_load_lds_dwordx4 v[144:145], off
	s_waitcnt vmcnt(8)
	s_waitcnt lgkmcnt(0)
	s_barrier
	s_setprio 1
	v_mfma_f32_16x16x32_bf16 v[126:129], v[140:143], v[188:191], v[126:129]
	v_mfma_f32_16x16x32_bf16 v[122:125], v[156:159], v[188:191], v[122:125]
	v_mfma_f32_16x16x32_bf16 v[110:113], v[140:143], v[196:199], v[110:113]
	v_mfma_f32_16x16x32_bf16 v[106:109], v[156:159], v[196:199], v[106:109]
	v_mfma_f32_16x16x32_bf16 v[92:95], v[140:143], v[208:211], v[92:95]
	v_mfma_f32_16x16x32_bf16 v[88:91], v[156:159], v[208:211], v[88:91]
	v_mfma_f32_16x16x32_bf16 v[76:79], v[140:143], v[216:219], v[76:79]
	v_mfma_f32_16x16x32_bf16 v[72:75], v[156:159], v[216:219], v[72:75]
	v_mfma_f32_16x16x32_bf16 v[126:129], v[152:155], v[192:195], v[126:129]
	v_mfma_f32_16x16x32_bf16 v[122:125], v[160:163], v[192:195], v[122:125]
	v_mfma_f32_16x16x32_bf16 v[110:113], v[152:155], v[204:207], v[110:113]
	v_mfma_f32_16x16x32_bf16 v[106:109], v[160:163], v[204:207], v[106:109]
	v_mfma_f32_16x16x32_bf16 v[92:95], v[152:155], v[212:215], v[92:95]
	v_mfma_f32_16x16x32_bf16 v[88:91], v[160:163], v[212:215], v[88:91]
	v_mfma_f32_16x16x32_bf16 v[76:79], v[152:155], v[220:223], v[76:79]
	v_mfma_f32_16x16x32_bf16 v[72:75], v[160:163], v[220:223], v[72:75]
	s_setprio 0
	s_setprio 1
	v_mfma_f32_16x16x32_bf16 v[118:121], v[172:175], v[188:191], v[118:121]
	v_mfma_f32_16x16x32_bf16 v[114:117], v[180:183], v[188:191], v[114:117]
	v_mfma_f32_16x16x32_bf16 v[102:105], v[172:175], v[196:199], v[102:105]
	v_mfma_f32_16x16x32_bf16 v[98:101], v[180:183], v[196:199], v[98:101]
	v_mfma_f32_16x16x32_bf16 v[84:87], v[172:175], v[208:211], v[84:87]
	v_mfma_f32_16x16x32_bf16 v[80:83], v[180:183], v[208:211], v[80:83]
	v_mfma_f32_16x16x32_bf16 v[68:71], v[172:175], v[216:219], v[68:71]
	v_mfma_f32_16x16x32_bf16 v[64:67], v[180:183], v[216:219], v[64:67]
	v_mfma_f32_16x16x32_bf16 v[118:121], v[176:179], v[192:195], v[118:121]
	v_mfma_f32_16x16x32_bf16 v[114:117], v[184:187], v[192:195], v[114:117]
	v_mfma_f32_16x16x32_bf16 v[102:105], v[176:179], v[204:207], v[102:105]
	v_mfma_f32_16x16x32_bf16 v[98:101], v[184:187], v[204:207], v[98:101]
	v_mfma_f32_16x16x32_bf16 v[84:87], v[176:179], v[212:215], v[84:87]
	v_mfma_f32_16x16x32_bf16 v[80:83], v[184:187], v[212:215], v[80:83]
	v_mfma_f32_16x16x32_bf16 v[68:71], v[176:179], v[220:223], v[68:71]
	v_mfma_f32_16x16x32_bf16 v[64:67], v[184:187], v[220:223], v[64:67]
	s_setprio 0
	s_barrier
	s_add_i32 s62, s62, s39
	v_lshl_add_u64 v[144:145], s[28:29], 0, v[96:97]
	s_mov_b32 m0, s62
	ds_read_b128 v[188:191], v150 offset:16384
	ds_read_b128 v[192:195], v150 offset:17408
	ds_read_b128 v[196:199], v150 offset:18432
	ds_read_b128 v[204:207], v150 offset:19456
	ds_read_b128 v[208:211], v150 offset:20480
	ds_read_b128 v[212:215], v150 offset:21504
	ds_read_b128 v[216:219], v150 offset:22528
	ds_read_b128 v[220:223], v150 offset:23552
	global_load_lds_dwordx4 v[144:145], off
	s_add_i32 m0, s62, 0x2000
	s_add_u32 s62, s28, 0x80000
	v_lshl_add_u64 v[164:165], s[28:29], 0, v[134:135]
	s_addc_u32 s63, s29, 0
	s_add_i32 s67, s67, s39
	global_load_lds_dwordx4 v[164:165], off
	v_lshl_add_u64 v[200:201], s[62:63], 0, v[96:97]
	s_mov_b32 m0, s67
	v_lshl_add_u64 v[224:225], s[30:31], 0, v[132:133]
	global_load_lds_dwordx4 v[200:201], off
	v_lshl_add_u64 v[200:201], s[62:63], 0, v[134:135]
	s_add_i32 m0, s67, 0x2000
	s_nop 0
	global_load_lds_dwordx4 v[200:201], off
	v_lshl_add_u64 v[200:201], s[30:31], 0, v[130:131]
	s_mov_b32 m0, s40
	s_nop 0
	global_load_lds_dwordx4 v[200:201], off
	s_mov_b32 m0, s41
	s_nop 0
	global_load_lds_dwordx4 v[224:225], off
	s_waitcnt vmcnt(8)
	s_waitcnt lgkmcnt(0)
	s_barrier
; #define PG8_STAGE(bufoff, gbase, voff) do { _Pragma("unroll") for (int _i = 0; _i < 2; ++_i) \
;         __builtin_amdgcn_global_load_lds((const unsigned*)((const char*)(gbase) + (voff)[_i]), (PG8_LAS unsigned*)(lds + (bufoff) + ldsw + _i * 8192), 16, 0, 0); } while (0)
; #define PG8_LDA(dst, b, h) do { _Pragma("unroll") for (int m = 0; m < 4; ++m) _Pragma("unroll") for (int k = 0; k < 2; ++k) dst[m][k] = *(const PG8_LAS bf16x8*)(lds + PG8_SA(b, h) + aoff + m * 2048 + k * 1024); } while (0)
; #define PG8_LDB(dst, b, h) do { _Pragma("unroll") for (int n = 0; n < 2; ++n) _Pragma("unroll") for (int k = 0; k < 2; ++k) dst[n][k] = *(const PG8_LAS bf16x8*)(lds + PG8_SB(b, h) + boff + n * 2048 + k * 1024); } while (0)
; #define PG8_MMA(ai, bj, At, Bt) do { __builtin_amdgcn_s_setprio(1); _Pragma("unroll") for (int m = 0; m < 4; ++m) _Pragma("unroll") for (int n = 0; n < 2; ++n) _Pragma("unroll") for (int k = 0; k < 2; ++k) \
;         acc[ai][bj][m][n] = __builtin_amdgcn_mfma_f32_16x16x32_bf16(Bt[n][k], At[m][k], acc[ai][bj][m][n], 0, 0, 0); __builtin_amdgcn_s_setprio(0); } while (0)
; #define PG8_WAIT_V(n) asm volatile("s_waitcnt vmcnt(" #n ")" ::: "memory")
; #define PG8_WAIT_L(n) asm volatile("s_waitcnt lgkmcnt(" #n ")" ::: "memory")
; #define PG8_BAR __builtin_amdgcn_s_barrier()
; #define PG8_SCHED __builtin_amdgcn_sched_barrier(0)
; template <class Epi, class Sched, bool ALIGN_EPI = false, bool SP2 = false>
; __device__ __forceinline__ void gemm_phase(PG8_LAS unsigned char* lds, const Gemm g, const Sched& S, const Epi& E, int tid_in) {
;     ...
;             PG8_WAIT_V(8); PG8_WAIT_L(0); PG8_BAR; PG8_MMA(1, 0, At, B0); PG8_MMA(1, 1, At, B1); PG8_BAR; PG8_SCHED;
;             PG8_LDB(B0, 1, 0); PG8_LDB(B1, 1, 1); PG8_SCHED; PG8_LDA(At, 1, 0); PG8_STAGE(PG8_SA(0, 1), a2 + hstep, voffA);
;             PG8_WAIT_V(8); PG8_WAIT_L(0); PG8_BAR; PG8_MMA(0, 0, At, B0); PG8_MMA(0, 1, At, B1); PG8_BAR; PG8_SCHED;
	s_setprio 1
	v_mfma_f32_16x16x32_bf16 v[60:63], v[140:143], v[188:191], v[60:63]
	v_mfma_f32_16x16x32_bf16 v[56:59], v[156:159], v[188:191], v[56:59]
	v_mfma_f32_16x16x32_bf16 v[44:47], v[140:143], v[196:199], v[44:47]
	v_mfma_f32_16x16x32_bf16 v[40:43], v[156:159], v[196:199], v[40:43]
	v_mfma_f32_16x16x32_bf16 v[28:31], v[140:143], v[208:211], v[28:31]
	v_mfma_f32_16x16x32_bf16 v[24:27], v[156:159], v[208:211], v[24:27]
	v_mfma_f32_16x16x32_bf16 v[12:15], v[140:143], v[216:219], v[12:15]
	v_mfma_f32_16x16x32_bf16 v[8:11], v[156:159], v[216:219], v[8:11]
	v_mfma_f32_16x16x32_bf16 v[60:63], v[152:155], v[192:195], v[60:63]
	v_mfma_f32_16x16x32_bf16 v[56:59], v[160:163], v[192:195], v[56:59]
	v_mfma_f32_16x16x32_bf16 v[44:47], v[152:155], v[204:207], v[44:47]
	v_mfma_f32_16x16x32_bf16 v[40:43], v[160:163], v[204:207], v[40:43]
	v_mfma_f32_16x16x32_bf16 v[28:31], v[152:155], v[212:215], v[28:31]
	v_mfma_f32_16x16x32_bf16 v[24:27], v[160:163], v[212:215], v[24:27]
	v_mfma_f32_16x16x32_bf16 v[12:15], v[152:155], v[220:223], v[12:15]
	v_mfma_f32_16x16x32_bf16 v[8:11], v[160:163], v[220:223], v[8:11]
	s_setprio 0
	s_setprio 1
	v_mfma_f32_16x16x32_bf16 v[52:55], v[172:175], v[188:191], v[52:55]
	v_mfma_f32_16x16x32_bf16 v[48:51], v[180:183], v[188:191], v[48:51]
	v_mfma_f32_16x16x32_bf16 v[36:39], v[172:175], v[196:199], v[36:39]
	v_mfma_f32_16x16x32_bf16 v[32:35], v[180:183], v[196:199], v[32:35]
	v_mfma_f32_16x16x32_bf16 v[20:23], v[172:175], v[208:211], v[20:23]
	v_mfma_f32_16x16x32_bf16 v[16:19], v[180:183], v[208:211], v[16:19]
	v_mfma_f32_16x16x32_bf16 v[4:7], v[172:175], v[216:219], v[4:7]
	v_mfma_f32_16x16x32_bf16 v[0:3], v[180:183], v[216:219], v[0:3]
	v_mfma_f32_16x16x32_bf16 v[52:55], v[176:179], v[192:195], v[52:55]
	v_mfma_f32_16x16x32_bf16 v[48:51], v[184:187], v[192:195], v[48:51]
	v_mfma_f32_16x16x32_bf16 v[36:39], v[176:179], v[204:207], v[36:39]
	v_mfma_f32_16x16x32_bf16 v[32:35], v[184:187], v[204:207], v[32:35]
	v_mfma_f32_16x16x32_bf16 v[20:23], v[176:179], v[212:215], v[20:23]
	v_mfma_f32_16x16x32_bf16 v[16:19], v[184:187], v[212:215], v[16:19]
	v_mfma_f32_16x16x32_bf16 v[4:7], v[176:179], v[220:223], v[4:7]
	v_mfma_f32_16x16x32_bf16 v[0:3], v[184:187], v[220:223], v[0:3]
	s_setprio 0
	s_barrier
	s_add_i32 s62, 0, 0x18000
	v_add_u32_e32 v151, s62, v148
	s_add_i32 s63, 0, 0x1c000
	ds_read_b128 v[140:143], v151
	ds_read_b128 v[152:155], v151 offset:1024
	ds_read_b128 v[156:159], v151 offset:2048
	ds_read_b128 v[160:163], v151 offset:3072
	v_add_u32_e32 v151, s63, v148
	ds_read_b128 v[172:175], v151
	ds_read_b128 v[176:179], v151 offset:1024
	ds_read_b128 v[180:183], v151 offset:2048
	ds_read_b128 v[184:187], v151 offset:3072
	s_add_u32 s30, s30, 0x80000
	s_addc_u32 s31, s31, 0
	s_mov_b32 m0, s42
	v_lshl_add_u64 v[226:227], s[30:31], 0, v[130:131]
	ds_read_b128 v[188:191], v150 offset:32768
	ds_read_b128 v[192:195], v150 offset:33792
	ds_read_b128 v[196:199], v150 offset:34816
	ds_read_b128 v[204:207], v150 offset:35840
	ds_read_b128 v[208:211], v150 offset:36864
	ds_read_b128 v[212:215], v150 offset:37888
	ds_read_b128 v[216:219], v150 offset:38912
	ds_read_b128 v[220:223], v150 offset:39936
	global_load_lds_dwordx4 v[226:227], off
	v_lshl_add_u64 v[226:227], s[30:31], 0, v[132:133]
	s_mov_b32 m0, s43
	s_nop 0
	global_load_lds_dwordx4 v[226:227], off
	s_waitcnt vmcnt(8)
	s_waitcnt lgkmcnt(0)
	s_barrier
	s_setprio 1
	v_mfma_f32_16x16x32_bf16 v[126:129], v[140:143], v[188:191], v[126:129]
	v_mfma_f32_16x16x32_bf16 v[122:125], v[156:159], v[188:191], v[122:125]
	v_mfma_f32_16x16x32_bf16 v[110:113], v[140:143], v[196:199], v[110:113]
	v_mfma_f32_16x16x32_bf16 v[106:109], v[156:159], v[196:199], v[106:109]
	v_mfma_f32_16x16x32_bf16 v[92:95], v[140:143], v[208:211], v[92:95]
	v_mfma_f32_16x16x32_bf16 v[88:91], v[156:159], v[208:211], v[88:91]
	v_mfma_f32_16x16x32_bf16 v[76:79], v[140:143], v[216:219], v[76:79]
	v_mfma_f32_16x16x32_bf16 v[72:75], v[156:159], v[216:219], v[72:75]
	v_mfma_f32_16x16x32_bf16 v[126:129], v[152:155], v[192:195], v[126:129]
	v_mfma_f32_16x16x32_bf16 v[122:125], v[160:163], v[192:195], v[122:125]
	v_mfma_f32_16x16x32_bf16 v[110:113], v[152:155], v[204:207], v[110:113]
	v_mfma_f32_16x16x32_bf16 v[106:109], v[160:163], v[204:207], v[106:109]
	v_mfma_f32_16x16x32_bf16 v[92:95], v[152:155], v[212:215], v[92:95]
	v_mfma_f32_16x16x32_bf16 v[88:91], v[160:163], v[212:215], v[88:91]
	v_mfma_f32_16x16x32_bf16 v[76:79], v[152:155], v[220:223], v[76:79]
	v_mfma_f32_16x16x32_bf16 v[72:75], v[160:163], v[220:223], v[72:75]
	s_setprio 0
	s_setprio 1
	v_mfma_f32_16x16x32_bf16 v[118:121], v[172:175], v[188:191], v[118:121]
	v_mfma_f32_16x16x32_bf16 v[114:117], v[180:183], v[188:191], v[114:117]
	v_mfma_f32_16x16x32_bf16 v[102:105], v[172:175], v[196:199], v[102:105]
	v_mfma_f32_16x16x32_bf16 v[98:101], v[180:183], v[196:199], v[98:101]
	v_mfma_f32_16x16x32_bf16 v[84:87], v[172:175], v[208:211], v[84:87]
	v_mfma_f32_16x16x32_bf16 v[80:83], v[180:183], v[208:211], v[80:83]
	v_mfma_f32_16x16x32_bf16 v[68:71], v[172:175], v[216:219], v[68:71]
	v_mfma_f32_16x16x32_bf16 v[64:67], v[180:183], v[216:219], v[64:67]
	v_mfma_f32_16x16x32_bf16 v[118:121], v[176:179], v[192:195], v[118:121]
	v_mfma_f32_16x16x32_bf16 v[114:117], v[184:187], v[192:195], v[114:117]
	v_mfma_f32_16x16x32_bf16 v[102:105], v[176:179], v[204:207], v[102:105]
	v_mfma_f32_16x16x32_bf16 v[98:101], v[184:187], v[204:207], v[98:101]
	v_mfma_f32_16x16x32_bf16 v[84:87], v[176:179], v[212:215], v[84:87]
	v_mfma_f32_16x16x32_bf16 v[80:83], v[184:187], v[212:215], v[80:83]
	v_mfma_f32_16x16x32_bf16 v[68:71], v[176:179], v[220:223], v[68:71]
	v_mfma_f32_16x16x32_bf16 v[64:67], v[184:187], v[220:223], v[64:67]
	s_setprio 0
	s_barrier
; #define PG8_STAGE(bufoff, gbase, voff) do { _Pragma("unroll") for (int _i = 0; _i < 2; ++_i) \
;         __builtin_amdgcn_global_load_lds((const unsigned*)((const char*)(gbase) + (voff)[_i]), (PG8_LAS unsigned*)(lds + (bufoff) + ldsw + _i * 8192), 16, 0, 0); } while (0)
; #define PG8_LDA(dst, b, h) do { _Pragma("unroll") for (int m = 0; m < 4; ++m) _Pragma("unroll") for (int k = 0; k < 2; ++k) dst[m][k] = *(const PG8_LAS bf16x8*)(lds + PG8_SA(b, h) + aoff + m * 2048 + k * 1024); } while (0)
; #define PG8_MMA(ai, bj, At, Bt) do { __builtin_amdgcn_s_setprio(1); _Pragma("unroll") for (int m = 0; m < 4; ++m) _Pragma("unroll") for (int n = 0; n < 2; ++n) _Pragma("unroll") for (int k = 0; k < 2; ++k) \
;         acc[ai][bj][m][n] = __builtin_amdgcn_mfma_f32_16x16x32_bf16(Bt[n][k], At[m][k], acc[ai][bj][m][n], 0, 0, 0); __builtin_amdgcn_s_setprio(0); } while (0)
; #define PG8_WAIT_V(n) asm volatile("s_waitcnt vmcnt(" #n ")" ::: "memory")
; #define PG8_WAIT_L(n) asm volatile("s_waitcnt lgkmcnt(" #n ")" ::: "memory")
; #define PG8_BAR __builtin_amdgcn_s_barrier()
; #define PG8_SCHED __builtin_amdgcn_sched_barrier(0)
; template <class Epi, class Sched, bool ALIGN_EPI = false, bool SP2 = false>
; __device__ __forceinline__ void gemm_phase(PG8_LAS unsigned char* lds, const Gemm g, const Sched& S, const Epi& E, int tid_in) {
;     ...
;             PG8_LDA(At, 1, 1); PG8_STAGE(PG8_SB(1, 0), b3, voffB); PG8_STAGE(PG8_SB(1, 1), b3 + hstep, voffB); PG8_STAGE(PG8_SA(1, 0), a3, voffA);
;             PG8_WAIT_V(8); PG8_WAIT_L(0); PG8_BAR; PG8_MMA(1, 0, At, B0); PG8_MMA(1, 1, At, B1); PG8_BAR; PG8_SCHED;
;     ...
;         if constexpr (ALIGN_EPI) { if (wr == 0) PG8_BAR; }
	s_add_i32 s30, s62, s39
	v_lshl_add_u64 v[144:145], v[144:145], 0, s[88:89]
	s_mov_b32 m0, s30
	ds_read_b128 v[188:191], v150 offset:49152
	ds_read_b128 v[192:195], v150 offset:50176
	ds_read_b128 v[196:199], v150 offset:51200
	ds_read_b128 v[204:207], v150 offset:52224
	ds_read_b128 v[208:211], v150 offset:53248
	ds_read_b128 v[212:215], v150 offset:54272
	ds_read_b128 v[216:219], v150 offset:55296
	ds_read_b128 v[220:223], v150 offset:56320
	global_load_lds_dwordx4 v[144:145], off
	s_add_i32 m0, s30, 0x2000
	s_add_u32 s28, s28, 0x80080
	v_lshl_add_u64 v[144:145], v[164:165], 0, s[88:89]
	s_addc_u32 s29, s29, 0
	s_add_i32 s30, s63, s39
	global_load_lds_dwordx4 v[144:145], off
	v_lshl_add_u64 v[144:145], s[28:29], 0, v[96:97]
	s_mov_b32 m0, s30
	s_nop 0
	global_load_lds_dwordx4 v[144:145], off
	v_lshl_add_u64 v[144:145], s[28:29], 0, v[134:135]
	s_add_i32 m0, s30, 0x2000
	s_nop 0
	global_load_lds_dwordx4 v[144:145], off
	v_lshl_add_u64 v[144:145], v[200:201], 0, s[88:89]
	s_mov_b32 m0, s44
	s_nop 0
	global_load_lds_dwordx4 v[144:145], off
	v_lshl_add_u64 v[144:145], v[224:225], 0, s[88:89]
	s_mov_b32 m0, s45
	s_nop 0
	global_load_lds_dwordx4 v[144:145], off
	s_waitcnt vmcnt(8)
	s_waitcnt lgkmcnt(0)
	s_barrier
	s_setprio 1
	v_mfma_f32_16x16x32_bf16 v[60:63], v[140:143], v[188:191], v[60:63]
	v_mfma_f32_16x16x32_bf16 v[56:59], v[156:159], v[188:191], v[56:59]
	v_mfma_f32_16x16x32_bf16 v[44:47], v[140:143], v[196:199], v[44:47]
	v_mfma_f32_16x16x32_bf16 v[40:43], v[156:159], v[196:199], v[40:43]
	v_mfma_f32_16x16x32_bf16 v[28:31], v[140:143], v[208:211], v[28:31]
	v_mfma_f32_16x16x32_bf16 v[24:27], v[156:159], v[208:211], v[24:27]
	v_mfma_f32_16x16x32_bf16 v[12:15], v[140:143], v[216:219], v[12:15]
	v_mfma_f32_16x16x32_bf16 v[8:11], v[156:159], v[216:219], v[8:11]
	v_mfma_f32_16x16x32_bf16 v[60:63], v[152:155], v[192:195], v[60:63]
	v_mfma_f32_16x16x32_bf16 v[56:59], v[160:163], v[192:195], v[56:59]
	v_mfma_f32_16x16x32_bf16 v[44:47], v[152:155], v[204:207], v[44:47]
	v_mfma_f32_16x16x32_bf16 v[40:43], v[160:163], v[204:207], v[40:43]
	v_mfma_f32_16x16x32_bf16 v[28:31], v[152:155], v[212:215], v[28:31]
	v_mfma_f32_16x16x32_bf16 v[24:27], v[160:163], v[212:215], v[24:27]
	v_mfma_f32_16x16x32_bf16 v[12:15], v[152:155], v[220:223], v[12:15]
	v_mfma_f32_16x16x32_bf16 v[8:11], v[160:163], v[220:223], v[8:11]
	s_setprio 0
	s_setprio 1
	v_mfma_f32_16x16x32_bf16 v[52:55], v[172:175], v[188:191], v[52:55]
	v_mfma_f32_16x16x32_bf16 v[48:51], v[180:183], v[188:191], v[48:51]
	v_mfma_f32_16x16x32_bf16 v[36:39], v[172:175], v[196:199], v[36:39]
	v_mfma_f32_16x16x32_bf16 v[32:35], v[180:183], v[196:199], v[32:35]
	v_mfma_f32_16x16x32_bf16 v[20:23], v[172:175], v[208:211], v[20:23]
	v_mfma_f32_16x16x32_bf16 v[16:19], v[180:183], v[208:211], v[16:19]
	v_mfma_f32_16x16x32_bf16 v[4:7], v[172:175], v[216:219], v[4:7]
	v_mfma_f32_16x16x32_bf16 v[0:3], v[180:183], v[216:219], v[0:3]
	v_mfma_f32_16x16x32_bf16 v[52:55], v[176:179], v[192:195], v[52:55]
	v_mfma_f32_16x16x32_bf16 v[48:51], v[184:187], v[192:195], v[48:51]
	v_mfma_f32_16x16x32_bf16 v[36:39], v[176:179], v[204:207], v[36:39]
	v_mfma_f32_16x16x32_bf16 v[32:35], v[184:187], v[204:207], v[32:35]
	v_mfma_f32_16x16x32_bf16 v[20:23], v[176:179], v[212:215], v[20:23]
	v_mfma_f32_16x16x32_bf16 v[16:19], v[184:187], v[212:215], v[16:19]
	v_mfma_f32_16x16x32_bf16 v[4:7], v[176:179], v[220:223], v[4:7]
	v_mfma_f32_16x16x32_bf16 v[0:3], v[184:187], v[220:223], v[0:3]
	s_setprio 0
	s_barrier
	s_add_i32 s66, s66, 2
	s_add_u32 s26, s26, 0x100
	s_addc_u32 s27, s27, 0
	s_add_u32 s64, s64, 0x100
	s_addc_u32 s65, s65, 0
	s_cmp_gt_u32 s66, 29
	s_cbranch_scc0 .LBB0_567
	s_and_b64 vcc, exec, s[14:15]
	s_cbranch_vccz .LBB0_570
	s_barrier

; #define PG8_STAGE(bufoff, gbase, voff) do { _Pragma("unroll") for (int _i = 0; _i < 2; ++_i) \
;         __builtin_amdgcn_global_load_lds((const unsigned*)((const char*)(gbase) + (voff)[_i]), (PG8_LAS unsigned*)(lds + (bufoff) + ldsw + _i * 8192), 16, 0, 0); } while (0)
; #define PG8_LDA(dst, b, h) do { _Pragma("unroll") for (int m = 0; m < 4; ++m) _Pragma("unroll") for (int k = 0; k < 2; ++k) dst[m][k] = *(const PG8_LAS bf16x8*)(lds + PG8_SA(b, h) + aoff + m * 2048 + k * 1024); } while (0)
; #define PG8_LDB(dst, b, h) do { _Pragma("unroll") for (int n = 0; n < 2; ++n) _Pragma("unroll") for (int k = 0; k < 2; ++k) dst[n][k] = *(const PG8_LAS bf16x8*)(lds + PG8_SB(b, h) + boff + n * 2048 + k * 1024); } while (0)
; #define PG8_MMA(ai, bj, At, Bt) do { __builtin_amdgcn_s_setprio(1); _Pragma("unroll") for (int m = 0; m < 4; ++m) _Pragma("unroll") for (int n = 0; n < 2; ++n) _Pragma("unroll") for (int k = 0; k < 2; ++k) \
;         acc[ai][bj][m][n] = __builtin_amdgcn_mfma_f32_16x16x32_bf16(Bt[n][k], At[m][k], acc[ai][bj][m][n], 0, 0, 0); __builtin_amdgcn_s_setprio(0); } while (0)
; #define PG8_WAIT_V(n) asm volatile("s_waitcnt vmcnt(" #n ")" ::: "memory")
; #define PG8_BAR __builtin_amdgcn_s_barrier()
; template <class Epi, class Sched, bool ALIGN_EPI = false, bool SP2 = false>
; __device__ __forceinline__ void gemm_phase(PG8_LAS unsigned char* lds, const Gemm g, const Sched& S, const Epi& E, int tid_in) {
;     ...
;         for (int t = 0; t < nt; t += 2) {
;             const bool last = (t == nt - 2);
;             const char* a1 = cA + (size_t)(t + 1) * kstep;
;             const char* a2 = last ? nA : cA + (size_t)(t + 2) * kstep; const char* b2 = last ? nB : cB + (size_t)(t + 2) * kstep;
;             const char* a3 = a2 + kstep; const char* b3 = b2 + kstep;
;             if (last && has_next) S.a_ready(nxt);
;             if constexpr (SP2) {
;             PG8_LDB(B0, 0, 0); PG8_LDB(B1, 0, 1); PG8_SCHED; PG8_LDA(At, 0, 0); PG8_STAGE(PG8_SA(1, 1), a1 + hstep, voffA);
;             PG8_WAIT_V(8); PG8_WAIT_L(0); PG8_BAR; PG8_MMA(0, 0, At, B0); PG8_MMA(0, 1, At, B1); PG8_BAR; PG8_SCHED;
;             PG8_LDA(At, 0, 1); PG8_STAGE(PG8_SB(0, 0), b2, voffB); PG8_STAGE(PG8_SB(0, 1), b2 + hstep, voffB); PG8_STAGE(PG8_SA(0, 0), a2, voffA);
;             PG8_WAIT_V(8); PG8_WAIT_L(0); PG8_BAR; PG8_MMA(1, 0, At, B0); PG8_MMA(1, 1, At, B1); PG8_BAR; PG8_SCHED;
.LBB0_632:
	s_add_u32 s30, s28, 0xfff80080
	s_addc_u32 s31, s29, -1
	s_add_i32 s62, 0, 0x10000
	s_cmp_eq_u32 s72, 28
	s_cselect_b32 s35, s21, s31
	s_cselect_b32 s34, s67, s30
	v_add_u32_e32 v148, s62, v133
	s_cselect_b32 s31, s19, s71
	s_cselect_b32 s30, s69, s70
	s_add_i32 s73, 0, 0x14000
	ds_read_b128 v[144:147], v148
	ds_read_b128 v[158:161], v148 offset:1024
	ds_read_b128 v[162:165], v148 offset:2048
	ds_read_b128 v[172:175], v148 offset:3072
	v_add_u32_e32 v148, s73, v133
	ds_read_b128 v[176:179], v148
	ds_read_b128 v[180:183], v148 offset:1024
	ds_read_b128 v[184:187], v148 offset:2048
	ds_read_b128 v[188:191], v148 offset:3072
	v_lshl_add_u64 v[148:149], s[28:29], 0, v[140:141]
	s_add_i32 m0, s45, 0xc000
	ds_read_b128 v[192:195], v156
	ds_read_b128 v[196:199], v156 offset:1024
	ds_read_b128 v[204:207], v156 offset:2048
	ds_read_b128 v[208:211], v156 offset:3072
	ds_read_b128 v[212:215], v156 offset:4096
	ds_read_b128 v[216:219], v156 offset:5120
	ds_read_b128 v[220:223], v156 offset:6144
	ds_read_b128 v[224:227], v156 offset:7168
	global_load_lds_dwordx4 v[148:149], off
	v_lshl_add_u64 v[148:149], s[28:29], 0, v[142:143]
	s_add_i32 m0, s45, 0xe000
	s_nop 0
	global_load_lds_dwordx4 v[148:149], off
	s_waitcnt vmcnt(8)
	s_waitcnt lgkmcnt(0)
	s_barrier
	s_setprio 1
	v_mfma_f32_16x16x32_bf16 v[126:129], v[144:147], v[192:195], v[126:129]
	v_mfma_f32_16x16x32_bf16 v[122:125], v[162:165], v[192:195], v[122:125]
	v_mfma_f32_16x16x32_bf16 v[110:113], v[144:147], v[204:207], v[110:113]
	v_mfma_f32_16x16x32_bf16 v[106:109], v[162:165], v[204:207], v[106:109]
	v_mfma_f32_16x16x32_bf16 v[92:95], v[144:147], v[212:215], v[92:95]
	v_mfma_f32_16x16x32_bf16 v[88:91], v[162:165], v[212:215], v[88:91]
	v_mfma_f32_16x16x32_bf16 v[76:79], v[144:147], v[220:223], v[76:79]
	v_mfma_f32_16x16x32_bf16 v[72:75], v[162:165], v[220:223], v[72:75]
	v_mfma_f32_16x16x32_bf16 v[126:129], v[158:161], v[196:199], v[126:129]
	v_mfma_f32_16x16x32_bf16 v[122:125], v[172:175], v[196:199], v[122:125]
	v_mfma_f32_16x16x32_bf16 v[110:113], v[158:161], v[208:211], v[110:113]
	v_mfma_f32_16x16x32_bf16 v[106:109], v[172:175], v[208:211], v[106:109]
	v_mfma_f32_16x16x32_bf16 v[92:95], v[158:161], v[216:219], v[92:95]
	v_mfma_f32_16x16x32_bf16 v[88:91], v[172:175], v[216:219], v[88:91]
	v_mfma_f32_16x16x32_bf16 v[76:79], v[158:161], v[224:227], v[76:79]
	v_mfma_f32_16x16x32_bf16 v[72:75], v[172:175], v[224:227], v[72:75]
	s_setprio 0
	s_setprio 1
	v_mfma_f32_16x16x32_bf16 v[118:121], v[176:179], v[192:195], v[118:121]
	v_mfma_f32_16x16x32_bf16 v[114:117], v[184:187], v[192:195], v[114:117]
	v_mfma_f32_16x16x32_bf16 v[102:105], v[176:179], v[204:207], v[102:105]
	v_mfma_f32_16x16x32_bf16 v[98:101], v[184:187], v[204:207], v[98:101]
	v_mfma_f32_16x16x32_bf16 v[84:87], v[176:179], v[212:215], v[84:87]
	v_mfma_f32_16x16x32_bf16 v[80:83], v[184:187], v[212:215], v[80:83]
	v_mfma_f32_16x16x32_bf16 v[68:71], v[176:179], v[220:223], v[68:71]
	v_mfma_f32_16x16x32_bf16 v[64:67], v[184:187], v[220:223], v[64:67]
	v_mfma_f32_16x16x32_bf16 v[118:121], v[180:183], v[196:199], v[118:121]
	v_mfma_f32_16x16x32_bf16 v[114:117], v[188:191], v[196:199], v[114:117]
	v_mfma_f32_16x16x32_bf16 v[102:105], v[180:183], v[208:211], v[102:105]
	v_mfma_f32_16x16x32_bf16 v[98:101], v[188:191], v[208:211], v[98:101]
	v_mfma_f32_16x16x32_bf16 v[84:87], v[180:183], v[216:219], v[84:87]
	v_mfma_f32_16x16x32_bf16 v[80:83], v[188:191], v[216:219], v[80:83]
	v_mfma_f32_16x16x32_bf16 v[68:71], v[180:183], v[224:227], v[68:71]
	v_mfma_f32_16x16x32_bf16 v[64:67], v[188:191], v[224:227], v[64:67]
	s_setprio 0
	s_barrier
	s_add_i32 s62, s62, s44
	v_lshl_add_u64 v[148:149], s[30:31], 0, v[96:97]
	s_mov_b32 m0, s62
	ds_read_b128 v[192:195], v156 offset:16384
	ds_read_b128 v[196:199], v156 offset:17408
	ds_read_b128 v[204:207], v156 offset:18432
	ds_read_b128 v[208:211], v156 offset:19456
	ds_read_b128 v[212:215], v156 offset:20480
	ds_read_b128 v[216:219], v156 offset:21504
	ds_read_b128 v[220:223], v156 offset:22528
	ds_read_b128 v[224:227], v156 offset:23552
	global_load_lds_dwordx4 v[148:149], off
	s_add_i32 m0, s62, 0x2000
	s_add_u32 s62, s30, 0x80000
	v_lshl_add_u64 v[200:201], s[30:31], 0, v[138:139]
	s_addc_u32 s63, s31, 0
	s_add_i32 s73, s73, s44
	global_load_lds_dwordx4 v[200:201], off
	v_lshl_add_u64 v[228:229], s[62:63], 0, v[96:97]
	s_mov_b32 m0, s73
	v_lshl_add_u64 v[230:231], s[34:35], 0, v[136:137]
	global_load_lds_dwordx4 v[228:229], off
	v_lshl_add_u64 v[228:229], s[62:63], 0, v[138:139]
	s_add_i32 m0, s73, 0x2000
	s_nop 0
	global_load_lds_dwordx4 v[228:229], off
	v_lshl_add_u64 v[228:229], s[34:35], 0, v[134:135]
	s_mov_b32 m0, s45
	s_nop 0
	global_load_lds_dwordx4 v[228:229], off
	s_mov_b32 m0, s46
	s_nop 0
	global_load_lds_dwordx4 v[230:231], off
	s_waitcnt vmcnt(8)
	s_waitcnt lgkmcnt(0)
	s_barrier
; #define PG8_STAGE(bufoff, gbase, voff) do { _Pragma("unroll") for (int _i = 0; _i < 2; ++_i) \
;         __builtin_amdgcn_global_load_lds((const unsigned*)((const char*)(gbase) + (voff)[_i]), (PG8_LAS unsigned*)(lds + (bufoff) + ldsw + _i * 8192), 16, 0, 0); } while (0)
; #define PG8_LDA(dst, b, h) do { _Pragma("unroll") for (int m = 0; m < 4; ++m) _Pragma("unroll") for (int k = 0; k < 2; ++k) dst[m][k] = *(const PG8_LAS bf16x8*)(lds + PG8_SA(b, h) + aoff + m * 2048 + k * 1024); } while (0)
; #define PG8_LDB(dst, b, h) do { _Pragma("unroll") for (int n = 0; n < 2; ++n) _Pragma("unroll") for (int k = 0; k < 2; ++k) dst[n][k] = *(const PG8_LAS bf16x8*)(lds + PG8_SB(b, h) + boff + n * 2048 + k * 1024); } while (0)
; #define PG8_MMA(ai, bj, At, Bt) do { __builtin_amdgcn_s_setprio(1); _Pragma("unroll") for (int m = 0; m < 4; ++m) _Pragma("unroll") for (int n = 0; n < 2; ++n) _Pragma("unroll") for (int k = 0; k < 2; ++k) \
;         acc[ai][bj][m][n] = __builtin_amdgcn_mfma_f32_16x16x32_bf16(Bt[n][k], At[m][k], acc[ai][bj][m][n], 0, 0, 0); __builtin_amdgcn_s_setprio(0); } while (0)
; #define PG8_WAIT_V(n) asm volatile("s_waitcnt vmcnt(" #n ")" ::: "memory")
; #define PG8_WAIT_L(n) asm volatile("s_waitcnt lgkmcnt(" #n ")" ::: "memory")
; #define PG8_BAR __builtin_amdgcn_s_barrier()
; #define PG8_SCHED __builtin_amdgcn_sched_barrier(0)
; template <class Epi, class Sched, bool ALIGN_EPI = false, bool SP2 = false>
; __device__ __forceinline__ void gemm_phase(PG8_LAS unsigned char* lds, const Gemm g, const Sched& S, const Epi& E, int tid_in) {
;     ...
;             PG8_WAIT_V(8); PG8_WAIT_L(0); PG8_BAR; PG8_MMA(1, 0, At, B0); PG8_MMA(1, 1, At, B1); PG8_BAR; PG8_SCHED;
;             PG8_LDB(B0, 1, 0); PG8_LDB(B1, 1, 1); PG8_SCHED; PG8_LDA(At, 1, 0); PG8_STAGE(PG8_SA(0, 1), a2 + hstep, voffA);
;             PG8_WAIT_V(8); PG8_WAIT_L(0); PG8_BAR; PG8_MMA(0, 0, At, B0); PG8_MMA(0, 1, At, B1); PG8_BAR; PG8_SCHED;
	s_setprio 1
	v_mfma_f32_16x16x32_bf16 v[60:63], v[144:147], v[192:195], v[60:63]
	v_mfma_f32_16x16x32_bf16 v[56:59], v[162:165], v[192:195], v[56:59]
	v_mfma_f32_16x16x32_bf16 v[44:47], v[144:147], v[204:207], v[44:47]
	v_mfma_f32_16x16x32_bf16 v[40:43], v[162:165], v[204:207], v[40:43]
	v_mfma_f32_16x16x32_bf16 v[28:31], v[144:147], v[212:215], v[28:31]
	v_mfma_f32_16x16x32_bf16 v[24:27], v[162:165], v[212:215], v[24:27]
	v_mfma_f32_16x16x32_bf16 v[12:15], v[144:147], v[220:223], v[12:15]
	v_mfma_f32_16x16x32_bf16 v[8:11], v[162:165], v[220:223], v[8:11]
	v_mfma_f32_16x16x32_bf16 v[60:63], v[158:161], v[196:199], v[60:63]
	v_mfma_f32_16x16x32_bf16 v[56:59], v[172:175], v[196:199], v[56:59]
	v_mfma_f32_16x16x32_bf16 v[44:47], v[158:161], v[208:211], v[44:47]
	v_mfma_f32_16x16x32_bf16 v[40:43], v[172:175], v[208:211], v[40:43]
	v_mfma_f32_16x16x32_bf16 v[28:31], v[158:161], v[216:219], v[28:31]
	v_mfma_f32_16x16x32_bf16 v[24:27], v[172:175], v[216:219], v[24:27]
	v_mfma_f32_16x16x32_bf16 v[12:15], v[158:161], v[224:227], v[12:15]
	v_mfma_f32_16x16x32_bf16 v[8:11], v[172:175], v[224:227], v[8:11]
	s_setprio 0
	s_setprio 1
	v_mfma_f32_16x16x32_bf16 v[52:55], v[176:179], v[192:195], v[52:55]
	v_mfma_f32_16x16x32_bf16 v[48:51], v[184:187], v[192:195], v[48:51]
	v_mfma_f32_16x16x32_bf16 v[36:39], v[176:179], v[204:207], v[36:39]
	v_mfma_f32_16x16x32_bf16 v[32:35], v[184:187], v[204:207], v[32:35]
	v_mfma_f32_16x16x32_bf16 v[20:23], v[176:179], v[212:215], v[20:23]
	v_mfma_f32_16x16x32_bf16 v[16:19], v[184:187], v[212:215], v[16:19]
	v_mfma_f32_16x16x32_bf16 v[4:7], v[176:179], v[220:223], v[4:7]
	v_mfma_f32_16x16x32_bf16 v[0:3], v[184:187], v[220:223], v[0:3]
	v_mfma_f32_16x16x32_bf16 v[52:55], v[180:183], v[196:199], v[52:55]
	v_mfma_f32_16x16x32_bf16 v[48:51], v[188:191], v[196:199], v[48:51]
	v_mfma_f32_16x16x32_bf16 v[36:39], v[180:183], v[208:211], v[36:39]
	v_mfma_f32_16x16x32_bf16 v[32:35], v[188:191], v[208:211], v[32:35]
	v_mfma_f32_16x16x32_bf16 v[20:23], v[180:183], v[216:219], v[20:23]
	v_mfma_f32_16x16x32_bf16 v[16:19], v[188:191], v[216:219], v[16:19]
	v_mfma_f32_16x16x32_bf16 v[4:7], v[180:183], v[224:227], v[4:7]
	v_mfma_f32_16x16x32_bf16 v[0:3], v[188:191], v[224:227], v[0:3]
	s_setprio 0
	s_barrier
	s_add_i32 s62, 0, 0x18000
	v_add_u32_e32 v157, s62, v133
	s_add_i32 s63, 0, 0x1c000
	ds_read_b128 v[144:147], v157
	ds_read_b128 v[158:161], v157 offset:1024
	ds_read_b128 v[162:165], v157 offset:2048
	ds_read_b128 v[172:175], v157 offset:3072
	v_add_u32_e32 v157, s63, v133
	ds_read_b128 v[176:179], v157
	ds_read_b128 v[180:183], v157 offset:1024
	ds_read_b128 v[184:187], v157 offset:2048
	ds_read_b128 v[188:191], v157 offset:3072
	s_add_u32 s34, s34, 0x80000
	s_addc_u32 s35, s35, 0
	s_mov_b32 m0, s47
	v_lshl_add_u64 v[232:233], s[34:35], 0, v[134:135]
	ds_read_b128 v[192:195], v156 offset:32768
	ds_read_b128 v[196:199], v156 offset:33792
	ds_read_b128 v[204:207], v156 offset:34816
	ds_read_b128 v[208:211], v156 offset:35840
	ds_read_b128 v[212:215], v156 offset:36864
	ds_read_b128 v[216:219], v156 offset:37888
	ds_read_b128 v[220:223], v156 offset:38912
	ds_read_b128 v[224:227], v156 offset:39936
	global_load_lds_dwordx4 v[232:233], off
	v_lshl_add_u64 v[232:233], s[34:35], 0, v[136:137]
	s_mov_b32 m0, s52
	s_nop 0
	global_load_lds_dwordx4 v[232:233], off
	s_waitcnt vmcnt(8)
	s_waitcnt lgkmcnt(0)
	s_barrier
	s_setprio 1
	v_mfma_f32_16x16x32_bf16 v[126:129], v[144:147], v[192:195], v[126:129]
	v_mfma_f32_16x16x32_bf16 v[122:125], v[162:165], v[192:195], v[122:125]
	v_mfma_f32_16x16x32_bf16 v[110:113], v[144:147], v[204:207], v[110:113]
	v_mfma_f32_16x16x32_bf16 v[106:109], v[162:165], v[204:207], v[106:109]
	v_mfma_f32_16x16x32_bf16 v[92:95], v[144:147], v[212:215], v[92:95]
	v_mfma_f32_16x16x32_bf16 v[88:91], v[162:165], v[212:215], v[88:91]
	v_mfma_f32_16x16x32_bf16 v[76:79], v[144:147], v[220:223], v[76:79]
	v_mfma_f32_16x16x32_bf16 v[72:75], v[162:165], v[220:223], v[72:75]
	v_mfma_f32_16x16x32_bf16 v[126:129], v[158:161], v[196:199], v[126:129]
	v_mfma_f32_16x16x32_bf16 v[122:125], v[172:175], v[196:199], v[122:125]
	v_mfma_f32_16x16x32_bf16 v[110:113], v[158:161], v[208:211], v[110:113]
	v_mfma_f32_16x16x32_bf16 v[106:109], v[172:175], v[208:211], v[106:109]
	v_mfma_f32_16x16x32_bf16 v[92:95], v[158:161], v[216:219], v[92:95]
	v_mfma_f32_16x16x32_bf16 v[88:91], v[172:175], v[216:219], v[88:91]
	v_mfma_f32_16x16x32_bf16 v[76:79], v[158:161], v[224:227], v[76:79]
	v_mfma_f32_16x16x32_bf16 v[72:75], v[172:175], v[224:227], v[72:75]
	s_setprio 0
	s_setprio 1
	v_mfma_f32_16x16x32_bf16 v[118:121], v[176:179], v[192:195], v[118:121]
	v_mfma_f32_16x16x32_bf16 v[114:117], v[184:187], v[192:195], v[114:117]
	v_mfma_f32_16x16x32_bf16 v[102:105], v[176:179], v[204:207], v[102:105]
	v_mfma_f32_16x16x32_bf16 v[98:101], v[184:187], v[204:207], v[98:101]
	v_mfma_f32_16x16x32_bf16 v[84:87], v[176:179], v[212:215], v[84:87]
	v_mfma_f32_16x16x32_bf16 v[80:83], v[184:187], v[212:215], v[80:83]
	v_mfma_f32_16x16x32_bf16 v[68:71], v[176:179], v[220:223], v[68:71]
	v_mfma_f32_16x16x32_bf16 v[64:67], v[184:187], v[220:223], v[64:67]
	v_mfma_f32_16x16x32_bf16 v[118:121], v[180:183], v[196:199], v[118:121]
	v_mfma_f32_16x16x32_bf16 v[114:117], v[188:191], v[196:199], v[114:117]
	v_mfma_f32_16x16x32_bf16 v[102:105], v[180:183], v[208:211], v[102:105]
	v_mfma_f32_16x16x32_bf16 v[98:101], v[188:191], v[208:211], v[98:101]
	v_mfma_f32_16x16x32_bf16 v[84:87], v[180:183], v[216:219], v[84:87]
	v_mfma_f32_16x16x32_bf16 v[80:83], v[188:191], v[216:219], v[80:83]
	v_mfma_f32_16x16x32_bf16 v[68:71], v[180:183], v[224:227], v[68:71]
	v_mfma_f32_16x16x32_bf16 v[64:67], v[188:191], v[224:227], v[64:67]
	s_setprio 0
	s_barrier
; #define PG8_STAGE(bufoff, gbase, voff) do { _Pragma("unroll") for (int _i = 0; _i < 2; ++_i) \
;         __builtin_amdgcn_global_load_lds((const unsigned*)((const char*)(gbase) + (voff)[_i]), (PG8_LAS unsigned*)(lds + (bufoff) + ldsw + _i * 8192), 16, 0, 0); } while (0)
; #define PG8_LDA(dst, b, h) do { _Pragma("unroll") for (int m = 0; m < 4; ++m) _Pragma("unroll") for (int k = 0; k < 2; ++k) dst[m][k] = *(const PG8_LAS bf16x8*)(lds + PG8_SA(b, h) + aoff + m * 2048 + k * 1024); } while (0)
; #define PG8_MMA(ai, bj, At, Bt) do { __builtin_amdgcn_s_setprio(1); _Pragma("unroll") for (int m = 0; m < 4; ++m) _Pragma("unroll") for (int n = 0; n < 2; ++n) _Pragma("unroll") for (int k = 0; k < 2; ++k) \
;         acc[ai][bj][m][n] = __builtin_amdgcn_mfma_f32_16x16x32_bf16(Bt[n][k], At[m][k], acc[ai][bj][m][n], 0, 0, 0); __builtin_amdgcn_s_setprio(0); } while (0)
; #define PG8_WAIT_V(n) asm volatile("s_waitcnt vmcnt(" #n ")" ::: "memory")
; #define PG8_WAIT_L(n) asm volatile("s_waitcnt lgkmcnt(" #n ")" ::: "memory")
; #define PG8_BAR __builtin_amdgcn_s_barrier()
; #define PG8_SCHED __builtin_amdgcn_sched_barrier(0)
; template <class Epi, class Sched, bool ALIGN_EPI = false, bool SP2 = false>
; __device__ __forceinline__ void gemm_phase(PG8_LAS unsigned char* lds, const Gemm g, const Sched& S, const Epi& E, int tid_in) {
;     ...
;             PG8_LDA(At, 1, 1); PG8_STAGE(PG8_SB(1, 0), b3, voffB); PG8_STAGE(PG8_SB(1, 1), b3 + hstep, voffB); PG8_STAGE(PG8_SA(1, 0), a3, voffA);
;             PG8_WAIT_V(8); PG8_WAIT_L(0); PG8_BAR; PG8_MMA(1, 0, At, B0); PG8_MMA(1, 1, At, B1); PG8_BAR; PG8_SCHED;
;     ...
;         if constexpr (ALIGN_EPI) { if (wr == 0) PG8_BAR; }
	s_add_i32 s34, s62, s44
	v_lshl_add_u64 v[148:149], v[148:149], 0, s[88:89]
	s_mov_b32 m0, s34
	ds_read_b128 v[192:195], v156 offset:49152
	ds_read_b128 v[196:199], v156 offset:50176
	ds_read_b128 v[204:207], v156 offset:51200
	ds_read_b128 v[208:211], v156 offset:52224
	ds_read_b128 v[212:215], v156 offset:53248
	ds_read_b128 v[216:219], v156 offset:54272
	ds_read_b128 v[220:223], v156 offset:55296
	ds_read_b128 v[224:227], v156 offset:56320
	global_load_lds_dwordx4 v[148:149], off
	s_add_i32 m0, s34, 0x2000
	s_add_u32 s30, s30, 0x80080
	v_lshl_add_u64 v[148:149], v[200:201], 0, s[88:89]
	s_addc_u32 s31, s31, 0
	s_add_i32 s34, s63, s44
	global_load_lds_dwordx4 v[148:149], off
	v_lshl_add_u64 v[148:149], s[30:31], 0, v[96:97]
	s_mov_b32 m0, s34
	s_nop 0
	global_load_lds_dwordx4 v[148:149], off
	v_lshl_add_u64 v[148:149], s[30:31], 0, v[138:139]
	s_add_i32 m0, s34, 0x2000
	s_nop 0
	global_load_lds_dwordx4 v[148:149], off
	v_lshl_add_u64 v[148:149], v[228:229], 0, s[88:89]
	s_mov_b32 m0, s64
	s_nop 0
	global_load_lds_dwordx4 v[148:149], off
	v_lshl_add_u64 v[148:149], v[230:231], 0, s[88:89]
	s_mov_b32 m0, s65
	s_nop 0
	global_load_lds_dwordx4 v[148:149], off
	s_waitcnt vmcnt(8)
	s_waitcnt lgkmcnt(0)
	s_barrier
	s_setprio 1
	v_mfma_f32_16x16x32_bf16 v[60:63], v[144:147], v[192:195], v[60:63]
	v_mfma_f32_16x16x32_bf16 v[56:59], v[162:165], v[192:195], v[56:59]
	v_mfma_f32_16x16x32_bf16 v[44:47], v[144:147], v[204:207], v[44:47]
	v_mfma_f32_16x16x32_bf16 v[40:43], v[162:165], v[204:207], v[40:43]
	v_mfma_f32_16x16x32_bf16 v[28:31], v[144:147], v[212:215], v[28:31]
	v_mfma_f32_16x16x32_bf16 v[24:27], v[162:165], v[212:215], v[24:27]
	v_mfma_f32_16x16x32_bf16 v[12:15], v[144:147], v[220:223], v[12:15]
	v_mfma_f32_16x16x32_bf16 v[8:11], v[162:165], v[220:223], v[8:11]
	v_mfma_f32_16x16x32_bf16 v[60:63], v[158:161], v[196:199], v[60:63]
	v_mfma_f32_16x16x32_bf16 v[56:59], v[172:175], v[196:199], v[56:59]
	v_mfma_f32_16x16x32_bf16 v[44:47], v[158:161], v[208:211], v[44:47]
	v_mfma_f32_16x16x32_bf16 v[40:43], v[172:175], v[208:211], v[40:43]
	v_mfma_f32_16x16x32_bf16 v[28:31], v[158:161], v[216:219], v[28:31]
	v_mfma_f32_16x16x32_bf16 v[24:27], v[172:175], v[216:219], v[24:27]
	v_mfma_f32_16x16x32_bf16 v[12:15], v[158:161], v[224:227], v[12:15]
	v_mfma_f32_16x16x32_bf16 v[8:11], v[172:175], v[224:227], v[8:11]
	s_setprio 0
	s_setprio 1
	v_mfma_f32_16x16x32_bf16 v[52:55], v[176:179], v[192:195], v[52:55]
	v_mfma_f32_16x16x32_bf16 v[48:51], v[184:187], v[192:195], v[48:51]
	v_mfma_f32_16x16x32_bf16 v[36:39], v[176:179], v[204:207], v[36:39]
	v_mfma_f32_16x16x32_bf16 v[32:35], v[184:187], v[204:207], v[32:35]
	v_mfma_f32_16x16x32_bf16 v[20:23], v[176:179], v[212:215], v[20:23]
	v_mfma_f32_16x16x32_bf16 v[16:19], v[184:187], v[212:215], v[16:19]
	v_mfma_f32_16x16x32_bf16 v[4:7], v[176:179], v[220:223], v[4:7]
	v_mfma_f32_16x16x32_bf16 v[0:3], v[184:187], v[220:223], v[0:3]
	v_mfma_f32_16x16x32_bf16 v[52:55], v[180:183], v[196:199], v[52:55]
	v_mfma_f32_16x16x32_bf16 v[48:51], v[188:191], v[196:199], v[48:51]
	v_mfma_f32_16x16x32_bf16 v[36:39], v[180:183], v[208:211], v[36:39]
	v_mfma_f32_16x16x32_bf16 v[32:35], v[188:191], v[208:211], v[32:35]
	v_mfma_f32_16x16x32_bf16 v[20:23], v[180:183], v[216:219], v[20:23]
	v_mfma_f32_16x16x32_bf16 v[16:19], v[188:191], v[216:219], v[16:19]
	v_mfma_f32_16x16x32_bf16 v[4:7], v[180:183], v[224:227], v[4:7]
	v_mfma_f32_16x16x32_bf16 v[0:3], v[188:191], v[224:227], v[0:3]
	s_setprio 0
	s_barrier
	s_add_i32 s72, s72, 2
	s_add_u32 s28, s28, 0x100
	s_addc_u32 s29, s29, 0
	s_add_u32 s70, s70, 0x100
	s_addc_u32 s71, s71, 0
	s_cmp_gt_u32 s72, 29
	s_cbranch_scc0 .LBB0_632
	v_readlane_b32 s70, v255, 33
	s_and_b64 vcc, exec, s[16:17]
	v_readlane_b32 s71, v255, 34
	s_cbranch_vccz .LBB0_635
	s_barrier

; #define PG8_STAGE(bufoff, gbase, voff) do { _Pragma("unroll") for (int _i = 0; _i < 2; ++_i) \
;         __builtin_amdgcn_global_load_lds((const unsigned*)((const char*)(gbase) + (voff)[_i]), (PG8_LAS unsigned*)(lds + (bufoff) + ldsw + _i * 8192), 16, 0, 0); } while (0)
; #define PG8_LDA(dst, b, h) do { _Pragma("unroll") for (int m = 0; m < 4; ++m) _Pragma("unroll") for (int k = 0; k < 2; ++k) dst[m][k] = *(const PG8_LAS bf16x8*)(lds + PG8_SA(b, h) + aoff + m * 2048 + k * 1024); } while (0)
; #define PG8_LDB(dst, b, h) do { _Pragma("unroll") for (int n = 0; n < 2; ++n) _Pragma("unroll") for (int k = 0; k < 2; ++k) dst[n][k] = *(const PG8_LAS bf16x8*)(lds + PG8_SB(b, h) + boff + n * 2048 + k * 1024); } while (0)
; #define PG8_MMA(ai, bj, At, Bt) do { __builtin_amdgcn_s_setprio(1); _Pragma("unroll") for (int m = 0; m < 4; ++m) _Pragma("unroll") for (int n = 0; n < 2; ++n) _Pragma("unroll") for (int k = 0; k < 2; ++k) \
;         acc[ai][bj][m][n] = __builtin_amdgcn_mfma_f32_16x16x32_bf16(Bt[n][k], At[m][k], acc[ai][bj][m][n], 0, 0, 0); __builtin_amdgcn_s_setprio(0); } while (0)
; #define PG8_WAIT_V(n) asm volatile("s_waitcnt vmcnt(" #n ")" ::: "memory")
; #define PG8_BAR __builtin_amdgcn_s_barrier()
; template <class Epi, class Sched, bool ALIGN_EPI = false, bool SP2 = false>
; __device__ __forceinline__ void gemm_phase(PG8_LAS unsigned char* lds, const Gemm g, const Sched& S, const Epi& E, int tid_in) {
;     ...
;         for (int t = 0; t < nt; t += 2) {
;             const bool last = (t == nt - 2);
;             const char* a1 = cA + (size_t)(t + 1) * kstep;
;             const char* a2 = last ? nA : cA + (size_t)(t + 2) * kstep; const char* b2 = last ? nB : cB + (size_t)(t + 2) * kstep;
;             const char* a3 = a2 + kstep; const char* b3 = b2 + kstep;
;             if (last && has_next) S.a_ready(nxt);
;             if constexpr (SP2) {
;             PG8_LDB(B0, 0, 0); PG8_LDB(B1, 0, 1); PG8_SCHED; PG8_LDA(At, 0, 0); PG8_STAGE(PG8_SA(1, 1), a1 + hstep, voffA);
;             PG8_WAIT_V(8); PG8_WAIT_L(0); PG8_BAR; PG8_MMA(0, 0, At, B0); PG8_MMA(0, 1, At, B1); PG8_BAR; PG8_SCHED;
;             PG8_LDA(At, 0, 1); PG8_STAGE(PG8_SB(0, 0), b2, voffB); PG8_STAGE(PG8_SB(0, 1), b2 + hstep, voffB); PG8_STAGE(PG8_SA(0, 0), a2, voffA);
;             PG8_WAIT_V(8); PG8_WAIT_L(0); PG8_BAR; PG8_MMA(1, 0, At, B0); PG8_MMA(1, 1, At, B1); PG8_BAR; PG8_SCHED;
.LBB0_749:
	s_add_u32 s24, s22, 0xfff80080
	s_addc_u32 s25, s23, -1
	s_add_i32 s52, 0, 0x10000
	s_cmp_eq_u32 s47, 28
	s_cselect_b32 s27, s17, s25
	s_cselect_b32 s26, s43, s24
	v_add_u32_e32 v145, s52, v142
	s_cselect_b32 s25, s15, s46
	s_cselect_b32 s24, s44, s45
	s_add_i32 s64, 0, 0x14000
	ds_read_b128 v[146:149], v145
	ds_read_b128 v[150:153], v145 offset:1024
	ds_read_b128 v[154:157], v145 offset:2048
	ds_read_b128 v[158:161], v145 offset:3072
	v_add_u32_e32 v145, s64, v142
	ds_read_b128 v[162:165], v145
	ds_read_b128 v[172:175], v145 offset:1024
	ds_read_b128 v[176:179], v145 offset:2048
	ds_read_b128 v[180:183], v145 offset:3072
	v_lshl_add_u64 v[200:201], s[22:23], 0, v[136:137]
	s_add_i32 m0, s13, 0xc000
	ds_read_b128 v[184:187], v144
	ds_read_b128 v[188:191], v144 offset:1024
	ds_read_b128 v[192:195], v144 offset:2048
	ds_read_b128 v[196:199], v144 offset:3072
	ds_read_b128 v[204:207], v144 offset:4096
	ds_read_b128 v[208:211], v144 offset:5120
	ds_read_b128 v[212:215], v144 offset:6144
	ds_read_b128 v[216:219], v144 offset:7168
	global_load_lds_dwordx4 v[200:201], off
	v_lshl_add_u64 v[200:201], s[22:23], 0, v[138:139]
	s_add_i32 m0, s13, 0xe000
	s_nop 0
	global_load_lds_dwordx4 v[200:201], off
	s_waitcnt vmcnt(8)
	s_waitcnt lgkmcnt(0)
	s_barrier
	s_setprio 1
	v_mfma_f32_16x16x32_bf16 v[126:129], v[146:149], v[184:187], v[126:129]
	v_mfma_f32_16x16x32_bf16 v[122:125], v[154:157], v[184:187], v[122:125]
	v_mfma_f32_16x16x32_bf16 v[118:121], v[146:149], v[192:195], v[118:121]
	v_mfma_f32_16x16x32_bf16 v[114:117], v[154:157], v[192:195], v[114:117]
	v_mfma_f32_16x16x32_bf16 v[102:105], v[146:149], v[204:207], v[102:105]
	v_mfma_f32_16x16x32_bf16 v[98:101], v[154:157], v[204:207], v[98:101]
	v_mfma_f32_16x16x32_bf16 v[84:87], v[146:149], v[212:215], v[84:87]
	v_mfma_f32_16x16x32_bf16 v[80:83], v[154:157], v[212:215], v[80:83]
	v_mfma_f32_16x16x32_bf16 v[126:129], v[150:153], v[188:191], v[126:129]
	v_mfma_f32_16x16x32_bf16 v[122:125], v[158:161], v[188:191], v[122:125]
	v_mfma_f32_16x16x32_bf16 v[118:121], v[150:153], v[196:199], v[118:121]
	v_mfma_f32_16x16x32_bf16 v[114:117], v[158:161], v[196:199], v[114:117]
	v_mfma_f32_16x16x32_bf16 v[102:105], v[150:153], v[208:211], v[102:105]
	v_mfma_f32_16x16x32_bf16 v[98:101], v[158:161], v[208:211], v[98:101]
	v_mfma_f32_16x16x32_bf16 v[84:87], v[150:153], v[216:219], v[84:87]
	v_mfma_f32_16x16x32_bf16 v[80:83], v[158:161], v[216:219], v[80:83]
	s_setprio 0
	s_setprio 1
	v_mfma_f32_16x16x32_bf16 v[110:113], v[162:165], v[184:187], v[110:113]
	v_mfma_f32_16x16x32_bf16 v[106:109], v[176:179], v[184:187], v[106:109]
	v_mfma_f32_16x16x32_bf16 v[92:95], v[162:165], v[192:195], v[92:95]
	v_mfma_f32_16x16x32_bf16 v[88:91], v[176:179], v[192:195], v[88:91]
	v_mfma_f32_16x16x32_bf16 v[76:79], v[162:165], v[204:207], v[76:79]
	v_mfma_f32_16x16x32_bf16 v[72:75], v[176:179], v[204:207], v[72:75]
	v_mfma_f32_16x16x32_bf16 v[68:71], v[162:165], v[212:215], v[68:71]
	v_mfma_f32_16x16x32_bf16 v[64:67], v[176:179], v[212:215], v[64:67]
	v_mfma_f32_16x16x32_bf16 v[110:113], v[172:175], v[188:191], v[110:113]
	v_mfma_f32_16x16x32_bf16 v[106:109], v[180:183], v[188:191], v[106:109]
	v_mfma_f32_16x16x32_bf16 v[92:95], v[172:175], v[196:199], v[92:95]
	v_mfma_f32_16x16x32_bf16 v[88:91], v[180:183], v[196:199], v[88:91]
	v_mfma_f32_16x16x32_bf16 v[76:79], v[172:175], v[208:211], v[76:79]
	v_mfma_f32_16x16x32_bf16 v[72:75], v[180:183], v[208:211], v[72:75]
	v_mfma_f32_16x16x32_bf16 v[68:71], v[172:175], v[216:219], v[68:71]
	v_mfma_f32_16x16x32_bf16 v[64:67], v[180:183], v[216:219], v[64:67]
	s_setprio 0
	s_barrier
	s_add_i32 s52, s52, s35
	v_lshl_add_u64 v[200:201], s[24:25], 0, v[96:97]
	s_mov_b32 m0, s52
	ds_read_b128 v[184:187], v144 offset:16384
	ds_read_b128 v[188:191], v144 offset:17408
	ds_read_b128 v[192:195], v144 offset:18432
	ds_read_b128 v[196:199], v144 offset:19456
	ds_read_b128 v[204:207], v144 offset:20480
	ds_read_b128 v[208:211], v144 offset:21504
	ds_read_b128 v[212:215], v144 offset:22528
	ds_read_b128 v[216:219], v144 offset:23552
	global_load_lds_dwordx4 v[200:201], off
	s_add_i32 m0, s52, 0x2000
	s_add_u32 s62, s24, 0x80000
	v_lshl_add_u64 v[220:221], s[24:25], 0, v[134:135]
	s_addc_u32 s63, s25, 0
	s_add_i32 s52, s64, s35
	global_load_lds_dwordx4 v[220:221], off
	v_lshl_add_u64 v[222:223], s[62:63], 0, v[96:97]
	s_mov_b32 m0, s52
	v_lshl_add_u64 v[224:225], s[26:27], 0, v[132:133]
	global_load_lds_dwordx4 v[222:223], off
	v_lshl_add_u64 v[222:223], s[62:63], 0, v[134:135]
	s_add_i32 m0, s52, 0x2000
	s_nop 0
	global_load_lds_dwordx4 v[222:223], off
	v_lshl_add_u64 v[222:223], s[26:27], 0, v[130:131]
	s_mov_b32 m0, s13
	s_nop 0
	global_load_lds_dwordx4 v[222:223], off
	s_mov_b32 m0, s36
	s_nop 0
	global_load_lds_dwordx4 v[224:225], off
	s_waitcnt vmcnt(8)
	s_waitcnt lgkmcnt(0)
	s_barrier
; #define PG8_STAGE(bufoff, gbase, voff) do { _Pragma("unroll") for (int _i = 0; _i < 2; ++_i) \
;         __builtin_amdgcn_global_load_lds((const unsigned*)((const char*)(gbase) + (voff)[_i]), (PG8_LAS unsigned*)(lds + (bufoff) + ldsw + _i * 8192), 16, 0, 0); } while (0)
; #define PG8_LDA(dst, b, h) do { _Pragma("unroll") for (int m = 0; m < 4; ++m) _Pragma("unroll") for (int k = 0; k < 2; ++k) dst[m][k] = *(const PG8_LAS bf16x8*)(lds + PG8_SA(b, h) + aoff + m * 2048 + k * 1024); } while (0)
; #define PG8_LDB(dst, b, h) do { _Pragma("unroll") for (int n = 0; n < 2; ++n) _Pragma("unroll") for (int k = 0; k < 2; ++k) dst[n][k] = *(const PG8_LAS bf16x8*)(lds + PG8_SB(b, h) + boff + n * 2048 + k * 1024); } while (0)
; #define PG8_MMA(ai, bj, At, Bt) do { __builtin_amdgcn_s_setprio(1); _Pragma("unroll") for (int m = 0; m < 4; ++m) _Pragma("unroll") for (int n = 0; n < 2; ++n) _Pragma("unroll") for (int k = 0; k < 2; ++k) \
;         acc[ai][bj][m][n] = __builtin_amdgcn_mfma_f32_16x16x32_bf16(Bt[n][k], At[m][k], acc[ai][bj][m][n], 0, 0, 0); __builtin_amdgcn_s_setprio(0); } while (0)
; #define PG8_WAIT_V(n) asm volatile("s_waitcnt vmcnt(" #n ")" ::: "memory")
; #define PG8_WAIT_L(n) asm volatile("s_waitcnt lgkmcnt(" #n ")" ::: "memory")
; #define PG8_BAR __builtin_amdgcn_s_barrier()
; #define PG8_SCHED __builtin_amdgcn_sched_barrier(0)
; template <class Epi, class Sched, bool ALIGN_EPI = false, bool SP2 = false>
; __device__ __forceinline__ void gemm_phase(PG8_LAS unsigned char* lds, const Gemm g, const Sched& S, const Epi& E, int tid_in) {
;     ...
;             PG8_WAIT_V(8); PG8_WAIT_L(0); PG8_BAR; PG8_MMA(1, 0, At, B0); PG8_MMA(1, 1, At, B1); PG8_BAR; PG8_SCHED;
;             PG8_LDB(B0, 1, 0); PG8_LDB(B1, 1, 1); PG8_SCHED; PG8_LDA(At, 1, 0); PG8_STAGE(PG8_SA(0, 1), a2 + hstep, voffA);
;             PG8_WAIT_V(8); PG8_WAIT_L(0); PG8_BAR; PG8_MMA(0, 0, At, B0); PG8_MMA(0, 1, At, B1); PG8_BAR; PG8_SCHED;
	s_setprio 1
	v_mfma_f32_16x16x32_bf16 v[60:63], v[146:149], v[184:187], v[60:63]
	v_mfma_f32_16x16x32_bf16 v[56:59], v[154:157], v[184:187], v[56:59]
	v_mfma_f32_16x16x32_bf16 v[52:55], v[146:149], v[192:195], v[52:55]
	v_mfma_f32_16x16x32_bf16 v[48:51], v[154:157], v[192:195], v[48:51]
	v_mfma_f32_16x16x32_bf16 v[36:39], v[146:149], v[204:207], v[36:39]
	v_mfma_f32_16x16x32_bf16 v[32:35], v[154:157], v[204:207], v[32:35]
	v_mfma_f32_16x16x32_bf16 v[20:23], v[146:149], v[212:215], v[20:23]
	v_mfma_f32_16x16x32_bf16 v[16:19], v[154:157], v[212:215], v[16:19]
	v_mfma_f32_16x16x32_bf16 v[60:63], v[150:153], v[188:191], v[60:63]
	v_mfma_f32_16x16x32_bf16 v[56:59], v[158:161], v[188:191], v[56:59]
	v_mfma_f32_16x16x32_bf16 v[52:55], v[150:153], v[196:199], v[52:55]
	v_mfma_f32_16x16x32_bf16 v[48:51], v[158:161], v[196:199], v[48:51]
	v_mfma_f32_16x16x32_bf16 v[36:39], v[150:153], v[208:211], v[36:39]
	v_mfma_f32_16x16x32_bf16 v[32:35], v[158:161], v[208:211], v[32:35]
	v_mfma_f32_16x16x32_bf16 v[20:23], v[150:153], v[216:219], v[20:23]
	v_mfma_f32_16x16x32_bf16 v[16:19], v[158:161], v[216:219], v[16:19]
	s_setprio 0
	s_setprio 1
	v_mfma_f32_16x16x32_bf16 v[44:47], v[162:165], v[184:187], v[44:47]
	v_mfma_f32_16x16x32_bf16 v[40:43], v[176:179], v[184:187], v[40:43]
	v_mfma_f32_16x16x32_bf16 v[28:31], v[162:165], v[192:195], v[28:31]
	v_mfma_f32_16x16x32_bf16 v[24:27], v[176:179], v[192:195], v[24:27]
	v_mfma_f32_16x16x32_bf16 v[12:15], v[162:165], v[204:207], v[12:15]
	v_mfma_f32_16x16x32_bf16 v[8:11], v[176:179], v[204:207], v[8:11]
	v_mfma_f32_16x16x32_bf16 v[4:7], v[162:165], v[212:215], v[4:7]
	v_mfma_f32_16x16x32_bf16 v[0:3], v[176:179], v[212:215], v[0:3]
	v_mfma_f32_16x16x32_bf16 v[44:47], v[172:175], v[188:191], v[44:47]
	v_mfma_f32_16x16x32_bf16 v[40:43], v[180:183], v[188:191], v[40:43]
	v_mfma_f32_16x16x32_bf16 v[28:31], v[172:175], v[196:199], v[28:31]
	v_mfma_f32_16x16x32_bf16 v[24:27], v[180:183], v[196:199], v[24:27]
	v_mfma_f32_16x16x32_bf16 v[12:15], v[172:175], v[208:211], v[12:15]
	v_mfma_f32_16x16x32_bf16 v[8:11], v[180:183], v[208:211], v[8:11]
	v_mfma_f32_16x16x32_bf16 v[4:7], v[172:175], v[216:219], v[4:7]
	v_mfma_f32_16x16x32_bf16 v[0:3], v[180:183], v[216:219], v[0:3]
	s_setprio 0
	s_barrier
	s_add_i32 s52, 0, 0x18000
	v_add_u32_e32 v145, s52, v142
	s_add_i32 s62, 0, 0x1c000
	ds_read_b128 v[146:149], v145
	ds_read_b128 v[150:153], v145 offset:1024
	ds_read_b128 v[154:157], v145 offset:2048
	ds_read_b128 v[158:161], v145 offset:3072
	v_add_u32_e32 v145, s62, v142
	ds_read_b128 v[162:165], v145
	ds_read_b128 v[172:175], v145 offset:1024
	ds_read_b128 v[176:179], v145 offset:2048
	ds_read_b128 v[180:183], v145 offset:3072
	s_add_u32 s26, s26, 0x80000
	s_addc_u32 s27, s27, 0
	s_mov_b32 m0, s37
	v_lshl_add_u64 v[226:227], s[26:27], 0, v[130:131]
	ds_read_b128 v[184:187], v144 offset:32768
	ds_read_b128 v[188:191], v144 offset:33792
	ds_read_b128 v[192:195], v144 offset:34816
	ds_read_b128 v[196:199], v144 offset:35840
	ds_read_b128 v[204:207], v144 offset:36864
	ds_read_b128 v[208:211], v144 offset:37888
	ds_read_b128 v[212:215], v144 offset:38912
	ds_read_b128 v[216:219], v144 offset:39936
	global_load_lds_dwordx4 v[226:227], off
	v_lshl_add_u64 v[226:227], s[26:27], 0, v[132:133]
	s_mov_b32 m0, s38
	s_nop 0
	global_load_lds_dwordx4 v[226:227], off
	s_waitcnt vmcnt(8)
	s_waitcnt lgkmcnt(0)
	s_barrier
	s_setprio 1
	v_mfma_f32_16x16x32_bf16 v[126:129], v[146:149], v[184:187], v[126:129]
	v_mfma_f32_16x16x32_bf16 v[122:125], v[154:157], v[184:187], v[122:125]
	v_mfma_f32_16x16x32_bf16 v[118:121], v[146:149], v[192:195], v[118:121]
	v_mfma_f32_16x16x32_bf16 v[114:117], v[154:157], v[192:195], v[114:117]
	v_mfma_f32_16x16x32_bf16 v[102:105], v[146:149], v[204:207], v[102:105]
	v_mfma_f32_16x16x32_bf16 v[98:101], v[154:157], v[204:207], v[98:101]
	v_mfma_f32_16x16x32_bf16 v[84:87], v[146:149], v[212:215], v[84:87]
	v_mfma_f32_16x16x32_bf16 v[80:83], v[154:157], v[212:215], v[80:83]
	v_mfma_f32_16x16x32_bf16 v[126:129], v[150:153], v[188:191], v[126:129]
	v_mfma_f32_16x16x32_bf16 v[122:125], v[158:161], v[188:191], v[122:125]
	v_mfma_f32_16x16x32_bf16 v[118:121], v[150:153], v[196:199], v[118:121]
	v_mfma_f32_16x16x32_bf16 v[114:117], v[158:161], v[196:199], v[114:117]
	v_mfma_f32_16x16x32_bf16 v[102:105], v[150:153], v[208:211], v[102:105]
	v_mfma_f32_16x16x32_bf16 v[98:101], v[158:161], v[208:211], v[98:101]
	v_mfma_f32_16x16x32_bf16 v[84:87], v[150:153], v[216:219], v[84:87]
	v_mfma_f32_16x16x32_bf16 v[80:83], v[158:161], v[216:219], v[80:83]
	s_setprio 0
	s_setprio 1
	v_mfma_f32_16x16x32_bf16 v[110:113], v[162:165], v[184:187], v[110:113]
	v_mfma_f32_16x16x32_bf16 v[106:109], v[176:179], v[184:187], v[106:109]
	v_mfma_f32_16x16x32_bf16 v[92:95], v[162:165], v[192:195], v[92:95]
	v_mfma_f32_16x16x32_bf16 v[88:91], v[176:179], v[192:195], v[88:91]
	v_mfma_f32_16x16x32_bf16 v[76:79], v[162:165], v[204:207], v[76:79]
	v_mfma_f32_16x16x32_bf16 v[72:75], v[176:179], v[204:207], v[72:75]
	v_mfma_f32_16x16x32_bf16 v[68:71], v[162:165], v[212:215], v[68:71]
	v_mfma_f32_16x16x32_bf16 v[64:67], v[176:179], v[212:215], v[64:67]
	v_mfma_f32_16x16x32_bf16 v[110:113], v[172:175], v[188:191], v[110:113]
	v_mfma_f32_16x16x32_bf16 v[106:109], v[180:183], v[188:191], v[106:109]
	v_mfma_f32_16x16x32_bf16 v[92:95], v[172:175], v[196:199], v[92:95]
	v_mfma_f32_16x16x32_bf16 v[88:91], v[180:183], v[196:199], v[88:91]
	v_mfma_f32_16x16x32_bf16 v[76:79], v[172:175], v[208:211], v[76:79]
	v_mfma_f32_16x16x32_bf16 v[72:75], v[180:183], v[208:211], v[72:75]
	v_mfma_f32_16x16x32_bf16 v[68:71], v[172:175], v[216:219], v[68:71]
	v_mfma_f32_16x16x32_bf16 v[64:67], v[180:183], v[216:219], v[64:67]
	s_setprio 0
	s_barrier
; #define PG8_STAGE(bufoff, gbase, voff) do { _Pragma("unroll") for (int _i = 0; _i < 2; ++_i) \
;         __builtin_amdgcn_global_load_lds((const unsigned*)((const char*)(gbase) + (voff)[_i]), (PG8_LAS unsigned*)(lds + (bufoff) + ldsw + _i * 8192), 16, 0, 0); } while (0)
; #define PG8_LDA(dst, b, h) do { _Pragma("unroll") for (int m = 0; m < 4; ++m) _Pragma("unroll") for (int k = 0; k < 2; ++k) dst[m][k] = *(const PG8_LAS bf16x8*)(lds + PG8_SA(b, h) + aoff + m * 2048 + k * 1024); } while (0)
; #define PG8_MMA(ai, bj, At, Bt) do { __builtin_amdgcn_s_setprio(1); _Pragma("unroll") for (int m = 0; m < 4; ++m) _Pragma("unroll") for (int n = 0; n < 2; ++n) _Pragma("unroll") for (int k = 0; k < 2; ++k) \
;         acc[ai][bj][m][n] = __builtin_amdgcn_mfma_f32_16x16x32_bf16(Bt[n][k], At[m][k], acc[ai][bj][m][n], 0, 0, 0); __builtin_amdgcn_s_setprio(0); } while (0)
; #define PG8_WAIT_V(n) asm volatile("s_waitcnt vmcnt(" #n ")" ::: "memory")
; #define PG8_WAIT_L(n) asm volatile("s_waitcnt lgkmcnt(" #n ")" ::: "memory")
; #define PG8_BAR __builtin_amdgcn_s_barrier()
; #define PG8_SCHED __builtin_amdgcn_sched_barrier(0)
; template <class Epi, class Sched, bool ALIGN_EPI = false, bool SP2 = false>
; __device__ __forceinline__ void gemm_phase(PG8_LAS unsigned char* lds, const Gemm g, const Sched& S, const Epi& E, int tid_in) {
;     ...
;             PG8_LDA(At, 1, 1); PG8_STAGE(PG8_SB(1, 0), b3, voffB); PG8_STAGE(PG8_SB(1, 1), b3 + hstep, voffB); PG8_STAGE(PG8_SA(1, 0), a3, voffA);
;             PG8_WAIT_V(8); PG8_WAIT_L(0); PG8_BAR; PG8_MMA(1, 0, At, B0); PG8_MMA(1, 1, At, B1); PG8_BAR; PG8_SCHED;
;     ...
;         if constexpr (ALIGN_EPI) { if (wr == 0) PG8_BAR; }
	s_add_i32 s26, s52, s35
	v_lshl_add_u64 v[200:201], v[200:201], 0, s[88:89]
	s_mov_b32 m0, s26
	ds_read_b128 v[184:187], v144 offset:49152
	ds_read_b128 v[188:191], v144 offset:50176
	ds_read_b128 v[192:195], v144 offset:51200
	ds_read_b128 v[196:199], v144 offset:52224
	ds_read_b128 v[204:207], v144 offset:53248
	ds_read_b128 v[208:211], v144 offset:54272
	ds_read_b128 v[212:215], v144 offset:55296
	ds_read_b128 v[216:219], v144 offset:56320
	global_load_lds_dwordx4 v[200:201], off
	s_add_i32 m0, s26, 0x2000
	s_add_u32 s24, s24, 0x80080
	v_lshl_add_u64 v[200:201], v[220:221], 0, s[88:89]
	s_addc_u32 s25, s25, 0
	s_add_i32 s26, s62, s35
	global_load_lds_dwordx4 v[200:201], off
	v_lshl_add_u64 v[200:201], s[24:25], 0, v[96:97]
	s_mov_b32 m0, s26
	s_nop 0
	global_load_lds_dwordx4 v[200:201], off
	v_lshl_add_u64 v[200:201], s[24:25], 0, v[134:135]
	s_add_i32 m0, s26, 0x2000
	s_nop 0
	global_load_lds_dwordx4 v[200:201], off
	v_lshl_add_u64 v[200:201], v[222:223], 0, s[88:89]
	s_mov_b32 m0, s39
	s_nop 0
	global_load_lds_dwordx4 v[200:201], off
	v_lshl_add_u64 v[200:201], v[224:225], 0, s[88:89]
	s_mov_b32 m0, s40
	s_nop 0
	global_load_lds_dwordx4 v[200:201], off
	s_waitcnt vmcnt(8)
	s_waitcnt lgkmcnt(0)
	s_barrier
	s_setprio 1
	v_mfma_f32_16x16x32_bf16 v[60:63], v[146:149], v[184:187], v[60:63]
	v_mfma_f32_16x16x32_bf16 v[56:59], v[154:157], v[184:187], v[56:59]
	v_mfma_f32_16x16x32_bf16 v[52:55], v[146:149], v[192:195], v[52:55]
	v_mfma_f32_16x16x32_bf16 v[48:51], v[154:157], v[192:195], v[48:51]
	v_mfma_f32_16x16x32_bf16 v[36:39], v[146:149], v[204:207], v[36:39]
	v_mfma_f32_16x16x32_bf16 v[32:35], v[154:157], v[204:207], v[32:35]
	v_mfma_f32_16x16x32_bf16 v[20:23], v[146:149], v[212:215], v[20:23]
	v_mfma_f32_16x16x32_bf16 v[16:19], v[154:157], v[212:215], v[16:19]
	v_mfma_f32_16x16x32_bf16 v[60:63], v[150:153], v[188:191], v[60:63]
	v_mfma_f32_16x16x32_bf16 v[56:59], v[158:161], v[188:191], v[56:59]
	v_mfma_f32_16x16x32_bf16 v[52:55], v[150:153], v[196:199], v[52:55]
	v_mfma_f32_16x16x32_bf16 v[48:51], v[158:161], v[196:199], v[48:51]
	v_mfma_f32_16x16x32_bf16 v[36:39], v[150:153], v[208:211], v[36:39]
	v_mfma_f32_16x16x32_bf16 v[32:35], v[158:161], v[208:211], v[32:35]
	v_mfma_f32_16x16x32_bf16 v[20:23], v[150:153], v[216:219], v[20:23]
	v_mfma_f32_16x16x32_bf16 v[16:19], v[158:161], v[216:219], v[16:19]
	s_setprio 0
	s_setprio 1
	v_mfma_f32_16x16x32_bf16 v[44:47], v[162:165], v[184:187], v[44:47]
	v_mfma_f32_16x16x32_bf16 v[40:43], v[176:179], v[184:187], v[40:43]
	v_mfma_f32_16x16x32_bf16 v[28:31], v[162:165], v[192:195], v[28:31]
	v_mfma_f32_16x16x32_bf16 v[24:27], v[176:179], v[192:195], v[24:27]
	v_mfma_f32_16x16x32_bf16 v[12:15], v[162:165], v[204:207], v[12:15]
	v_mfma_f32_16x16x32_bf16 v[8:11], v[176:179], v[204:207], v[8:11]
	v_mfma_f32_16x16x32_bf16 v[4:7], v[162:165], v[212:215], v[4:7]
	v_mfma_f32_16x16x32_bf16 v[0:3], v[176:179], v[212:215], v[0:3]
	v_mfma_f32_16x16x32_bf16 v[44:47], v[172:175], v[188:191], v[44:47]
	v_mfma_f32_16x16x32_bf16 v[40:43], v[180:183], v[188:191], v[40:43]
	v_mfma_f32_16x16x32_bf16 v[28:31], v[172:175], v[196:199], v[28:31]
	v_mfma_f32_16x16x32_bf16 v[24:27], v[180:183], v[196:199], v[24:27]
	v_mfma_f32_16x16x32_bf16 v[12:15], v[172:175], v[208:211], v[12:15]
	v_mfma_f32_16x16x32_bf16 v[8:11], v[180:183], v[208:211], v[8:11]
	v_mfma_f32_16x16x32_bf16 v[4:7], v[172:175], v[216:219], v[4:7]
	v_mfma_f32_16x16x32_bf16 v[0:3], v[180:183], v[216:219], v[0:3]
	s_setprio 0
	s_barrier
	s_add_i32 s47, s47, 2
	s_add_u32 s22, s22, 0x100
	s_addc_u32 s23, s23, 0
	s_add_u32 s45, s45, 0x100
	s_addc_u32 s46, s46, 0
	s_cmp_gt_u32 s47, 29
	s_cbranch_scc0 .LBB0_749
	s_and_b64 vcc, exec, s[10:11]
	s_cbranch_vccz .LBB0_752
	s_barrier

; #define PG8_STAGE(bufoff, gbase, voff) do { _Pragma("unroll") for (int _i = 0; _i < 2; ++_i) \
;         __builtin_amdgcn_global_load_lds((const unsigned*)((const char*)(gbase) + (voff)[_i]), (PG8_LAS unsigned*)(lds + (bufoff) + ldsw + _i * 8192), 16, 0, 0); } while (0)
; #define PG8_LDA(dst, b, h) do { _Pragma("unroll") for (int m = 0; m < 4; ++m) _Pragma("unroll") for (int k = 0; k < 2; ++k) dst[m][k] = *(const PG8_LAS bf16x8*)(lds + PG8_SA(b, h) + aoff + m * 2048 + k * 1024); } while (0)
; #define PG8_LDB(dst, b, h) do { _Pragma("unroll") for (int n = 0; n < 2; ++n) _Pragma("unroll") for (int k = 0; k < 2; ++k) dst[n][k] = *(const PG8_LAS bf16x8*)(lds + PG8_SB(b, h) + boff + n * 2048 + k * 1024); } while (0)
; #define PG8_MMA(ai, bj, At, Bt) do { __builtin_amdgcn_s_setprio(1); _Pragma("unroll") for (int m = 0; m < 4; ++m) _Pragma("unroll") for (int n = 0; n < 2; ++n) _Pragma("unroll") for (int k = 0; k < 2; ++k) \
;         acc[ai][bj][m][n] = __builtin_amdgcn_mfma_f32_16x16x32_bf16(Bt[n][k], At[m][k], acc[ai][bj][m][n], 0, 0, 0); __builtin_amdgcn_s_setprio(0); } while (0)
; #define PG8_WAIT_V(n) asm volatile("s_waitcnt vmcnt(" #n ")" ::: "memory")
; #define PG8_BAR __builtin_amdgcn_s_barrier()
; template <class Epi, class Sched, bool ALIGN_EPI = false, bool SP2 = false>
; __device__ __forceinline__ void gemm_phase(PG8_LAS unsigned char* lds, const Gemm g, const Sched& S, const Epi& E, int tid_in) {
;     ...
;         for (int t = 0; t < nt; t += 2) {
;             const bool last = (t == nt - 2);
;             const char* a1 = cA + (size_t)(t + 1) * kstep;
;             const char* a2 = last ? nA : cA + (size_t)(t + 2) * kstep; const char* b2 = last ? nB : cB + (size_t)(t + 2) * kstep;
;             const char* a3 = a2 + kstep; const char* b3 = b2 + kstep;
;             if (last && has_next) S.a_ready(nxt);
;             if constexpr (SP2) {
;             PG8_LDB(B0, 0, 0); PG8_LDB(B1, 0, 1); PG8_SCHED; PG8_LDA(At, 0, 0); PG8_STAGE(PG8_SA(1, 1), a1 + hstep, voffA);
;             PG8_WAIT_V(8); PG8_WAIT_L(0); PG8_BAR; PG8_MMA(0, 0, At, B0); PG8_MMA(0, 1, At, B1); PG8_BAR; PG8_SCHED;
;             PG8_LDA(At, 0, 1); PG8_STAGE(PG8_SB(0, 0), b2, voffB); PG8_STAGE(PG8_SB(0, 1), b2 + hstep, voffB); PG8_STAGE(PG8_SA(0, 0), a2, voffA);
;             PG8_WAIT_V(8); PG8_WAIT_L(0); PG8_BAR; PG8_MMA(1, 0, At, B0); PG8_MMA(1, 1, At, B1); PG8_BAR; PG8_SCHED;
.LBB0_979:
	s_add_u32 s26, s24, 0xfff80080
	s_addc_u32 s27, s25, -1
	s_add_i32 s62, 0, 0x10000
	s_cmp_eq_u32 s64, 28
	s_cselect_b32 s29, s17, s27
	s_cselect_b32 s28, s45, s26
	v_add_u32_e32 v140, s62, v144
	s_cselect_b32 s27, s15, s52
	s_cselect_b32 s26, s46, s47
	s_add_i32 s65, 0, 0x14000
	ds_read_b128 v[148:151], v140
	ds_read_b128 v[152:155], v140 offset:1024
	ds_read_b128 v[156:159], v140 offset:2048
	ds_read_b128 v[160:163], v140 offset:3072
	v_add_u32_e32 v140, s65, v144
	ds_read_b128 v[172:175], v140
	ds_read_b128 v[176:179], v140 offset:1024
	ds_read_b128 v[180:183], v140 offset:2048
	ds_read_b128 v[184:187], v140 offset:3072
	v_lshl_add_u64 v[140:141], s[24:25], 0, v[136:137]
	s_add_i32 m0, s38, 0xc000
	ds_read_b128 v[188:191], v146
	ds_read_b128 v[192:195], v146 offset:1024
	ds_read_b128 v[196:199], v146 offset:2048
	ds_read_b128 v[204:207], v146 offset:3072
	ds_read_b128 v[208:211], v146 offset:4096
	ds_read_b128 v[212:215], v146 offset:5120
	ds_read_b128 v[216:219], v146 offset:6144
	ds_read_b128 v[220:223], v146 offset:7168
	global_load_lds_dwordx4 v[140:141], off
	v_lshl_add_u64 v[140:141], s[24:25], 0, v[138:139]
	s_add_i32 m0, s38, 0xe000
	s_nop 0
	global_load_lds_dwordx4 v[140:141], off
	s_waitcnt vmcnt(8)
	s_waitcnt lgkmcnt(0)
	s_barrier
	s_setprio 1
	v_mfma_f32_16x16x32_bf16 v[126:129], v[148:151], v[188:191], v[126:129]
	v_mfma_f32_16x16x32_bf16 v[118:121], v[156:159], v[188:191], v[118:121]
	v_mfma_f32_16x16x32_bf16 v[110:113], v[148:151], v[196:199], v[110:113]
	v_mfma_f32_16x16x32_bf16 v[102:105], v[156:159], v[196:199], v[102:105]
	v_mfma_f32_16x16x32_bf16 v[92:95], v[148:151], v[208:211], v[92:95]
	v_mfma_f32_16x16x32_bf16 v[84:87], v[156:159], v[208:211], v[84:87]
	v_mfma_f32_16x16x32_bf16 v[76:79], v[148:151], v[216:219], v[76:79]
	v_mfma_f32_16x16x32_bf16 v[68:71], v[156:159], v[216:219], v[68:71]
	v_mfma_f32_16x16x32_bf16 v[126:129], v[152:155], v[192:195], v[126:129]
	v_mfma_f32_16x16x32_bf16 v[118:121], v[160:163], v[192:195], v[118:121]
	v_mfma_f32_16x16x32_bf16 v[110:113], v[152:155], v[204:207], v[110:113]
	v_mfma_f32_16x16x32_bf16 v[102:105], v[160:163], v[204:207], v[102:105]
	v_mfma_f32_16x16x32_bf16 v[92:95], v[152:155], v[212:215], v[92:95]
	v_mfma_f32_16x16x32_bf16 v[84:87], v[160:163], v[212:215], v[84:87]
	v_mfma_f32_16x16x32_bf16 v[76:79], v[152:155], v[220:223], v[76:79]
	v_mfma_f32_16x16x32_bf16 v[68:71], v[160:163], v[220:223], v[68:71]
	s_setprio 0
	s_setprio 1
	v_mfma_f32_16x16x32_bf16 v[122:125], v[172:175], v[188:191], v[122:125]
	v_mfma_f32_16x16x32_bf16 v[114:117], v[180:183], v[188:191], v[114:117]
	v_mfma_f32_16x16x32_bf16 v[106:109], v[172:175], v[196:199], v[106:109]
	v_mfma_f32_16x16x32_bf16 v[98:101], v[180:183], v[196:199], v[98:101]
	v_mfma_f32_16x16x32_bf16 v[88:91], v[172:175], v[208:211], v[88:91]
	v_mfma_f32_16x16x32_bf16 v[80:83], v[180:183], v[208:211], v[80:83]
	v_mfma_f32_16x16x32_bf16 v[72:75], v[172:175], v[216:219], v[72:75]
	v_mfma_f32_16x16x32_bf16 v[64:67], v[180:183], v[216:219], v[64:67]
	v_mfma_f32_16x16x32_bf16 v[122:125], v[176:179], v[192:195], v[122:125]
	v_mfma_f32_16x16x32_bf16 v[114:117], v[184:187], v[192:195], v[114:117]
	v_mfma_f32_16x16x32_bf16 v[106:109], v[176:179], v[204:207], v[106:109]
	v_mfma_f32_16x16x32_bf16 v[98:101], v[184:187], v[204:207], v[98:101]
	v_mfma_f32_16x16x32_bf16 v[88:91], v[176:179], v[212:215], v[88:91]
	v_mfma_f32_16x16x32_bf16 v[80:83], v[184:187], v[212:215], v[80:83]
	v_mfma_f32_16x16x32_bf16 v[72:75], v[176:179], v[220:223], v[72:75]
	v_mfma_f32_16x16x32_bf16 v[64:67], v[184:187], v[220:223], v[64:67]
	s_setprio 0
	s_barrier
	s_add_i32 s62, s62, s36
	v_lshl_add_u64 v[140:141], s[26:27], 0, v[96:97]
	s_mov_b32 m0, s62
	ds_read_b128 v[188:191], v146 offset:16384
	ds_read_b128 v[192:195], v146 offset:17408
	ds_read_b128 v[196:199], v146 offset:18432
	ds_read_b128 v[204:207], v146 offset:19456
	ds_read_b128 v[208:211], v146 offset:20480
	ds_read_b128 v[212:215], v146 offset:21504
	ds_read_b128 v[216:219], v146 offset:22528
	ds_read_b128 v[220:223], v146 offset:23552
	global_load_lds_dwordx4 v[140:141], off
	s_add_i32 m0, s62, 0x2000
	s_add_u32 s62, s26, 0x80000
	v_lshl_add_u64 v[164:165], s[26:27], 0, v[130:131]
	s_addc_u32 s63, s27, 0
	s_add_i32 s65, s65, s36
	global_load_lds_dwordx4 v[164:165], off
	v_lshl_add_u64 v[200:201], s[62:63], 0, v[96:97]
	s_mov_b32 m0, s65
	v_lshl_add_u64 v[224:225], s[28:29], 0, v[132:133]
	global_load_lds_dwordx4 v[200:201], off
	v_lshl_add_u64 v[200:201], s[62:63], 0, v[130:131]
	s_add_i32 m0, s65, 0x2000
	s_nop 0
	global_load_lds_dwordx4 v[200:201], off
	v_lshl_add_u64 v[200:201], s[28:29], 0, v[134:135]
	s_mov_b32 m0, s38
	s_nop 0
	global_load_lds_dwordx4 v[200:201], off
	s_mov_b32 m0, s39
	s_nop 0
	global_load_lds_dwordx4 v[224:225], off
	s_waitcnt vmcnt(8)
	s_waitcnt lgkmcnt(0)
	s_barrier
; #define PG8_STAGE(bufoff, gbase, voff) do { _Pragma("unroll") for (int _i = 0; _i < 2; ++_i) \
;         __builtin_amdgcn_global_load_lds((const unsigned*)((const char*)(gbase) + (voff)[_i]), (PG8_LAS unsigned*)(lds + (bufoff) + ldsw + _i * 8192), 16, 0, 0); } while (0)
; #define PG8_LDA(dst, b, h) do { _Pragma("unroll") for (int m = 0; m < 4; ++m) _Pragma("unroll") for (int k = 0; k < 2; ++k) dst[m][k] = *(const PG8_LAS bf16x8*)(lds + PG8_SA(b, h) + aoff + m * 2048 + k * 1024); } while (0)
; #define PG8_LDB(dst, b, h) do { _Pragma("unroll") for (int n = 0; n < 2; ++n) _Pragma("unroll") for (int k = 0; k < 2; ++k) dst[n][k] = *(const PG8_LAS bf16x8*)(lds + PG8_SB(b, h) + boff + n * 2048 + k * 1024); } while (0)
; #define PG8_MMA(ai, bj, At, Bt) do { __builtin_amdgcn_s_setprio(1); _Pragma("unroll") for (int m = 0; m < 4; ++m) _Pragma("unroll") for (int n = 0; n < 2; ++n) _Pragma("unroll") for (int k = 0; k < 2; ++k) \
;         acc[ai][bj][m][n] = __builtin_amdgcn_mfma_f32_16x16x32_bf16(Bt[n][k], At[m][k], acc[ai][bj][m][n], 0, 0, 0); __builtin_amdgcn_s_setprio(0); } while (0)
; #define PG8_WAIT_V(n) asm volatile("s_waitcnt vmcnt(" #n ")" ::: "memory")
; #define PG8_WAIT_L(n) asm volatile("s_waitcnt lgkmcnt(" #n ")" ::: "memory")
; #define PG8_BAR __builtin_amdgcn_s_barrier()
; #define PG8_SCHED __builtin_amdgcn_sched_barrier(0)
; template <class Epi, class Sched, bool ALIGN_EPI = false, bool SP2 = false>
; __device__ __forceinline__ void gemm_phase(PG8_LAS unsigned char* lds, const Gemm g, const Sched& S, const Epi& E, int tid_in) {
;     ...
;             PG8_WAIT_V(8); PG8_WAIT_L(0); PG8_BAR; PG8_MMA(1, 0, At, B0); PG8_MMA(1, 1, At, B1); PG8_BAR; PG8_SCHED;
;             PG8_LDB(B0, 1, 0); PG8_LDB(B1, 1, 1); PG8_SCHED; PG8_LDA(At, 1, 0); PG8_STAGE(PG8_SA(0, 1), a2 + hstep, voffA);
;             PG8_WAIT_V(8); PG8_WAIT_L(0); PG8_BAR; PG8_MMA(0, 0, At, B0); PG8_MMA(0, 1, At, B1); PG8_BAR; PG8_SCHED;
	s_setprio 1
	v_mfma_f32_16x16x32_bf16 v[60:63], v[148:151], v[188:191], v[60:63]
	v_mfma_f32_16x16x32_bf16 v[52:55], v[156:159], v[188:191], v[52:55]
	v_mfma_f32_16x16x32_bf16 v[44:47], v[148:151], v[196:199], v[44:47]
	v_mfma_f32_16x16x32_bf16 v[36:39], v[156:159], v[196:199], v[36:39]
	v_mfma_f32_16x16x32_bf16 v[28:31], v[148:151], v[208:211], v[28:31]
	v_mfma_f32_16x16x32_bf16 v[20:23], v[156:159], v[208:211], v[20:23]
	v_mfma_f32_16x16x32_bf16 v[12:15], v[148:151], v[216:219], v[12:15]
	v_mfma_f32_16x16x32_bf16 v[4:7], v[156:159], v[216:219], v[4:7]
	v_mfma_f32_16x16x32_bf16 v[60:63], v[152:155], v[192:195], v[60:63]
	v_mfma_f32_16x16x32_bf16 v[52:55], v[160:163], v[192:195], v[52:55]
	v_mfma_f32_16x16x32_bf16 v[44:47], v[152:155], v[204:207], v[44:47]
	v_mfma_f32_16x16x32_bf16 v[36:39], v[160:163], v[204:207], v[36:39]
	v_mfma_f32_16x16x32_bf16 v[28:31], v[152:155], v[212:215], v[28:31]
	v_mfma_f32_16x16x32_bf16 v[20:23], v[160:163], v[212:215], v[20:23]
	v_mfma_f32_16x16x32_bf16 v[12:15], v[152:155], v[220:223], v[12:15]
	v_mfma_f32_16x16x32_bf16 v[4:7], v[160:163], v[220:223], v[4:7]
	s_setprio 0
	s_setprio 1
	v_mfma_f32_16x16x32_bf16 v[56:59], v[172:175], v[188:191], v[56:59]
	v_mfma_f32_16x16x32_bf16 v[48:51], v[180:183], v[188:191], v[48:51]
	v_mfma_f32_16x16x32_bf16 v[40:43], v[172:175], v[196:199], v[40:43]
	v_mfma_f32_16x16x32_bf16 v[32:35], v[180:183], v[196:199], v[32:35]
	v_mfma_f32_16x16x32_bf16 v[24:27], v[172:175], v[208:211], v[24:27]
	v_mfma_f32_16x16x32_bf16 v[16:19], v[180:183], v[208:211], v[16:19]
	v_mfma_f32_16x16x32_bf16 v[8:11], v[172:175], v[216:219], v[8:11]
	v_mfma_f32_16x16x32_bf16 v[0:3], v[180:183], v[216:219], v[0:3]
	v_mfma_f32_16x16x32_bf16 v[56:59], v[176:179], v[192:195], v[56:59]
	v_mfma_f32_16x16x32_bf16 v[48:51], v[184:187], v[192:195], v[48:51]
	v_mfma_f32_16x16x32_bf16 v[40:43], v[176:179], v[204:207], v[40:43]
	v_mfma_f32_16x16x32_bf16 v[32:35], v[184:187], v[204:207], v[32:35]
	v_mfma_f32_16x16x32_bf16 v[24:27], v[176:179], v[212:215], v[24:27]
	v_mfma_f32_16x16x32_bf16 v[16:19], v[184:187], v[212:215], v[16:19]
	v_mfma_f32_16x16x32_bf16 v[8:11], v[176:179], v[220:223], v[8:11]
	v_mfma_f32_16x16x32_bf16 v[0:3], v[184:187], v[220:223], v[0:3]
	s_setprio 0
	s_barrier
	s_add_i32 s62, 0, 0x18000
	v_add_u32_e32 v147, s62, v144
	s_add_i32 s63, 0, 0x1c000
	ds_read_b128 v[148:151], v147
	ds_read_b128 v[152:155], v147 offset:1024
	ds_read_b128 v[156:159], v147 offset:2048
	ds_read_b128 v[160:163], v147 offset:3072
	v_add_u32_e32 v147, s63, v144
	ds_read_b128 v[172:175], v147
	ds_read_b128 v[176:179], v147 offset:1024
	ds_read_b128 v[180:183], v147 offset:2048
	ds_read_b128 v[184:187], v147 offset:3072
	s_add_u32 s28, s28, 0x80000
	s_addc_u32 s29, s29, 0
	s_mov_b32 m0, s40
	v_lshl_add_u64 v[226:227], s[28:29], 0, v[134:135]
	ds_read_b128 v[188:191], v146 offset:32768
	ds_read_b128 v[192:195], v146 offset:33792
	ds_read_b128 v[196:199], v146 offset:34816
	ds_read_b128 v[204:207], v146 offset:35840
	ds_read_b128 v[208:211], v146 offset:36864
	ds_read_b128 v[212:215], v146 offset:37888
	ds_read_b128 v[216:219], v146 offset:38912
	ds_read_b128 v[220:223], v146 offset:39936
	global_load_lds_dwordx4 v[226:227], off
	v_lshl_add_u64 v[226:227], s[28:29], 0, v[132:133]
	s_mov_b32 m0, s41
	s_nop 0
	global_load_lds_dwordx4 v[226:227], off
	s_waitcnt vmcnt(8)
	s_waitcnt lgkmcnt(0)
	s_barrier
	s_setprio 1
	v_mfma_f32_16x16x32_bf16 v[126:129], v[148:151], v[188:191], v[126:129]
	v_mfma_f32_16x16x32_bf16 v[118:121], v[156:159], v[188:191], v[118:121]
	v_mfma_f32_16x16x32_bf16 v[110:113], v[148:151], v[196:199], v[110:113]
	v_mfma_f32_16x16x32_bf16 v[102:105], v[156:159], v[196:199], v[102:105]
	v_mfma_f32_16x16x32_bf16 v[92:95], v[148:151], v[208:211], v[92:95]
	v_mfma_f32_16x16x32_bf16 v[84:87], v[156:159], v[208:211], v[84:87]
	v_mfma_f32_16x16x32_bf16 v[76:79], v[148:151], v[216:219], v[76:79]
	v_mfma_f32_16x16x32_bf16 v[68:71], v[156:159], v[216:219], v[68:71]
	v_mfma_f32_16x16x32_bf16 v[126:129], v[152:155], v[192:195], v[126:129]
	v_mfma_f32_16x16x32_bf16 v[118:121], v[160:163], v[192:195], v[118:121]
	v_mfma_f32_16x16x32_bf16 v[110:113], v[152:155], v[204:207], v[110:113]
	v_mfma_f32_16x16x32_bf16 v[102:105], v[160:163], v[204:207], v[102:105]
	v_mfma_f32_16x16x32_bf16 v[92:95], v[152:155], v[212:215], v[92:95]
	v_mfma_f32_16x16x32_bf16 v[84:87], v[160:163], v[212:215], v[84:87]
	v_mfma_f32_16x16x32_bf16 v[76:79], v[152:155], v[220:223], v[76:79]
	v_mfma_f32_16x16x32_bf16 v[68:71], v[160:163], v[220:223], v[68:71]
	s_setprio 0
	s_setprio 1
	v_mfma_f32_16x16x32_bf16 v[122:125], v[172:175], v[188:191], v[122:125]
	v_mfma_f32_16x16x32_bf16 v[114:117], v[180:183], v[188:191], v[114:117]
	v_mfma_f32_16x16x32_bf16 v[106:109], v[172:175], v[196:199], v[106:109]
	v_mfma_f32_16x16x32_bf16 v[98:101], v[180:183], v[196:199], v[98:101]
	v_mfma_f32_16x16x32_bf16 v[88:91], v[172:175], v[208:211], v[88:91]
	v_mfma_f32_16x16x32_bf16 v[80:83], v[180:183], v[208:211], v[80:83]
	v_mfma_f32_16x16x32_bf16 v[72:75], v[172:175], v[216:219], v[72:75]
	v_mfma_f32_16x16x32_bf16 v[64:67], v[180:183], v[216:219], v[64:67]
	v_mfma_f32_16x16x32_bf16 v[122:125], v[176:179], v[192:195], v[122:125]
	v_mfma_f32_16x16x32_bf16 v[114:117], v[184:187], v[192:195], v[114:117]
	v_mfma_f32_16x16x32_bf16 v[106:109], v[176:179], v[204:207], v[106:109]
	v_mfma_f32_16x16x32_bf16 v[98:101], v[184:187], v[204:207], v[98:101]
	v_mfma_f32_16x16x32_bf16 v[88:91], v[176:179], v[212:215], v[88:91]
	v_mfma_f32_16x16x32_bf16 v[80:83], v[184:187], v[212:215], v[80:83]
	v_mfma_f32_16x16x32_bf16 v[72:75], v[176:179], v[220:223], v[72:75]
	v_mfma_f32_16x16x32_bf16 v[64:67], v[184:187], v[220:223], v[64:67]
	s_setprio 0
	s_barrier
; #define PG8_STAGE(bufoff, gbase, voff) do { _Pragma("unroll") for (int _i = 0; _i < 2; ++_i) \
;         __builtin_amdgcn_global_load_lds((const unsigned*)((const char*)(gbase) + (voff)[_i]), (PG8_LAS unsigned*)(lds + (bufoff) + ldsw + _i * 8192), 16, 0, 0); } while (0)
; #define PG8_LDA(dst, b, h) do { _Pragma("unroll") for (int m = 0; m < 4; ++m) _Pragma("unroll") for (int k = 0; k < 2; ++k) dst[m][k] = *(const PG8_LAS bf16x8*)(lds + PG8_SA(b, h) + aoff + m * 2048 + k * 1024); } while (0)
; #define PG8_MMA(ai, bj, At, Bt) do { __builtin_amdgcn_s_setprio(1); _Pragma("unroll") for (int m = 0; m < 4; ++m) _Pragma("unroll") for (int n = 0; n < 2; ++n) _Pragma("unroll") for (int k = 0; k < 2; ++k) \
;         acc[ai][bj][m][n] = __builtin_amdgcn_mfma_f32_16x16x32_bf16(Bt[n][k], At[m][k], acc[ai][bj][m][n], 0, 0, 0); __builtin_amdgcn_s_setprio(0); } while (0)
; #define PG8_WAIT_V(n) asm volatile("s_waitcnt vmcnt(" #n ")" ::: "memory")
; #define PG8_WAIT_L(n) asm volatile("s_waitcnt lgkmcnt(" #n ")" ::: "memory")
; #define PG8_BAR __builtin_amdgcn_s_barrier()
; #define PG8_SCHED __builtin_amdgcn_sched_barrier(0)
; template <class Epi, class Sched, bool ALIGN_EPI = false, bool SP2 = false>
; __device__ __forceinline__ void gemm_phase(PG8_LAS unsigned char* lds, const Gemm g, const Sched& S, const Epi& E, int tid_in) {
;     ...
;             PG8_LDA(At, 1, 1); PG8_STAGE(PG8_SB(1, 0), b3, voffB); PG8_STAGE(PG8_SB(1, 1), b3 + hstep, voffB); PG8_STAGE(PG8_SA(1, 0), a3, voffA);
;             PG8_WAIT_V(8); PG8_WAIT_L(0); PG8_BAR; PG8_MMA(1, 0, At, B0); PG8_MMA(1, 1, At, B1); PG8_BAR; PG8_SCHED;
;     ...
;         if constexpr (ALIGN_EPI) { if (wr == 0) PG8_BAR; }
	s_add_i32 s28, s62, s36
	v_lshl_add_u64 v[140:141], v[140:141], 0, s[88:89]
	s_mov_b32 m0, s28
	ds_read_b128 v[188:191], v146 offset:49152
	ds_read_b128 v[192:195], v146 offset:50176
	ds_read_b128 v[196:199], v146 offset:51200
	ds_read_b128 v[204:207], v146 offset:52224
	ds_read_b128 v[208:211], v146 offset:53248
	ds_read_b128 v[212:215], v146 offset:54272
	ds_read_b128 v[216:219], v146 offset:55296
	ds_read_b128 v[220:223], v146 offset:56320
	global_load_lds_dwordx4 v[140:141], off
	s_add_i32 m0, s28, 0x2000
	s_add_u32 s26, s26, 0x80080
	v_lshl_add_u64 v[140:141], v[164:165], 0, s[88:89]
	s_addc_u32 s27, s27, 0
	s_add_i32 s28, s63, s36
	global_load_lds_dwordx4 v[140:141], off
	v_lshl_add_u64 v[140:141], s[26:27], 0, v[96:97]
	s_mov_b32 m0, s28
	s_nop 0
	global_load_lds_dwordx4 v[140:141], off
	v_lshl_add_u64 v[140:141], s[26:27], 0, v[130:131]
	s_add_i32 m0, s28, 0x2000
	s_nop 0
	global_load_lds_dwordx4 v[140:141], off
	v_lshl_add_u64 v[140:141], v[200:201], 0, s[88:89]
	s_mov_b32 m0, s42
	s_nop 0
	global_load_lds_dwordx4 v[140:141], off
	v_lshl_add_u64 v[140:141], v[224:225], 0, s[88:89]
	s_mov_b32 m0, s43
	s_nop 0
	global_load_lds_dwordx4 v[140:141], off
	s_waitcnt vmcnt(8)
	s_waitcnt lgkmcnt(0)
	s_barrier
	s_setprio 1
	v_mfma_f32_16x16x32_bf16 v[60:63], v[148:151], v[188:191], v[60:63]
	v_mfma_f32_16x16x32_bf16 v[52:55], v[156:159], v[188:191], v[52:55]
	v_mfma_f32_16x16x32_bf16 v[44:47], v[148:151], v[196:199], v[44:47]
	v_mfma_f32_16x16x32_bf16 v[36:39], v[156:159], v[196:199], v[36:39]
	v_mfma_f32_16x16x32_bf16 v[28:31], v[148:151], v[208:211], v[28:31]
	v_mfma_f32_16x16x32_bf16 v[20:23], v[156:159], v[208:211], v[20:23]
	v_mfma_f32_16x16x32_bf16 v[12:15], v[148:151], v[216:219], v[12:15]
	v_mfma_f32_16x16x32_bf16 v[4:7], v[156:159], v[216:219], v[4:7]
	v_mfma_f32_16x16x32_bf16 v[60:63], v[152:155], v[192:195], v[60:63]
	v_mfma_f32_16x16x32_bf16 v[52:55], v[160:163], v[192:195], v[52:55]
	v_mfma_f32_16x16x32_bf16 v[44:47], v[152:155], v[204:207], v[44:47]
	v_mfma_f32_16x16x32_bf16 v[36:39], v[160:163], v[204:207], v[36:39]
	v_mfma_f32_16x16x32_bf16 v[28:31], v[152:155], v[212:215], v[28:31]
	v_mfma_f32_16x16x32_bf16 v[20:23], v[160:163], v[212:215], v[20:23]
	v_mfma_f32_16x16x32_bf16 v[12:15], v[152:155], v[220:223], v[12:15]
	v_mfma_f32_16x16x32_bf16 v[4:7], v[160:163], v[220:223], v[4:7]
	s_setprio 0
	s_setprio 1
	v_mfma_f32_16x16x32_bf16 v[56:59], v[172:175], v[188:191], v[56:59]
	v_mfma_f32_16x16x32_bf16 v[48:51], v[180:183], v[188:191], v[48:51]
	v_mfma_f32_16x16x32_bf16 v[40:43], v[172:175], v[196:199], v[40:43]
	v_mfma_f32_16x16x32_bf16 v[32:35], v[180:183], v[196:199], v[32:35]
	v_mfma_f32_16x16x32_bf16 v[24:27], v[172:175], v[208:211], v[24:27]
	v_mfma_f32_16x16x32_bf16 v[16:19], v[180:183], v[208:211], v[16:19]
	v_mfma_f32_16x16x32_bf16 v[8:11], v[172:175], v[216:219], v[8:11]
	v_mfma_f32_16x16x32_bf16 v[0:3], v[180:183], v[216:219], v[0:3]
	v_mfma_f32_16x16x32_bf16 v[56:59], v[176:179], v[192:195], v[56:59]
	v_mfma_f32_16x16x32_bf16 v[48:51], v[184:187], v[192:195], v[48:51]
	v_mfma_f32_16x16x32_bf16 v[40:43], v[176:179], v[204:207], v[40:43]
	v_mfma_f32_16x16x32_bf16 v[32:35], v[184:187], v[204:207], v[32:35]
	v_mfma_f32_16x16x32_bf16 v[24:27], v[176:179], v[212:215], v[24:27]
	v_mfma_f32_16x16x32_bf16 v[16:19], v[184:187], v[212:215], v[16:19]
	v_mfma_f32_16x16x32_bf16 v[8:11], v[176:179], v[220:223], v[8:11]
	v_mfma_f32_16x16x32_bf16 v[0:3], v[184:187], v[220:223], v[0:3]
	s_setprio 0
	s_barrier
	s_add_i32 s64, s64, 2
	s_add_u32 s24, s24, 0x100
	s_addc_u32 s25, s25, 0
	s_add_u32 s47, s47, 0x100
	s_addc_u32 s52, s52, 0
	s_cmp_gt_u32 s64, 29
	s_cbranch_scc0 .LBB0_979
	s_and_b64 vcc, exec, s[12:13]
	s_cbranch_vccz .LBB0_982
	s_barrier

; #define PG8_STAGE(bufoff, gbase, voff) do { _Pragma("unroll") for (int _i = 0; _i < 2; ++_i) \
;         __builtin_amdgcn_global_load_lds((const unsigned*)((const char*)(gbase) + (voff)[_i]), (PG8_LAS unsigned*)(lds + (bufoff) + ldsw + _i * 8192), 16, 0, 0); } while (0)
; #define PG8_LDA(dst, b, h) do { _Pragma("unroll") for (int m = 0; m < 4; ++m) _Pragma("unroll") for (int k = 0; k < 2; ++k) dst[m][k] = *(const PG8_LAS bf16x8*)(lds + PG8_SA(b, h) + aoff + m * 2048 + k * 1024); } while (0)
; #define PG8_LDB(dst, b, h) do { _Pragma("unroll") for (int n = 0; n < 2; ++n) _Pragma("unroll") for (int k = 0; k < 2; ++k) dst[n][k] = *(const PG8_LAS bf16x8*)(lds + PG8_SB(b, h) + boff + n * 2048 + k * 1024); } while (0)
; #define PG8_MMA(ai, bj, At, Bt) do { __builtin_amdgcn_s_setprio(1); _Pragma("unroll") for (int m = 0; m < 4; ++m) _Pragma("unroll") for (int n = 0; n < 2; ++n) _Pragma("unroll") for (int k = 0; k < 2; ++k) \
;         acc[ai][bj][m][n] = __builtin_amdgcn_mfma_f32_16x16x32_bf16(Bt[n][k], At[m][k], acc[ai][bj][m][n], 0, 0, 0); __builtin_amdgcn_s_setprio(0); } while (0)
; #define PG8_WAIT_V(n) asm volatile("s_waitcnt vmcnt(" #n ")" ::: "memory")
; #define PG8_BAR __builtin_amdgcn_s_barrier()
; template <class Epi, class Sched, bool ALIGN_EPI = false, bool SP2 = false>
; __device__ __forceinline__ void gemm_phase(PG8_LAS unsigned char* lds, const Gemm g, const Sched& S, const Epi& E, int tid_in) {
;     ...
;         for (int t = 0; t < nt; t += 2) {
;             const bool last = (t == nt - 2);
;             const char* a1 = cA + (size_t)(t + 1) * kstep;
;             const char* a2 = last ? nA : cA + (size_t)(t + 2) * kstep; const char* b2 = last ? nB : cB + (size_t)(t + 2) * kstep;
;             const char* a3 = a2 + kstep; const char* b3 = b2 + kstep;
;             if (last && has_next) S.a_ready(nxt);
;             if constexpr (SP2) {
;             PG8_LDB(B0, 0, 0); PG8_LDB(B1, 0, 1); PG8_SCHED; PG8_LDA(At, 0, 0); PG8_STAGE(PG8_SA(1, 1), a1 + hstep, voffA);
;             PG8_WAIT_V(8); PG8_WAIT_L(0); PG8_BAR; PG8_MMA(0, 0, At, B0); PG8_MMA(0, 1, At, B1); PG8_BAR; PG8_SCHED;
;             PG8_LDA(At, 0, 1); PG8_STAGE(PG8_SB(0, 0), b2, voffB); PG8_STAGE(PG8_SB(0, 1), b2 + hstep, voffB); PG8_STAGE(PG8_SA(0, 0), a2, voffA);
;             PG8_WAIT_V(8); PG8_WAIT_L(0); PG8_BAR; PG8_MMA(1, 0, At, B0); PG8_MMA(1, 1, At, B1); PG8_BAR; PG8_SCHED;
.LBB0_1100:
	s_add_u32 s20, s18, 0x100
	s_addc_u32 s21, s19, 0
	s_add_i32 s52, 0, 0x10000
	s_cmpk_eq_i32 s47, 0x54
	s_cselect_b32 s25, s3, s21
	s_cselect_b32 s24, s2, s20
	v_add_u32_e32 v145, s52, v142
	s_cselect_b32 s23, s17, s46
	s_cselect_b32 s22, s16, s45
	s_add_i32 s62, 0, 0x14000
	ds_read_b128 v[146:149], v145
	ds_read_b128 v[150:153], v145 offset:1024
	ds_read_b128 v[154:157], v145 offset:2048
	ds_read_b128 v[158:161], v145 offset:3072
	v_add_u32_e32 v145, s62, v142
	ds_read_b128 v[162:165], v145
	ds_read_b128 v[172:175], v145 offset:1024
	ds_read_b128 v[176:179], v145 offset:2048
	ds_read_b128 v[180:183], v145 offset:3072
	v_lshl_add_u64 v[200:201], s[18:19], 0, v[136:137]
	s_add_i32 m0, s34, 0xc000
	ds_read_b128 v[184:187], v144
	ds_read_b128 v[188:191], v144 offset:1024
	ds_read_b128 v[192:195], v144 offset:2048
	ds_read_b128 v[196:199], v144 offset:3072
	ds_read_b128 v[204:207], v144 offset:4096
	ds_read_b128 v[208:211], v144 offset:5120
	ds_read_b128 v[212:215], v144 offset:6144
	ds_read_b128 v[216:219], v144 offset:7168
	global_load_lds_dwordx4 v[200:201], off
	v_lshl_add_u64 v[200:201], s[18:19], 0, v[138:139]
	s_add_i32 m0, s34, 0xe000
	s_nop 0
	global_load_lds_dwordx4 v[200:201], off
	s_waitcnt vmcnt(8)
	s_waitcnt lgkmcnt(0)
	s_barrier
	s_setprio 1
	v_mfma_f32_16x16x32_bf16 v[126:129], v[146:149], v[184:187], v[126:129]
	v_mfma_f32_16x16x32_bf16 v[122:125], v[154:157], v[184:187], v[122:125]
	v_mfma_f32_16x16x32_bf16 v[118:121], v[146:149], v[192:195], v[118:121]
	v_mfma_f32_16x16x32_bf16 v[114:117], v[154:157], v[192:195], v[114:117]
	v_mfma_f32_16x16x32_bf16 v[102:105], v[146:149], v[204:207], v[102:105]
	v_mfma_f32_16x16x32_bf16 v[98:101], v[154:157], v[204:207], v[98:101]
	v_mfma_f32_16x16x32_bf16 v[84:87], v[146:149], v[212:215], v[84:87]
	v_mfma_f32_16x16x32_bf16 v[80:83], v[154:157], v[212:215], v[80:83]
	v_mfma_f32_16x16x32_bf16 v[126:129], v[150:153], v[188:191], v[126:129]
	v_mfma_f32_16x16x32_bf16 v[122:125], v[158:161], v[188:191], v[122:125]
	v_mfma_f32_16x16x32_bf16 v[118:121], v[150:153], v[196:199], v[118:121]
	v_mfma_f32_16x16x32_bf16 v[114:117], v[158:161], v[196:199], v[114:117]
	v_mfma_f32_16x16x32_bf16 v[102:105], v[150:153], v[208:211], v[102:105]
	v_mfma_f32_16x16x32_bf16 v[98:101], v[158:161], v[208:211], v[98:101]
	v_mfma_f32_16x16x32_bf16 v[84:87], v[150:153], v[216:219], v[84:87]
	v_mfma_f32_16x16x32_bf16 v[80:83], v[158:161], v[216:219], v[80:83]
	s_setprio 0
	s_setprio 1
	v_mfma_f32_16x16x32_bf16 v[110:113], v[162:165], v[184:187], v[110:113]
	v_mfma_f32_16x16x32_bf16 v[106:109], v[176:179], v[184:187], v[106:109]
	v_mfma_f32_16x16x32_bf16 v[92:95], v[162:165], v[192:195], v[92:95]
	v_mfma_f32_16x16x32_bf16 v[88:91], v[176:179], v[192:195], v[88:91]
	v_mfma_f32_16x16x32_bf16 v[76:79], v[162:165], v[204:207], v[76:79]
	v_mfma_f32_16x16x32_bf16 v[72:75], v[176:179], v[204:207], v[72:75]
	v_mfma_f32_16x16x32_bf16 v[68:71], v[162:165], v[212:215], v[68:71]
	v_mfma_f32_16x16x32_bf16 v[64:67], v[176:179], v[212:215], v[64:67]
	v_mfma_f32_16x16x32_bf16 v[110:113], v[172:175], v[188:191], v[110:113]
	v_mfma_f32_16x16x32_bf16 v[106:109], v[180:183], v[188:191], v[106:109]
	v_mfma_f32_16x16x32_bf16 v[92:95], v[172:175], v[196:199], v[92:95]
	v_mfma_f32_16x16x32_bf16 v[88:91], v[180:183], v[196:199], v[88:91]
	v_mfma_f32_16x16x32_bf16 v[76:79], v[172:175], v[208:211], v[76:79]
	v_mfma_f32_16x16x32_bf16 v[72:75], v[180:183], v[208:211], v[72:75]
	v_mfma_f32_16x16x32_bf16 v[68:71], v[172:175], v[216:219], v[68:71]
	v_mfma_f32_16x16x32_bf16 v[64:67], v[180:183], v[216:219], v[64:67]
	s_setprio 0
	s_barrier
	s_add_i32 s18, s52, s31
	v_lshl_add_u64 v[200:201], s[22:23], 0, v[96:97]
	s_mov_b32 m0, s18
	ds_read_b128 v[184:187], v144 offset:16384
	ds_read_b128 v[188:191], v144 offset:17408
	ds_read_b128 v[192:195], v144 offset:18432
	ds_read_b128 v[196:199], v144 offset:19456
	ds_read_b128 v[204:207], v144 offset:20480
	ds_read_b128 v[208:211], v144 offset:21504
	ds_read_b128 v[212:215], v144 offset:22528
	ds_read_b128 v[216:219], v144 offset:23552
	global_load_lds_dwordx4 v[200:201], off
	s_add_i32 m0, s18, 0x2000
	s_add_u32 s18, s22, 0x160000
	v_lshl_add_u64 v[220:221], s[22:23], 0, v[134:135]
	s_addc_u32 s19, s23, 0
	s_add_i32 s52, s62, s31
	global_load_lds_dwordx4 v[220:221], off
	v_lshl_add_u64 v[222:223], s[18:19], 0, v[96:97]
	s_mov_b32 m0, s52
	v_lshl_add_u64 v[224:225], s[24:25], 0, v[132:133]
	global_load_lds_dwordx4 v[222:223], off
	v_lshl_add_u64 v[222:223], s[18:19], 0, v[134:135]
	s_add_i32 m0, s52, 0x2000
	s_nop 0
	global_load_lds_dwordx4 v[222:223], off
	v_lshl_add_u64 v[222:223], s[24:25], 0, v[130:131]
	s_mov_b32 m0, s34
	s_nop 0
	global_load_lds_dwordx4 v[222:223], off
	s_mov_b32 m0, s35
	s_nop 0
	global_load_lds_dwordx4 v[224:225], off
	s_waitcnt vmcnt(8)
	s_waitcnt lgkmcnt(0)
	s_barrier
; #define PG8_STAGE(bufoff, gbase, voff) do { _Pragma("unroll") for (int _i = 0; _i < 2; ++_i) \
;         __builtin_amdgcn_global_load_lds((const unsigned*)((const char*)(gbase) + (voff)[_i]), (PG8_LAS unsigned*)(lds + (bufoff) + ldsw + _i * 8192), 16, 0, 0); } while (0)
; #define PG8_LDA(dst, b, h) do { _Pragma("unroll") for (int m = 0; m < 4; ++m) _Pragma("unroll") for (int k = 0; k < 2; ++k) dst[m][k] = *(const PG8_LAS bf16x8*)(lds + PG8_SA(b, h) + aoff + m * 2048 + k * 1024); } while (0)
; #define PG8_LDB(dst, b, h) do { _Pragma("unroll") for (int n = 0; n < 2; ++n) _Pragma("unroll") for (int k = 0; k < 2; ++k) dst[n][k] = *(const PG8_LAS bf16x8*)(lds + PG8_SB(b, h) + boff + n * 2048 + k * 1024); } while (0)
; #define PG8_MMA(ai, bj, At, Bt) do { __builtin_amdgcn_s_setprio(1); _Pragma("unroll") for (int m = 0; m < 4; ++m) _Pragma("unroll") for (int n = 0; n < 2; ++n) _Pragma("unroll") for (int k = 0; k < 2; ++k) \
;         acc[ai][bj][m][n] = __builtin_amdgcn_mfma_f32_16x16x32_bf16(Bt[n][k], At[m][k], acc[ai][bj][m][n], 0, 0, 0); __builtin_amdgcn_s_setprio(0); } while (0)
; #define PG8_WAIT_V(n) asm volatile("s_waitcnt vmcnt(" #n ")" ::: "memory")
; #define PG8_WAIT_L(n) asm volatile("s_waitcnt lgkmcnt(" #n ")" ::: "memory")
; #define PG8_BAR __builtin_amdgcn_s_barrier()
; #define PG8_SCHED __builtin_amdgcn_sched_barrier(0)
; template <class Epi, class Sched, bool ALIGN_EPI = false, bool SP2 = false>
; __device__ __forceinline__ void gemm_phase(PG8_LAS unsigned char* lds, const Gemm g, const Sched& S, const Epi& E, int tid_in) {
;     ...
;             PG8_WAIT_V(8); PG8_WAIT_L(0); PG8_BAR; PG8_MMA(1, 0, At, B0); PG8_MMA(1, 1, At, B1); PG8_BAR; PG8_SCHED;
;             PG8_LDB(B0, 1, 0); PG8_LDB(B1, 1, 1); PG8_SCHED; PG8_LDA(At, 1, 0); PG8_STAGE(PG8_SA(0, 1), a2 + hstep, voffA);
;             PG8_WAIT_V(8); PG8_WAIT_L(0); PG8_BAR; PG8_MMA(0, 0, At, B0); PG8_MMA(0, 1, At, B1); PG8_BAR; PG8_SCHED;
	s_setprio 1
	v_mfma_f32_16x16x32_bf16 v[60:63], v[146:149], v[184:187], v[60:63]
	v_mfma_f32_16x16x32_bf16 v[56:59], v[154:157], v[184:187], v[56:59]
	v_mfma_f32_16x16x32_bf16 v[52:55], v[146:149], v[192:195], v[52:55]
	v_mfma_f32_16x16x32_bf16 v[48:51], v[154:157], v[192:195], v[48:51]
	v_mfma_f32_16x16x32_bf16 v[36:39], v[146:149], v[204:207], v[36:39]
	v_mfma_f32_16x16x32_bf16 v[32:35], v[154:157], v[204:207], v[32:35]
	v_mfma_f32_16x16x32_bf16 v[20:23], v[146:149], v[212:215], v[20:23]
	v_mfma_f32_16x16x32_bf16 v[16:19], v[154:157], v[212:215], v[16:19]
	v_mfma_f32_16x16x32_bf16 v[60:63], v[150:153], v[188:191], v[60:63]
	v_mfma_f32_16x16x32_bf16 v[56:59], v[158:161], v[188:191], v[56:59]
	v_mfma_f32_16x16x32_bf16 v[52:55], v[150:153], v[196:199], v[52:55]
	v_mfma_f32_16x16x32_bf16 v[48:51], v[158:161], v[196:199], v[48:51]
	v_mfma_f32_16x16x32_bf16 v[36:39], v[150:153], v[208:211], v[36:39]
	v_mfma_f32_16x16x32_bf16 v[32:35], v[158:161], v[208:211], v[32:35]
	v_mfma_f32_16x16x32_bf16 v[20:23], v[150:153], v[216:219], v[20:23]
	v_mfma_f32_16x16x32_bf16 v[16:19], v[158:161], v[216:219], v[16:19]
	s_setprio 0
	s_setprio 1
	v_mfma_f32_16x16x32_bf16 v[44:47], v[162:165], v[184:187], v[44:47]
	v_mfma_f32_16x16x32_bf16 v[40:43], v[176:179], v[184:187], v[40:43]
	v_mfma_f32_16x16x32_bf16 v[28:31], v[162:165], v[192:195], v[28:31]
	v_mfma_f32_16x16x32_bf16 v[24:27], v[176:179], v[192:195], v[24:27]
	v_mfma_f32_16x16x32_bf16 v[12:15], v[162:165], v[204:207], v[12:15]
	v_mfma_f32_16x16x32_bf16 v[8:11], v[176:179], v[204:207], v[8:11]
	v_mfma_f32_16x16x32_bf16 v[4:7], v[162:165], v[212:215], v[4:7]
	v_mfma_f32_16x16x32_bf16 v[0:3], v[176:179], v[212:215], v[0:3]
	v_mfma_f32_16x16x32_bf16 v[44:47], v[172:175], v[188:191], v[44:47]
	v_mfma_f32_16x16x32_bf16 v[40:43], v[180:183], v[188:191], v[40:43]
	v_mfma_f32_16x16x32_bf16 v[28:31], v[172:175], v[196:199], v[28:31]
	v_mfma_f32_16x16x32_bf16 v[24:27], v[180:183], v[196:199], v[24:27]
	v_mfma_f32_16x16x32_bf16 v[12:15], v[172:175], v[208:211], v[12:15]
	v_mfma_f32_16x16x32_bf16 v[8:11], v[180:183], v[208:211], v[8:11]
	v_mfma_f32_16x16x32_bf16 v[4:7], v[172:175], v[216:219], v[4:7]
	v_mfma_f32_16x16x32_bf16 v[0:3], v[180:183], v[216:219], v[0:3]
	s_setprio 0
	s_barrier
	s_add_i32 s52, 0, 0x18000
	v_add_u32_e32 v145, s52, v142
	s_add_i32 s62, 0, 0x1c000
	ds_read_b128 v[146:149], v145
	ds_read_b128 v[150:153], v145 offset:1024
	ds_read_b128 v[154:157], v145 offset:2048
	ds_read_b128 v[158:161], v145 offset:3072
	v_add_u32_e32 v145, s62, v142
	ds_read_b128 v[162:165], v145
	ds_read_b128 v[172:175], v145 offset:1024
	ds_read_b128 v[176:179], v145 offset:2048
	ds_read_b128 v[180:183], v145 offset:3072
	s_add_u32 s18, s24, 0x160000
	s_addc_u32 s19, s25, 0
	s_mov_b32 m0, s36
	v_lshl_add_u64 v[226:227], s[18:19], 0, v[130:131]
	ds_read_b128 v[184:187], v144 offset:32768
	ds_read_b128 v[188:191], v144 offset:33792
	ds_read_b128 v[192:195], v144 offset:34816
	ds_read_b128 v[196:199], v144 offset:35840
	ds_read_b128 v[204:207], v144 offset:36864
	ds_read_b128 v[208:211], v144 offset:37888
	ds_read_b128 v[212:215], v144 offset:38912
	ds_read_b128 v[216:219], v144 offset:39936
	global_load_lds_dwordx4 v[226:227], off
	v_lshl_add_u64 v[226:227], s[18:19], 0, v[132:133]
	s_mov_b32 m0, s37
	s_nop 0
	global_load_lds_dwordx4 v[226:227], off
	s_waitcnt vmcnt(8)
	s_waitcnt lgkmcnt(0)
	s_barrier
	s_setprio 1
	v_mfma_f32_16x16x32_bf16 v[126:129], v[146:149], v[184:187], v[126:129]
	v_mfma_f32_16x16x32_bf16 v[122:125], v[154:157], v[184:187], v[122:125]
	v_mfma_f32_16x16x32_bf16 v[118:121], v[146:149], v[192:195], v[118:121]
	v_mfma_f32_16x16x32_bf16 v[114:117], v[154:157], v[192:195], v[114:117]
	v_mfma_f32_16x16x32_bf16 v[102:105], v[146:149], v[204:207], v[102:105]
	v_mfma_f32_16x16x32_bf16 v[98:101], v[154:157], v[204:207], v[98:101]
	v_mfma_f32_16x16x32_bf16 v[84:87], v[146:149], v[212:215], v[84:87]
	v_mfma_f32_16x16x32_bf16 v[80:83], v[154:157], v[212:215], v[80:83]
	v_mfma_f32_16x16x32_bf16 v[126:129], v[150:153], v[188:191], v[126:129]
	v_mfma_f32_16x16x32_bf16 v[122:125], v[158:161], v[188:191], v[122:125]
	v_mfma_f32_16x16x32_bf16 v[118:121], v[150:153], v[196:199], v[118:121]
	v_mfma_f32_16x16x32_bf16 v[114:117], v[158:161], v[196:199], v[114:117]
	v_mfma_f32_16x16x32_bf16 v[102:105], v[150:153], v[208:211], v[102:105]
	v_mfma_f32_16x16x32_bf16 v[98:101], v[158:161], v[208:211], v[98:101]
	v_mfma_f32_16x16x32_bf16 v[84:87], v[150:153], v[216:219], v[84:87]
	v_mfma_f32_16x16x32_bf16 v[80:83], v[158:161], v[216:219], v[80:83]
	s_setprio 0
	s_setprio 1
	v_mfma_f32_16x16x32_bf16 v[110:113], v[162:165], v[184:187], v[110:113]
	v_mfma_f32_16x16x32_bf16 v[106:109], v[176:179], v[184:187], v[106:109]
	v_mfma_f32_16x16x32_bf16 v[92:95], v[162:165], v[192:195], v[92:95]
	v_mfma_f32_16x16x32_bf16 v[88:91], v[176:179], v[192:195], v[88:91]
	v_mfma_f32_16x16x32_bf16 v[76:79], v[162:165], v[204:207], v[76:79]
	v_mfma_f32_16x16x32_bf16 v[72:75], v[176:179], v[204:207], v[72:75]
	v_mfma_f32_16x16x32_bf16 v[68:71], v[162:165], v[212:215], v[68:71]
	v_mfma_f32_16x16x32_bf16 v[64:67], v[176:179], v[212:215], v[64:67]
	v_mfma_f32_16x16x32_bf16 v[110:113], v[172:175], v[188:191], v[110:113]
	v_mfma_f32_16x16x32_bf16 v[106:109], v[180:183], v[188:191], v[106:109]
	v_mfma_f32_16x16x32_bf16 v[92:95], v[172:175], v[196:199], v[92:95]
	v_mfma_f32_16x16x32_bf16 v[88:91], v[180:183], v[196:199], v[88:91]
	v_mfma_f32_16x16x32_bf16 v[76:79], v[172:175], v[208:211], v[76:79]
	v_mfma_f32_16x16x32_bf16 v[72:75], v[180:183], v[208:211], v[72:75]
	v_mfma_f32_16x16x32_bf16 v[68:71], v[172:175], v[216:219], v[68:71]
	v_mfma_f32_16x16x32_bf16 v[64:67], v[180:183], v[216:219], v[64:67]
	s_setprio 0
	s_barrier
; #define PG8_STAGE(bufoff, gbase, voff) do { _Pragma("unroll") for (int _i = 0; _i < 2; ++_i) \
;         __builtin_amdgcn_global_load_lds((const unsigned*)((const char*)(gbase) + (voff)[_i]), (PG8_LAS unsigned*)(lds + (bufoff) + ldsw + _i * 8192), 16, 0, 0); } while (0)
; #define PG8_LDA(dst, b, h) do { _Pragma("unroll") for (int m = 0; m < 4; ++m) _Pragma("unroll") for (int k = 0; k < 2; ++k) dst[m][k] = *(const PG8_LAS bf16x8*)(lds + PG8_SA(b, h) + aoff + m * 2048 + k * 1024); } while (0)
; #define PG8_MMA(ai, bj, At, Bt) do { __builtin_amdgcn_s_setprio(1); _Pragma("unroll") for (int m = 0; m < 4; ++m) _Pragma("unroll") for (int n = 0; n < 2; ++n) _Pragma("unroll") for (int k = 0; k < 2; ++k) \
;         acc[ai][bj][m][n] = __builtin_amdgcn_mfma_f32_16x16x32_bf16(Bt[n][k], At[m][k], acc[ai][bj][m][n], 0, 0, 0); __builtin_amdgcn_s_setprio(0); } while (0)
; #define PG8_WAIT_V(n) asm volatile("s_waitcnt vmcnt(" #n ")" ::: "memory")
; #define PG8_WAIT_L(n) asm volatile("s_waitcnt lgkmcnt(" #n ")" ::: "memory")
; #define PG8_BAR __builtin_amdgcn_s_barrier()
; #define PG8_SCHED __builtin_amdgcn_sched_barrier(0)
; template <class Epi, class Sched, bool ALIGN_EPI = false, bool SP2 = false>
; __device__ __forceinline__ void gemm_phase(PG8_LAS unsigned char* lds, const Gemm g, const Sched& S, const Epi& E, int tid_in) {
;     ...
;             PG8_LDA(At, 1, 1); PG8_STAGE(PG8_SB(1, 0), b3, voffB); PG8_STAGE(PG8_SB(1, 1), b3 + hstep, voffB); PG8_STAGE(PG8_SA(1, 0), a3, voffA);
;             PG8_WAIT_V(8); PG8_WAIT_L(0); PG8_BAR; PG8_MMA(1, 0, At, B0); PG8_MMA(1, 1, At, B1); PG8_BAR; PG8_SCHED;
;     ...
;         if constexpr (ALIGN_EPI) { if (wr == 0) PG8_BAR; }
	s_add_i32 s18, s52, s31
	v_lshl_add_u64 v[200:201], v[200:201], 0, s[88:89]
	s_mov_b32 m0, s18
	ds_read_b128 v[184:187], v144 offset:49152
	ds_read_b128 v[188:191], v144 offset:50176
	ds_read_b128 v[192:195], v144 offset:51200
	ds_read_b128 v[196:199], v144 offset:52224
	ds_read_b128 v[204:207], v144 offset:53248
	ds_read_b128 v[208:211], v144 offset:54272
	ds_read_b128 v[212:215], v144 offset:55296
	ds_read_b128 v[216:219], v144 offset:56320
	global_load_lds_dwordx4 v[200:201], off
	s_add_i32 m0, s18, 0x2000
	s_add_u32 s18, s22, 0x160080
	v_lshl_add_u64 v[200:201], v[220:221], 0, s[88:89]
	s_addc_u32 s19, s23, 0
	s_add_i32 s22, s62, s31
	global_load_lds_dwordx4 v[200:201], off
	v_lshl_add_u64 v[200:201], s[18:19], 0, v[96:97]
	s_mov_b32 m0, s22
	s_nop 0
	global_load_lds_dwordx4 v[200:201], off
	v_lshl_add_u64 v[200:201], s[18:19], 0, v[134:135]
	s_add_i32 m0, s22, 0x2000
	s_nop 0
	global_load_lds_dwordx4 v[200:201], off
	v_lshl_add_u64 v[200:201], v[222:223], 0, s[88:89]
	s_mov_b32 m0, s38
	s_nop 0
	global_load_lds_dwordx4 v[200:201], off
	v_lshl_add_u64 v[200:201], v[224:225], 0, s[88:89]
	s_mov_b32 m0, s39
	s_nop 0
	global_load_lds_dwordx4 v[200:201], off
	s_waitcnt vmcnt(8)
	s_waitcnt lgkmcnt(0)
	s_barrier
	s_setprio 1
	v_mfma_f32_16x16x32_bf16 v[60:63], v[146:149], v[184:187], v[60:63]
	v_mfma_f32_16x16x32_bf16 v[56:59], v[154:157], v[184:187], v[56:59]
	v_mfma_f32_16x16x32_bf16 v[52:55], v[146:149], v[192:195], v[52:55]
	v_mfma_f32_16x16x32_bf16 v[48:51], v[154:157], v[192:195], v[48:51]
	v_mfma_f32_16x16x32_bf16 v[36:39], v[146:149], v[204:207], v[36:39]
	v_mfma_f32_16x16x32_bf16 v[32:35], v[154:157], v[204:207], v[32:35]
	v_mfma_f32_16x16x32_bf16 v[20:23], v[146:149], v[212:215], v[20:23]
	v_mfma_f32_16x16x32_bf16 v[16:19], v[154:157], v[212:215], v[16:19]
	v_mfma_f32_16x16x32_bf16 v[60:63], v[150:153], v[188:191], v[60:63]
	v_mfma_f32_16x16x32_bf16 v[56:59], v[158:161], v[188:191], v[56:59]
	v_mfma_f32_16x16x32_bf16 v[52:55], v[150:153], v[196:199], v[52:55]
	v_mfma_f32_16x16x32_bf16 v[48:51], v[158:161], v[196:199], v[48:51]
	v_mfma_f32_16x16x32_bf16 v[36:39], v[150:153], v[208:211], v[36:39]
	v_mfma_f32_16x16x32_bf16 v[32:35], v[158:161], v[208:211], v[32:35]
	v_mfma_f32_16x16x32_bf16 v[20:23], v[150:153], v[216:219], v[20:23]
	v_mfma_f32_16x16x32_bf16 v[16:19], v[158:161], v[216:219], v[16:19]
	s_setprio 0
	s_setprio 1
	v_mfma_f32_16x16x32_bf16 v[44:47], v[162:165], v[184:187], v[44:47]
	v_mfma_f32_16x16x32_bf16 v[40:43], v[176:179], v[184:187], v[40:43]
	v_mfma_f32_16x16x32_bf16 v[28:31], v[162:165], v[192:195], v[28:31]
	v_mfma_f32_16x16x32_bf16 v[24:27], v[176:179], v[192:195], v[24:27]
	v_mfma_f32_16x16x32_bf16 v[12:15], v[162:165], v[204:207], v[12:15]
	v_mfma_f32_16x16x32_bf16 v[8:11], v[176:179], v[204:207], v[8:11]
	v_mfma_f32_16x16x32_bf16 v[4:7], v[162:165], v[212:215], v[4:7]
	v_mfma_f32_16x16x32_bf16 v[0:3], v[176:179], v[212:215], v[0:3]
	v_mfma_f32_16x16x32_bf16 v[44:47], v[172:175], v[188:191], v[44:47]
	v_mfma_f32_16x16x32_bf16 v[40:43], v[180:183], v[188:191], v[40:43]
	v_mfma_f32_16x16x32_bf16 v[28:31], v[172:175], v[196:199], v[28:31]
	v_mfma_f32_16x16x32_bf16 v[24:27], v[180:183], v[196:199], v[24:27]
	v_mfma_f32_16x16x32_bf16 v[12:15], v[172:175], v[208:211], v[12:15]
	v_mfma_f32_16x16x32_bf16 v[8:11], v[180:183], v[208:211], v[8:11]
	v_mfma_f32_16x16x32_bf16 v[4:7], v[172:175], v[216:219], v[4:7]
	v_mfma_f32_16x16x32_bf16 v[0:3], v[180:183], v[216:219], v[0:3]
	s_setprio 0
	s_barrier
	s_add_i32 s47, s47, 2
	s_add_u32 s45, s45, 0x100
	s_addc_u32 s46, s46, 0
	s_cmpk_gt_u32 s47, 0x55
	s_mov_b64 s[18:19], s[20:21]
	s_cbranch_scc0 .LBB0_1100
	s_and_b64 vcc, exec, s[14:15]
	s_cbranch_vccz .LBB0_1103
	s_barrier
